# B1 barrier + first K-loop iteration of every GEMM unit peeled: first MFMA per accumulator takes C=0, the 127 zeroing v_mov per unit removed
# speedup vs baseline: 1.0131x; 1.0045x over previous
.Lpeel_13:
	ds_read_b128 v[152:155], v149
	ds_read_b128 v[156:159], v149 offset:1024
	ds_read_b128 v[160:163], v149 offset:2048
	ds_read_b128 v[164:167], v149 offset:3072
	ds_read_b128 v[168:171], v150
	ds_read_b128 v[172:175], v150 offset:1024
	ds_read_b128 v[176:179], v150 offset:2048
	ds_read_b128 v[180:183], v150 offset:3072
	s_add_i32 s37, s25, 2
	s_add_u32 s40, s38, 0xfff80080
	s_addc_u32 s41, s39, -1
	s_cmp_eq_u32 s36, s25
	s_cselect_b32 s43, s27, s41
	s_cselect_b32 s42, s26, s40
	s_cselect_b32 s41, s29, s23
	s_cselect_b32 s40, s28, s21
	v_lshl_add_u64 v[144:145], s[38:39], 0, v[140:141]
	s_add_i32 m0, s35, 0xc000
	ds_read_b128 v[184:187], v151
	ds_read_b128 v[188:191], v151 offset:1024
	ds_read_b128 v[196:199], v151 offset:2048
	ds_read_b128 v[200:203], v151 offset:3072
	ds_read_b128 v[204:207], v151 offset:4096
	ds_read_b128 v[208:211], v151 offset:5120
	ds_read_b128 v[212:215], v151 offset:6144
	ds_read_b128 v[216:219], v151 offset:7168
	global_load_lds_dwordx4 v[144:145], off
	v_lshl_add_u64 v[144:145], s[38:39], 0, v[142:143]
	s_add_i32 m0, s35, 0xe000
	s_nop 0
	global_load_lds_dwordx4 v[144:145], off
	s_waitcnt vmcnt(8)
	s_waitcnt lgkmcnt(0)
	s_barrier
	s_setprio 1
	s_waitcnt lgkmcnt(0)
	v_mfma_f32_16x16x32_bf16 v[126:129], v[152:155], v[184:187], 0
	v_mfma_f32_16x16x32_bf16 v[122:125], v[160:163], v[184:187], 0
	v_mfma_f32_16x16x32_bf16 v[110:113], v[152:155], v[196:199], 0
	v_mfma_f32_16x16x32_bf16 v[106:109], v[160:163], v[196:199], 0
	v_mfma_f32_16x16x32_bf16 v[94:97], v[152:155], v[204:207], 0
	v_mfma_f32_16x16x32_bf16 v[90:93], v[160:163], v[204:207], 0
	v_mfma_f32_16x16x32_bf16 v[78:81], v[152:155], v[212:215], 0
	v_mfma_f32_16x16x32_bf16 v[74:77], v[160:163], v[212:215], 0
	v_mfma_f32_16x16x32_bf16 v[126:129], v[156:159], v[188:191], v[126:129]
	v_mfma_f32_16x16x32_bf16 v[122:125], v[164:167], v[188:191], v[122:125]
	v_mfma_f32_16x16x32_bf16 v[110:113], v[156:159], v[200:203], v[110:113]
	v_mfma_f32_16x16x32_bf16 v[106:109], v[164:167], v[200:203], v[106:109]
	v_mfma_f32_16x16x32_bf16 v[94:97], v[156:159], v[208:211], v[94:97]
	v_mfma_f32_16x16x32_bf16 v[90:93], v[164:167], v[208:211], v[90:93]
	v_mfma_f32_16x16x32_bf16 v[78:81], v[156:159], v[216:219], v[78:81]
	v_mfma_f32_16x16x32_bf16 v[74:77], v[164:167], v[216:219], v[74:77]
	s_setprio 0
	s_setprio 1
	v_mfma_f32_16x16x32_bf16 v[118:121], v[168:171], v[184:187], 0
	v_mfma_f32_16x16x32_bf16 v[114:117], v[176:179], v[184:187], 0
	v_mfma_f32_16x16x32_bf16 v[102:105], v[168:171], v[196:199], 0
	v_mfma_f32_16x16x32_bf16 v[98:101], v[176:179], v[196:199], 0
	v_mfma_f32_16x16x32_bf16 v[86:89], v[168:171], v[204:207], 0
	v_mfma_f32_16x16x32_bf16 v[82:85], v[176:179], v[204:207], 0
	v_mfma_f32_16x16x32_bf16 v[70:73], v[168:171], v[212:215], 0
	v_mfma_f32_16x16x32_bf16 v[66:69], v[176:179], v[212:215], 0
	v_mfma_f32_16x16x32_bf16 v[118:121], v[172:175], v[188:191], v[118:121]
	v_mfma_f32_16x16x32_bf16 v[114:117], v[180:183], v[188:191], v[114:117]
	v_mfma_f32_16x16x32_bf16 v[102:105], v[172:175], v[200:203], v[102:105]
	v_mfma_f32_16x16x32_bf16 v[98:101], v[180:183], v[200:203], v[98:101]
	v_mfma_f32_16x16x32_bf16 v[86:89], v[172:175], v[208:211], v[86:89]
	v_mfma_f32_16x16x32_bf16 v[82:85], v[180:183], v[208:211], v[82:85]
	v_mfma_f32_16x16x32_bf16 v[70:73], v[172:175], v[216:219], v[70:73]
	v_mfma_f32_16x16x32_bf16 v[66:69], v[180:183], v[216:219], v[66:69]
	s_setprio 0
	s_barrier
	s_add_i32 s25, s54, s33
	v_lshl_add_u64 v[144:145], s[40:41], 0, v[132:133]
	s_mov_b32 m0, s25
	ds_read_b128 v[184:187], v151 offset:16384
	ds_read_b128 v[188:191], v151 offset:17408
	ds_read_b128 v[196:199], v151 offset:18432
	ds_read_b128 v[200:203], v151 offset:19456
	ds_read_b128 v[204:207], v151 offset:20480
	ds_read_b128 v[208:211], v151 offset:21504
	ds_read_b128 v[212:215], v151 offset:22528
	ds_read_b128 v[216:219], v151 offset:23552
	global_load_lds_dwordx4 v[144:145], off
	s_add_i32 m0, s25, 0x2000
	s_add_u32 s44, s40, 0x80000
	v_lshl_add_u64 v[192:193], s[40:41], 0, v[136:137]
	s_addc_u32 s45, s41, 0
	s_add_i32 s25, s55, s33
	global_load_lds_dwordx4 v[192:193], off
	v_lshl_add_u64 v[220:221], s[44:45], 0, v[132:133]
	s_mov_b32 m0, s25
	v_lshl_add_u64 v[222:223], s[42:43], 0, v[134:135]
	global_load_lds_dwordx4 v[220:221], off
	v_lshl_add_u64 v[220:221], s[44:45], 0, v[136:137]
	s_add_i32 m0, s25, 0x2000
	s_nop 0
	global_load_lds_dwordx4 v[220:221], off
	v_lshl_add_u64 v[220:221], s[42:43], 0, v[130:131]
	s_mov_b32 m0, s35
	s_nop 0
	global_load_lds_dwordx4 v[220:221], off
	s_mov_b32 m0, s47
	s_nop 0
	global_load_lds_dwordx4 v[222:223], off
	s_waitcnt vmcnt(8)
	s_waitcnt lgkmcnt(0)
	s_barrier
	s_setprio 1
	s_waitcnt lgkmcnt(0)
	v_mfma_f32_16x16x32_bf16 v[62:65], v[152:155], v[184:187], 0
	v_mfma_f32_16x16x32_bf16 v[58:61], v[160:163], v[184:187], 0
	v_mfma_f32_16x16x32_bf16 v[46:49], v[152:155], v[196:199], 0
	v_mfma_f32_16x16x32_bf16 v[42:45], v[160:163], v[196:199], 0
	v_mfma_f32_16x16x32_bf16 v[30:33], v[152:155], v[204:207], 0
	v_mfma_f32_16x16x32_bf16 v[26:29], v[160:163], v[204:207], 0
	v_mfma_f32_16x16x32_bf16 v[14:17], v[152:155], v[212:215], 0
	v_mfma_f32_16x16x32_bf16 v[10:13], v[160:163], v[212:215], 0
	v_mfma_f32_16x16x32_bf16 v[62:65], v[156:159], v[188:191], v[62:65]
	v_mfma_f32_16x16x32_bf16 v[58:61], v[164:167], v[188:191], v[58:61]
	v_mfma_f32_16x16x32_bf16 v[46:49], v[156:159], v[200:203], v[46:49]
	v_mfma_f32_16x16x32_bf16 v[42:45], v[164:167], v[200:203], v[42:45]
	v_mfma_f32_16x16x32_bf16 v[30:33], v[156:159], v[208:211], v[30:33]
	v_mfma_f32_16x16x32_bf16 v[26:29], v[164:167], v[208:211], v[26:29]
	v_mfma_f32_16x16x32_bf16 v[14:17], v[156:159], v[216:219], v[14:17]
	v_mfma_f32_16x16x32_bf16 v[10:13], v[164:167], v[216:219], v[10:13]
	s_setprio 0
	s_setprio 1
	v_mfma_f32_16x16x32_bf16 v[54:57], v[168:171], v[184:187], 0
	v_mfma_f32_16x16x32_bf16 v[50:53], v[176:179], v[184:187], 0
	v_mfma_f32_16x16x32_bf16 v[38:41], v[168:171], v[196:199], 0
	v_mfma_f32_16x16x32_bf16 v[34:37], v[176:179], v[196:199], 0
	v_mfma_f32_16x16x32_bf16 v[22:25], v[168:171], v[204:207], 0
	v_mfma_f32_16x16x32_bf16 v[18:21], v[176:179], v[204:207], 0
	v_mfma_f32_16x16x32_bf16 v[6:9], v[168:171], v[212:215], 0
	v_mfma_f32_16x16x32_bf16 v[2:5], v[176:179], v[212:215], 0
	v_mfma_f32_16x16x32_bf16 v[54:57], v[172:175], v[188:191], v[54:57]
	v_mfma_f32_16x16x32_bf16 v[50:53], v[180:183], v[188:191], v[50:53]
	v_mfma_f32_16x16x32_bf16 v[38:41], v[172:175], v[200:203], v[38:41]
	v_mfma_f32_16x16x32_bf16 v[34:37], v[180:183], v[200:203], v[34:37]
	v_mfma_f32_16x16x32_bf16 v[22:25], v[172:175], v[208:211], v[22:25]
	v_mfma_f32_16x16x32_bf16 v[18:21], v[180:183], v[208:211], v[18:21]
	v_mfma_f32_16x16x32_bf16 v[6:9], v[172:175], v[216:219], v[6:9]
	v_mfma_f32_16x16x32_bf16 v[2:5], v[180:183], v[216:219], v[2:5]
	s_setprio 0
	s_barrier
	s_add_i32 s25, 0, 0x18000
	s_add_i32 s44, 0, 0x1c000
	v_add_u32_e32 v164, s25, v147
	v_add_u32_e32 v180, s44, v147
	ds_read_b128 v[152:155], v164
	ds_read_b128 v[156:159], v164 offset:1024
	ds_read_b128 v[160:163], v164 offset:2048
	ds_read_b128 v[164:167], v164 offset:3072
	ds_read_b128 v[168:171], v180
	ds_read_b128 v[172:175], v180 offset:1024
	ds_read_b128 v[176:179], v180 offset:2048
	ds_read_b128 v[180:183], v180 offset:3072
	s_add_u32 s42, s42, 0x80000
	s_addc_u32 s43, s43, 0
	s_mov_b32 m0, s48
	v_lshl_add_u64 v[224:225], s[42:43], 0, v[130:131]
	ds_read_b128 v[184:187], v151 offset:32768
	ds_read_b128 v[188:191], v151 offset:33792
	ds_read_b128 v[196:199], v151 offset:34816
	ds_read_b128 v[200:203], v151 offset:35840
	ds_read_b128 v[204:207], v151 offset:36864
	ds_read_b128 v[208:211], v151 offset:37888
	ds_read_b128 v[212:215], v151 offset:38912
	ds_read_b128 v[216:219], v151 offset:39936
	global_load_lds_dwordx4 v[224:225], off
	v_lshl_add_u64 v[224:225], s[42:43], 0, v[134:135]
	s_mov_b32 m0, s49
	s_nop 0
	global_load_lds_dwordx4 v[224:225], off
	s_waitcnt vmcnt(8)
	s_waitcnt lgkmcnt(0)
	s_barrier
	s_setprio 1
	s_waitcnt lgkmcnt(0)
	v_mfma_f32_16x16x32_bf16 v[126:129], v[152:155], v[184:187], v[126:129]
	v_mfma_f32_16x16x32_bf16 v[122:125], v[160:163], v[184:187], v[122:125]
	v_mfma_f32_16x16x32_bf16 v[110:113], v[152:155], v[196:199], v[110:113]
	v_mfma_f32_16x16x32_bf16 v[106:109], v[160:163], v[196:199], v[106:109]
	v_mfma_f32_16x16x32_bf16 v[94:97], v[152:155], v[204:207], v[94:97]
	v_mfma_f32_16x16x32_bf16 v[90:93], v[160:163], v[204:207], v[90:93]
	v_mfma_f32_16x16x32_bf16 v[78:81], v[152:155], v[212:215], v[78:81]
	v_mfma_f32_16x16x32_bf16 v[74:77], v[160:163], v[212:215], v[74:77]
	v_mfma_f32_16x16x32_bf16 v[126:129], v[156:159], v[188:191], v[126:129]
	v_mfma_f32_16x16x32_bf16 v[122:125], v[164:167], v[188:191], v[122:125]
	v_mfma_f32_16x16x32_bf16 v[110:113], v[156:159], v[200:203], v[110:113]
	v_mfma_f32_16x16x32_bf16 v[106:109], v[164:167], v[200:203], v[106:109]
	v_mfma_f32_16x16x32_bf16 v[94:97], v[156:159], v[208:211], v[94:97]
	v_mfma_f32_16x16x32_bf16 v[90:93], v[164:167], v[208:211], v[90:93]
	v_mfma_f32_16x16x32_bf16 v[78:81], v[156:159], v[216:219], v[78:81]
	v_mfma_f32_16x16x32_bf16 v[74:77], v[164:167], v[216:219], v[74:77]
	s_setprio 0
	s_setprio 1
	v_mfma_f32_16x16x32_bf16 v[118:121], v[168:171], v[184:187], v[118:121]
	v_mfma_f32_16x16x32_bf16 v[114:117], v[176:179], v[184:187], v[114:117]
	v_mfma_f32_16x16x32_bf16 v[102:105], v[168:171], v[196:199], v[102:105]
	v_mfma_f32_16x16x32_bf16 v[98:101], v[176:179], v[196:199], v[98:101]
	v_mfma_f32_16x16x32_bf16 v[86:89], v[168:171], v[204:207], v[86:89]
	v_mfma_f32_16x16x32_bf16 v[82:85], v[176:179], v[204:207], v[82:85]
	v_mfma_f32_16x16x32_bf16 v[70:73], v[168:171], v[212:215], v[70:73]
	v_mfma_f32_16x16x32_bf16 v[66:69], v[176:179], v[212:215], v[66:69]
	v_mfma_f32_16x16x32_bf16 v[118:121], v[172:175], v[188:191], v[118:121]
	v_mfma_f32_16x16x32_bf16 v[114:117], v[180:183], v[188:191], v[114:117]
	v_mfma_f32_16x16x32_bf16 v[102:105], v[172:175], v[200:203], v[102:105]
	v_mfma_f32_16x16x32_bf16 v[98:101], v[180:183], v[200:203], v[98:101]
	v_mfma_f32_16x16x32_bf16 v[86:89], v[172:175], v[208:211], v[86:89]
	v_mfma_f32_16x16x32_bf16 v[82:85], v[180:183], v[208:211], v[82:85]
	v_mfma_f32_16x16x32_bf16 v[70:73], v[172:175], v[216:219], v[70:73]
	v_mfma_f32_16x16x32_bf16 v[66:69], v[180:183], v[216:219], v[66:69]
	s_setprio 0
	s_barrier
	s_add_i32 s25, s25, s33
	v_lshl_add_u64 v[144:145], v[144:145], 0, s[16:17]
	s_mov_b32 m0, s25
	ds_read_b128 v[184:187], v151 offset:49152
	ds_read_b128 v[188:191], v151 offset:50176
	ds_read_b128 v[196:199], v151 offset:51200
	ds_read_b128 v[200:203], v151 offset:52224
	ds_read_b128 v[204:207], v151 offset:53248
	ds_read_b128 v[208:211], v151 offset:54272
	ds_read_b128 v[212:215], v151 offset:55296
	ds_read_b128 v[216:219], v151 offset:56320
	global_load_lds_dwordx4 v[144:145], off
	s_add_i32 m0, s25, 0x2000
	s_add_u32 s40, s40, 0x80080
	v_lshl_add_u64 v[144:145], v[192:193], 0, s[16:17]
	s_addc_u32 s41, s41, 0
	s_add_i32 s25, s44, s33
	global_load_lds_dwordx4 v[144:145], off
	v_lshl_add_u64 v[144:145], s[40:41], 0, v[132:133]
	s_mov_b32 m0, s25
	s_nop 0
	global_load_lds_dwordx4 v[144:145], off
	v_lshl_add_u64 v[144:145], s[40:41], 0, v[136:137]
	s_add_i32 m0, s25, 0x2000
	s_nop 0
	global_load_lds_dwordx4 v[144:145], off
	v_lshl_add_u64 v[144:145], v[220:221], 0, s[16:17]
	s_mov_b32 m0, s50
	s_nop 0
	global_load_lds_dwordx4 v[144:145], off
	v_lshl_add_u64 v[144:145], v[222:223], 0, s[16:17]
	s_mov_b32 m0, s51
	s_nop 0
	global_load_lds_dwordx4 v[144:145], off
	s_waitcnt vmcnt(8)
	s_waitcnt lgkmcnt(0)
	s_barrier
	s_setprio 1
	s_waitcnt lgkmcnt(0)
	v_mfma_f32_16x16x32_bf16 v[62:65], v[152:155], v[184:187], v[62:65]
	v_mfma_f32_16x16x32_bf16 v[58:61], v[160:163], v[184:187], v[58:61]
	v_mfma_f32_16x16x32_bf16 v[46:49], v[152:155], v[196:199], v[46:49]
	v_mfma_f32_16x16x32_bf16 v[42:45], v[160:163], v[196:199], v[42:45]
	v_mfma_f32_16x16x32_bf16 v[30:33], v[152:155], v[204:207], v[30:33]
	v_mfma_f32_16x16x32_bf16 v[26:29], v[160:163], v[204:207], v[26:29]
	v_mfma_f32_16x16x32_bf16 v[14:17], v[152:155], v[212:215], v[14:17]
	v_mfma_f32_16x16x32_bf16 v[10:13], v[160:163], v[212:215], v[10:13]
	v_mfma_f32_16x16x32_bf16 v[62:65], v[156:159], v[188:191], v[62:65]
	v_mfma_f32_16x16x32_bf16 v[58:61], v[164:167], v[188:191], v[58:61]
	v_mfma_f32_16x16x32_bf16 v[46:49], v[156:159], v[200:203], v[46:49]
	v_mfma_f32_16x16x32_bf16 v[42:45], v[164:167], v[200:203], v[42:45]
	v_mfma_f32_16x16x32_bf16 v[30:33], v[156:159], v[208:211], v[30:33]
	v_mfma_f32_16x16x32_bf16 v[26:29], v[164:167], v[208:211], v[26:29]
	v_mfma_f32_16x16x32_bf16 v[14:17], v[156:159], v[216:219], v[14:17]
	v_mfma_f32_16x16x32_bf16 v[10:13], v[164:167], v[216:219], v[10:13]
	s_setprio 0
	s_setprio 1
	v_mfma_f32_16x16x32_bf16 v[54:57], v[168:171], v[184:187], v[54:57]
	v_mfma_f32_16x16x32_bf16 v[50:53], v[176:179], v[184:187], v[50:53]
	v_mfma_f32_16x16x32_bf16 v[38:41], v[168:171], v[196:199], v[38:41]
	v_mfma_f32_16x16x32_bf16 v[34:37], v[176:179], v[196:199], v[34:37]
	v_mfma_f32_16x16x32_bf16 v[22:25], v[168:171], v[204:207], v[22:25]
	v_mfma_f32_16x16x32_bf16 v[18:21], v[176:179], v[204:207], v[18:21]
	v_mfma_f32_16x16x32_bf16 v[6:9], v[168:171], v[212:215], v[6:9]
	v_mfma_f32_16x16x32_bf16 v[2:5], v[176:179], v[212:215], v[2:5]
	v_mfma_f32_16x16x32_bf16 v[54:57], v[172:175], v[188:191], v[54:57]
	v_mfma_f32_16x16x32_bf16 v[50:53], v[180:183], v[188:191], v[50:53]
	v_mfma_f32_16x16x32_bf16 v[38:41], v[172:175], v[200:203], v[38:41]
	v_mfma_f32_16x16x32_bf16 v[34:37], v[180:183], v[200:203], v[34:37]
	v_mfma_f32_16x16x32_bf16 v[22:25], v[172:175], v[208:211], v[22:25]
	v_mfma_f32_16x16x32_bf16 v[18:21], v[180:183], v[208:211], v[18:21]
	v_mfma_f32_16x16x32_bf16 v[6:9], v[172:175], v[216:219], v[6:9]
	v_mfma_f32_16x16x32_bf16 v[2:5], v[180:183], v[216:219], v[2:5]
	s_setprio 0
	s_barrier
	s_add_u32 s38, s38, 0x100
	s_addc_u32 s39, s39, 0
	s_add_u32 s21, s21, 0x100
	s_addc_u32 s23, s23, 0
	s_cmp_ge_i32 s37, s62
	s_mov_b32 s25, s37
	s_cbranch_scc0 .LBB0_221
	s_branch .Lpeeldone_13

.Lpeeldone_13:
	s_and_b64 vcc, exec, s[18:19]
	s_cbranch_vccnz .LBB0_229
	s_cmp_gt_i32 s6, -1
	s_mov_b64 s[36:37], -1
	s_cbranch_scc1 .LBB0_230

.Lpeel_12:
	ds_read_b128 v[130:133], v215
	ds_read_b128 v[134:137], v215 offset:1024
	ds_read_b128 v[138:141], v215 offset:2048
	ds_read_b128 v[142:145], v215 offset:3072
	ds_read_b128 v[146:149], v216
	ds_read_b128 v[150:153], v216 offset:1024
	ds_read_b128 v[154:157], v216 offset:2048
	ds_read_b128 v[158:161], v216 offset:3072
	s_add_i32 s38, s34, 2
	s_add_u32 s35, s30, 0xffea0080
	s_addc_u32 s36, s31, -1
	s_cmp_eq_u32 s28, s34
	s_cselect_b32 s34, s26, s23
	s_cselect_b32 s37, s25, s36
	s_cselect_b32 s36, s24, s35
	s_cselect_b32 s35, s27, s29
	v_lshl_add_u64 v[192:193], s[30:31], 0, v[188:189]
	s_add_i32 m0, s40, 0xc000
	ds_read_b128 v[162:165], v217
	ds_read_b128 v[166:169], v217 offset:1024
	ds_read_b128 v[170:173], v217 offset:2048
	ds_read_b128 v[174:177], v217 offset:3072
	ds_read_b128 v[196:199], v217 offset:4096
	ds_read_b128 v[200:203], v217 offset:5120
	ds_read_b128 v[204:207], v217 offset:6144
	ds_read_b128 v[208:211], v217 offset:7168
	global_load_lds_dwordx4 v[192:193], off
	v_lshl_add_u64 v[192:193], s[30:31], 0, v[190:191]
	s_add_i32 m0, s40, 0xe000
	s_nop 0
	global_load_lds_dwordx4 v[192:193], off
	s_waitcnt vmcnt(8)
	s_waitcnt lgkmcnt(0)
	s_barrier
	s_setprio 1
	s_waitcnt lgkmcnt(0)
	v_mfma_f32_16x16x32_bf16 v[126:129], v[130:133], v[162:165], 0
	v_mfma_f32_16x16x32_bf16 v[122:125], v[138:141], v[162:165], 0
	v_mfma_f32_16x16x32_bf16 v[118:121], v[130:133], v[170:173], 0
	v_mfma_f32_16x16x32_bf16 v[114:117], v[138:141], v[170:173], 0
	v_mfma_f32_16x16x32_bf16 v[94:97], v[130:133], v[196:199], 0
	v_mfma_f32_16x16x32_bf16 v[90:93], v[138:141], v[196:199], 0
	v_mfma_f32_16x16x32_bf16 v[86:89], v[130:133], v[204:207], 0
	v_mfma_f32_16x16x32_bf16 v[82:85], v[138:141], v[204:207], 0
	v_mfma_f32_16x16x32_bf16 v[126:129], v[134:137], v[166:169], v[126:129]
	v_mfma_f32_16x16x32_bf16 v[122:125], v[142:145], v[166:169], v[122:125]
	v_mfma_f32_16x16x32_bf16 v[118:121], v[134:137], v[174:177], v[118:121]
	v_mfma_f32_16x16x32_bf16 v[114:117], v[142:145], v[174:177], v[114:117]
	v_mfma_f32_16x16x32_bf16 v[94:97], v[134:137], v[200:203], v[94:97]
	v_mfma_f32_16x16x32_bf16 v[90:93], v[142:145], v[200:203], v[90:93]
	v_mfma_f32_16x16x32_bf16 v[86:89], v[134:137], v[208:211], v[86:89]
	v_mfma_f32_16x16x32_bf16 v[82:85], v[142:145], v[208:211], v[82:85]
	s_setprio 0
	s_setprio 1
	v_mfma_f32_16x16x32_bf16 v[110:113], v[146:149], v[162:165], 0
	v_mfma_f32_16x16x32_bf16 v[106:109], v[154:157], v[162:165], 0
	v_mfma_f32_16x16x32_bf16 v[102:105], v[146:149], v[170:173], 0
	v_mfma_f32_16x16x32_bf16 v[98:101], v[154:157], v[170:173], 0
	v_mfma_f32_16x16x32_bf16 v[78:81], v[146:149], v[196:199], 0
	v_mfma_f32_16x16x32_bf16 v[74:77], v[154:157], v[196:199], 0
	v_mfma_f32_16x16x32_bf16 v[70:73], v[146:149], v[204:207], 0
	v_mfma_f32_16x16x32_bf16 v[66:69], v[154:157], v[204:207], 0
	v_mfma_f32_16x16x32_bf16 v[110:113], v[150:153], v[166:169], v[110:113]
	v_mfma_f32_16x16x32_bf16 v[106:109], v[158:161], v[166:169], v[106:109]
	v_mfma_f32_16x16x32_bf16 v[102:105], v[150:153], v[174:177], v[102:105]
	v_mfma_f32_16x16x32_bf16 v[98:101], v[158:161], v[174:177], v[98:101]
	v_mfma_f32_16x16x32_bf16 v[78:81], v[150:153], v[200:203], v[78:81]
	v_mfma_f32_16x16x32_bf16 v[74:77], v[158:161], v[200:203], v[74:77]
	v_mfma_f32_16x16x32_bf16 v[70:73], v[150:153], v[208:211], v[70:73]
	v_mfma_f32_16x16x32_bf16 v[66:69], v[158:161], v[208:211], v[66:69]
	s_setprio 0
	s_barrier
	s_add_i32 s39, s53, s33
	v_lshl_add_u64 v[192:193], s[34:35], 0, v[180:181]
	s_mov_b32 m0, s39
	ds_read_b128 v[162:165], v217 offset:16384
	ds_read_b128 v[166:169], v217 offset:17408
	ds_read_b128 v[170:173], v217 offset:18432
	ds_read_b128 v[174:177], v217 offset:19456
	ds_read_b128 v[196:199], v217 offset:20480
	ds_read_b128 v[200:203], v217 offset:21504
	ds_read_b128 v[204:207], v217 offset:22528
	ds_read_b128 v[208:211], v217 offset:23552
	global_load_lds_dwordx4 v[192:193], off
	s_add_i32 m0, s39, 0x2000
	s_add_u32 s62, s34, 0x160000
	v_lshl_add_u64 v[218:219], s[34:35], 0, v[184:185]
	s_addc_u32 s63, s35, 0
	s_add_i32 s39, s54, s33
	global_load_lds_dwordx4 v[218:219], off
	v_lshl_add_u64 v[220:221], s[62:63], 0, v[180:181]
	s_mov_b32 m0, s39
	v_lshl_add_u64 v[222:223], s[36:37], 0, v[182:183]
	global_load_lds_dwordx4 v[220:221], off
	v_lshl_add_u64 v[220:221], s[62:63], 0, v[184:185]
	s_add_i32 m0, s39, 0x2000
	s_nop 0
	global_load_lds_dwordx4 v[220:221], off
	v_lshl_add_u64 v[220:221], s[36:37], 0, v[178:179]
	s_mov_b32 m0, s40
	s_nop 0
	global_load_lds_dwordx4 v[220:221], off
	s_mov_b32 m0, s41
	s_nop 0
	global_load_lds_dwordx4 v[222:223], off
	s_waitcnt vmcnt(8)
	s_waitcnt lgkmcnt(0)
	s_barrier
	s_setprio 1
	s_waitcnt lgkmcnt(0)
	v_mfma_f32_16x16x32_bf16 v[62:65], v[130:133], v[162:165], 0
	v_mfma_f32_16x16x32_bf16 v[58:61], v[138:141], v[162:165], 0
	v_mfma_f32_16x16x32_bf16 v[54:57], v[130:133], v[170:173], 0
	v_mfma_f32_16x16x32_bf16 v[50:53], v[138:141], v[170:173], 0
	v_mfma_f32_16x16x32_bf16 v[30:33], v[130:133], v[196:199], 0
	v_mfma_f32_16x16x32_bf16 v[26:29], v[138:141], v[196:199], 0
	v_mfma_f32_16x16x32_bf16 v[22:25], v[130:133], v[204:207], 0
	v_mfma_f32_16x16x32_bf16 v[18:21], v[138:141], v[204:207], 0
	v_mfma_f32_16x16x32_bf16 v[62:65], v[134:137], v[166:169], v[62:65]
	v_mfma_f32_16x16x32_bf16 v[58:61], v[142:145], v[166:169], v[58:61]
	v_mfma_f32_16x16x32_bf16 v[54:57], v[134:137], v[174:177], v[54:57]
	v_mfma_f32_16x16x32_bf16 v[50:53], v[142:145], v[174:177], v[50:53]
	v_mfma_f32_16x16x32_bf16 v[30:33], v[134:137], v[200:203], v[30:33]
	v_mfma_f32_16x16x32_bf16 v[26:29], v[142:145], v[200:203], v[26:29]
	v_mfma_f32_16x16x32_bf16 v[22:25], v[134:137], v[208:211], v[22:25]
	v_mfma_f32_16x16x32_bf16 v[18:21], v[142:145], v[208:211], v[18:21]
	s_setprio 0
	s_setprio 1
	v_mfma_f32_16x16x32_bf16 v[46:49], v[146:149], v[162:165], 0
	v_mfma_f32_16x16x32_bf16 v[42:45], v[154:157], v[162:165], 0
	v_mfma_f32_16x16x32_bf16 v[38:41], v[146:149], v[170:173], 0
	v_mfma_f32_16x16x32_bf16 v[34:37], v[154:157], v[170:173], 0
	v_mfma_f32_16x16x32_bf16 v[14:17], v[146:149], v[196:199], 0
	v_mfma_f32_16x16x32_bf16 v[10:13], v[154:157], v[196:199], 0
	v_mfma_f32_16x16x32_bf16 v[6:9], v[146:149], v[204:207], 0
	v_mfma_f32_16x16x32_bf16 v[2:5], v[154:157], v[204:207], 0
	v_mfma_f32_16x16x32_bf16 v[46:49], v[150:153], v[166:169], v[46:49]
	v_mfma_f32_16x16x32_bf16 v[42:45], v[158:161], v[166:169], v[42:45]
	v_mfma_f32_16x16x32_bf16 v[38:41], v[150:153], v[174:177], v[38:41]
	v_mfma_f32_16x16x32_bf16 v[34:37], v[158:161], v[174:177], v[34:37]
	v_mfma_f32_16x16x32_bf16 v[14:17], v[150:153], v[200:203], v[14:17]
	v_mfma_f32_16x16x32_bf16 v[10:13], v[158:161], v[200:203], v[10:13]
	v_mfma_f32_16x16x32_bf16 v[6:9], v[150:153], v[208:211], v[6:9]
	v_mfma_f32_16x16x32_bf16 v[2:5], v[158:161], v[208:211], v[2:5]
	s_setprio 0
	s_barrier
	s_add_i32 s39, 0, 0x18000
	s_add_i32 s62, 0, 0x1c000
	v_add_u32_e32 v142, s39, v213
	v_add_u32_e32 v158, s62, v213
	ds_read_b128 v[130:133], v142
	ds_read_b128 v[134:137], v142 offset:1024
	ds_read_b128 v[138:141], v142 offset:2048
	ds_read_b128 v[142:145], v142 offset:3072
	ds_read_b128 v[146:149], v158
	ds_read_b128 v[150:153], v158 offset:1024
	ds_read_b128 v[154:157], v158 offset:2048
	ds_read_b128 v[158:161], v158 offset:3072
	s_add_u32 s36, s36, 0x160000
	s_addc_u32 s37, s37, 0
	s_mov_b32 m0, s42
	v_lshl_add_u64 v[224:225], s[36:37], 0, v[178:179]
	ds_read_b128 v[162:165], v217 offset:32768
	ds_read_b128 v[166:169], v217 offset:33792
	ds_read_b128 v[170:173], v217 offset:34816
	ds_read_b128 v[174:177], v217 offset:35840
	ds_read_b128 v[196:199], v217 offset:36864
	ds_read_b128 v[200:203], v217 offset:37888
	ds_read_b128 v[204:207], v217 offset:38912
	ds_read_b128 v[208:211], v217 offset:39936
	global_load_lds_dwordx4 v[224:225], off
	v_lshl_add_u64 v[224:225], s[36:37], 0, v[182:183]
	s_mov_b32 m0, s43
	s_nop 0
	global_load_lds_dwordx4 v[224:225], off
	s_waitcnt vmcnt(8)
	s_waitcnt lgkmcnt(0)
	s_barrier
	s_setprio 1
	s_waitcnt lgkmcnt(0)
	v_mfma_f32_16x16x32_bf16 v[126:129], v[130:133], v[162:165], v[126:129]
	v_mfma_f32_16x16x32_bf16 v[122:125], v[138:141], v[162:165], v[122:125]
	v_mfma_f32_16x16x32_bf16 v[118:121], v[130:133], v[170:173], v[118:121]
	v_mfma_f32_16x16x32_bf16 v[114:117], v[138:141], v[170:173], v[114:117]
	v_mfma_f32_16x16x32_bf16 v[94:97], v[130:133], v[196:199], v[94:97]
	v_mfma_f32_16x16x32_bf16 v[90:93], v[138:141], v[196:199], v[90:93]
	v_mfma_f32_16x16x32_bf16 v[86:89], v[130:133], v[204:207], v[86:89]
	v_mfma_f32_16x16x32_bf16 v[82:85], v[138:141], v[204:207], v[82:85]
	v_mfma_f32_16x16x32_bf16 v[126:129], v[134:137], v[166:169], v[126:129]
	v_mfma_f32_16x16x32_bf16 v[122:125], v[142:145], v[166:169], v[122:125]
	v_mfma_f32_16x16x32_bf16 v[118:121], v[134:137], v[174:177], v[118:121]
	v_mfma_f32_16x16x32_bf16 v[114:117], v[142:145], v[174:177], v[114:117]
	v_mfma_f32_16x16x32_bf16 v[94:97], v[134:137], v[200:203], v[94:97]
	v_mfma_f32_16x16x32_bf16 v[90:93], v[142:145], v[200:203], v[90:93]
	v_mfma_f32_16x16x32_bf16 v[86:89], v[134:137], v[208:211], v[86:89]
	v_mfma_f32_16x16x32_bf16 v[82:85], v[142:145], v[208:211], v[82:85]
	s_setprio 0
	s_setprio 1
	v_mfma_f32_16x16x32_bf16 v[110:113], v[146:149], v[162:165], v[110:113]
	v_mfma_f32_16x16x32_bf16 v[106:109], v[154:157], v[162:165], v[106:109]
	v_mfma_f32_16x16x32_bf16 v[102:105], v[146:149], v[170:173], v[102:105]
	v_mfma_f32_16x16x32_bf16 v[98:101], v[154:157], v[170:173], v[98:101]
	v_mfma_f32_16x16x32_bf16 v[78:81], v[146:149], v[196:199], v[78:81]
	v_mfma_f32_16x16x32_bf16 v[74:77], v[154:157], v[196:199], v[74:77]
	v_mfma_f32_16x16x32_bf16 v[70:73], v[146:149], v[204:207], v[70:73]
	v_mfma_f32_16x16x32_bf16 v[66:69], v[154:157], v[204:207], v[66:69]
	v_mfma_f32_16x16x32_bf16 v[110:113], v[150:153], v[166:169], v[110:113]
	v_mfma_f32_16x16x32_bf16 v[106:109], v[158:161], v[166:169], v[106:109]
	v_mfma_f32_16x16x32_bf16 v[102:105], v[150:153], v[174:177], v[102:105]
	v_mfma_f32_16x16x32_bf16 v[98:101], v[158:161], v[174:177], v[98:101]
	v_mfma_f32_16x16x32_bf16 v[78:81], v[150:153], v[200:203], v[78:81]
	v_mfma_f32_16x16x32_bf16 v[74:77], v[158:161], v[200:203], v[74:77]
	v_mfma_f32_16x16x32_bf16 v[70:73], v[150:153], v[208:211], v[70:73]
	v_mfma_f32_16x16x32_bf16 v[66:69], v[158:161], v[208:211], v[66:69]
	s_setprio 0
	s_barrier
	s_add_i32 s36, s39, s33
	v_lshl_add_u64 v[192:193], v[192:193], 0, s[18:19]
	s_mov_b32 m0, s36
	ds_read_b128 v[162:165], v217 offset:49152
	ds_read_b128 v[166:169], v217 offset:50176
	ds_read_b128 v[170:173], v217 offset:51200
	ds_read_b128 v[174:177], v217 offset:52224
	ds_read_b128 v[196:199], v217 offset:53248
	ds_read_b128 v[200:203], v217 offset:54272
	ds_read_b128 v[204:207], v217 offset:55296
	ds_read_b128 v[208:211], v217 offset:56320
	global_load_lds_dwordx4 v[192:193], off
	s_add_i32 m0, s36, 0x2000
	s_add_u32 s34, s34, 0x160080
	v_lshl_add_u64 v[192:193], v[218:219], 0, s[18:19]
	s_addc_u32 s35, s35, 0
	s_add_i32 s36, s62, s33
	global_load_lds_dwordx4 v[192:193], off
	v_lshl_add_u64 v[192:193], s[34:35], 0, v[180:181]
	s_mov_b32 m0, s36
	s_nop 0
	global_load_lds_dwordx4 v[192:193], off
	v_lshl_add_u64 v[192:193], s[34:35], 0, v[184:185]
	s_add_i32 m0, s36, 0x2000
	s_nop 0
	global_load_lds_dwordx4 v[192:193], off
	v_lshl_add_u64 v[192:193], v[220:221], 0, s[18:19]
	s_mov_b32 m0, s46
	s_nop 0
	global_load_lds_dwordx4 v[192:193], off
	v_lshl_add_u64 v[192:193], v[222:223], 0, s[18:19]
	s_mov_b32 m0, s47
	s_nop 0
	global_load_lds_dwordx4 v[192:193], off
	s_waitcnt vmcnt(8)
	s_waitcnt lgkmcnt(0)
	s_barrier
	s_setprio 1
	s_waitcnt lgkmcnt(0)
	v_mfma_f32_16x16x32_bf16 v[62:65], v[130:133], v[162:165], v[62:65]
	v_mfma_f32_16x16x32_bf16 v[58:61], v[138:141], v[162:165], v[58:61]
	v_mfma_f32_16x16x32_bf16 v[54:57], v[130:133], v[170:173], v[54:57]
	v_mfma_f32_16x16x32_bf16 v[50:53], v[138:141], v[170:173], v[50:53]
	v_mfma_f32_16x16x32_bf16 v[30:33], v[130:133], v[196:199], v[30:33]
	v_mfma_f32_16x16x32_bf16 v[26:29], v[138:141], v[196:199], v[26:29]
	v_mfma_f32_16x16x32_bf16 v[22:25], v[130:133], v[204:207], v[22:25]
	v_mfma_f32_16x16x32_bf16 v[18:21], v[138:141], v[204:207], v[18:21]
	v_mfma_f32_16x16x32_bf16 v[62:65], v[134:137], v[166:169], v[62:65]
	v_mfma_f32_16x16x32_bf16 v[58:61], v[142:145], v[166:169], v[58:61]
	v_mfma_f32_16x16x32_bf16 v[54:57], v[134:137], v[174:177], v[54:57]
	v_mfma_f32_16x16x32_bf16 v[50:53], v[142:145], v[174:177], v[50:53]
	v_mfma_f32_16x16x32_bf16 v[30:33], v[134:137], v[200:203], v[30:33]
	v_mfma_f32_16x16x32_bf16 v[26:29], v[142:145], v[200:203], v[26:29]
	v_mfma_f32_16x16x32_bf16 v[22:25], v[134:137], v[208:211], v[22:25]
	v_mfma_f32_16x16x32_bf16 v[18:21], v[142:145], v[208:211], v[18:21]
	s_setprio 0
	s_setprio 1
	v_mfma_f32_16x16x32_bf16 v[46:49], v[146:149], v[162:165], v[46:49]
	v_mfma_f32_16x16x32_bf16 v[42:45], v[154:157], v[162:165], v[42:45]
	v_mfma_f32_16x16x32_bf16 v[38:41], v[146:149], v[170:173], v[38:41]
	v_mfma_f32_16x16x32_bf16 v[34:37], v[154:157], v[170:173], v[34:37]
	v_mfma_f32_16x16x32_bf16 v[14:17], v[146:149], v[196:199], v[14:17]
	v_mfma_f32_16x16x32_bf16 v[10:13], v[154:157], v[196:199], v[10:13]
	v_mfma_f32_16x16x32_bf16 v[6:9], v[146:149], v[204:207], v[6:9]
	v_mfma_f32_16x16x32_bf16 v[2:5], v[154:157], v[204:207], v[2:5]
	v_mfma_f32_16x16x32_bf16 v[46:49], v[150:153], v[166:169], v[46:49]
	v_mfma_f32_16x16x32_bf16 v[42:45], v[158:161], v[166:169], v[42:45]
	v_mfma_f32_16x16x32_bf16 v[38:41], v[150:153], v[174:177], v[38:41]
	v_mfma_f32_16x16x32_bf16 v[34:37], v[158:161], v[174:177], v[34:37]
	v_mfma_f32_16x16x32_bf16 v[14:17], v[150:153], v[200:203], v[14:17]
	v_mfma_f32_16x16x32_bf16 v[10:13], v[158:161], v[200:203], v[10:13]
	v_mfma_f32_16x16x32_bf16 v[6:9], v[150:153], v[208:211], v[6:9]
	v_mfma_f32_16x16x32_bf16 v[2:5], v[158:161], v[208:211], v[2:5]
	s_setprio 0
	s_barrier
	s_add_u32 s30, s30, 0x100
	s_addc_u32 s31, s31, 0
	s_add_u32 s23, s23, 0x100
	s_addc_u32 s29, s29, 0
	s_cmp_ge_i32 s38, s61
	s_mov_b32 s34, s38
	s_cbranch_scc0 .LBB0_357
	s_branch .Lpeeldone_12

.Lpeeldone_12:
	s_and_b64 vcc, exec, s[20:21]
	s_cbranch_vccnz .LBB0_365
	s_cmp_gt_i32 s6, -1
	s_mov_b64 s[28:29], -1
	s_cbranch_scc1 .LBB0_366

.Lpeel_11:
	ds_read_b128 v[148:151], v145
	ds_read_b128 v[152:155], v145 offset:1024
	ds_read_b128 v[156:159], v145 offset:2048
	ds_read_b128 v[160:163], v145 offset:3072
	ds_read_b128 v[164:167], v146
	ds_read_b128 v[168:171], v146 offset:1024
	ds_read_b128 v[172:175], v146 offset:2048
	ds_read_b128 v[176:179], v146 offset:3072
	s_add_u32 s36, s34, 0xfff80080
	s_addc_u32 s37, s35, -1
	s_cmp_eq_u32 s58, 28
	s_cselect_b32 s39, s21, s37
	s_cselect_b32 s38, s54, s36
	s_cselect_b32 s37, s23, s57
	s_cselect_b32 s36, s55, s56
	v_lshl_add_u64 v[192:193], s[34:35], 0, v[138:139]
	s_add_i32 m0, s27, 0xc000
	ds_read_b128 v[180:183], v147
	ds_read_b128 v[184:187], v147 offset:1024
	ds_read_b128 v[188:191], v147 offset:2048
	ds_read_b128 v[196:199], v147 offset:3072
	ds_read_b128 v[200:203], v147 offset:4096
	ds_read_b128 v[204:207], v147 offset:5120
	ds_read_b128 v[208:211], v147 offset:6144
	ds_read_b128 v[212:215], v147 offset:7168
	global_load_lds_dwordx4 v[192:193], off
	v_lshl_add_u64 v[192:193], s[34:35], 0, v[140:141]
	s_add_i32 m0, s27, 0xe000
	s_nop 0
	global_load_lds_dwordx4 v[192:193], off
	s_waitcnt vmcnt(8)
	s_waitcnt lgkmcnt(0)
	s_barrier
	s_setprio 1
	s_waitcnt lgkmcnt(0)
	v_mfma_f32_16x16x32_bf16 v[126:129], v[148:151], v[180:183], 0
	v_mfma_f32_16x16x32_bf16 v[122:125], v[156:159], v[180:183], 0
	v_mfma_f32_16x16x32_bf16 v[118:121], v[148:151], v[188:191], 0
	v_mfma_f32_16x16x32_bf16 v[114:117], v[156:159], v[188:191], 0
	v_mfma_f32_16x16x32_bf16 v[102:105], v[148:151], v[200:203], 0
	v_mfma_f32_16x16x32_bf16 v[98:101], v[156:159], v[200:203], 0
	v_mfma_f32_16x16x32_bf16 v[86:89], v[148:151], v[208:211], 0
	v_mfma_f32_16x16x32_bf16 v[82:85], v[156:159], v[208:211], 0
	v_mfma_f32_16x16x32_bf16 v[126:129], v[152:155], v[184:187], v[126:129]
	v_mfma_f32_16x16x32_bf16 v[122:125], v[160:163], v[184:187], v[122:125]
	v_mfma_f32_16x16x32_bf16 v[118:121], v[152:155], v[196:199], v[118:121]
	v_mfma_f32_16x16x32_bf16 v[114:117], v[160:163], v[196:199], v[114:117]
	v_mfma_f32_16x16x32_bf16 v[102:105], v[152:155], v[204:207], v[102:105]
	v_mfma_f32_16x16x32_bf16 v[98:101], v[160:163], v[204:207], v[98:101]
	v_mfma_f32_16x16x32_bf16 v[86:89], v[152:155], v[212:215], v[86:89]
	v_mfma_f32_16x16x32_bf16 v[82:85], v[160:163], v[212:215], v[82:85]
	s_setprio 0
	s_setprio 1
	v_mfma_f32_16x16x32_bf16 v[110:113], v[164:167], v[180:183], 0
	v_mfma_f32_16x16x32_bf16 v[106:109], v[172:175], v[180:183], 0
	v_mfma_f32_16x16x32_bf16 v[94:97], v[164:167], v[188:191], 0
	v_mfma_f32_16x16x32_bf16 v[90:93], v[172:175], v[188:191], 0
	v_mfma_f32_16x16x32_bf16 v[78:81], v[164:167], v[200:203], 0
	v_mfma_f32_16x16x32_bf16 v[74:77], v[172:175], v[200:203], 0
	v_mfma_f32_16x16x32_bf16 v[70:73], v[164:167], v[208:211], 0
	v_mfma_f32_16x16x32_bf16 v[66:69], v[172:175], v[208:211], 0
	v_mfma_f32_16x16x32_bf16 v[110:113], v[168:171], v[184:187], v[110:113]
	v_mfma_f32_16x16x32_bf16 v[106:109], v[176:179], v[184:187], v[106:109]
	v_mfma_f32_16x16x32_bf16 v[94:97], v[168:171], v[196:199], v[94:97]
	v_mfma_f32_16x16x32_bf16 v[90:93], v[176:179], v[196:199], v[90:93]
	v_mfma_f32_16x16x32_bf16 v[78:81], v[168:171], v[204:207], v[78:81]
	v_mfma_f32_16x16x32_bf16 v[74:77], v[176:179], v[204:207], v[74:77]
	v_mfma_f32_16x16x32_bf16 v[70:73], v[168:171], v[212:215], v[70:73]
	v_mfma_f32_16x16x32_bf16 v[66:69], v[176:179], v[212:215], v[66:69]
	s_setprio 0
	s_barrier
	s_add_i32 s59, s47, s33
	v_lshl_add_u64 v[192:193], s[36:37], 0, v[134:135]
	s_mov_b32 m0, s59
	ds_read_b128 v[180:183], v147 offset:16384
	ds_read_b128 v[184:187], v147 offset:17408
	ds_read_b128 v[188:191], v147 offset:18432
	ds_read_b128 v[196:199], v147 offset:19456
	ds_read_b128 v[200:203], v147 offset:20480
	ds_read_b128 v[204:207], v147 offset:21504
	ds_read_b128 v[208:211], v147 offset:22528
	ds_read_b128 v[212:215], v147 offset:23552
	global_load_lds_dwordx4 v[192:193], off
	s_add_i32 m0, s59, 0x2000
	s_add_u32 s60, s36, 0x80000
	v_lshl_add_u64 v[216:217], s[36:37], 0, v[130:131]
	s_addc_u32 s61, s37, 0
	s_add_i32 s59, s48, s33
	global_load_lds_dwordx4 v[216:217], off
	v_lshl_add_u64 v[218:219], s[60:61], 0, v[134:135]
	s_mov_b32 m0, s59
	v_lshl_add_u64 v[220:221], s[38:39], 0, v[132:133]
	global_load_lds_dwordx4 v[218:219], off
	v_lshl_add_u64 v[218:219], s[60:61], 0, v[130:131]
	s_add_i32 m0, s59, 0x2000
	s_nop 0
	global_load_lds_dwordx4 v[218:219], off
	v_lshl_add_u64 v[218:219], s[38:39], 0, v[136:137]
	s_mov_b32 m0, s27
	s_nop 0
	global_load_lds_dwordx4 v[218:219], off
	s_mov_b32 m0, s41
	s_nop 0
	global_load_lds_dwordx4 v[220:221], off
	s_waitcnt vmcnt(8)
	s_waitcnt lgkmcnt(0)
	s_barrier
	s_setprio 1
	s_waitcnt lgkmcnt(0)
	v_mfma_f32_16x16x32_bf16 v[62:65], v[148:151], v[180:183], 0
	v_mfma_f32_16x16x32_bf16 v[58:61], v[156:159], v[180:183], 0
	v_mfma_f32_16x16x32_bf16 v[54:57], v[148:151], v[188:191], 0
	v_mfma_f32_16x16x32_bf16 v[50:53], v[156:159], v[188:191], 0
	v_mfma_f32_16x16x32_bf16 v[38:41], v[148:151], v[200:203], 0
	v_mfma_f32_16x16x32_bf16 v[34:37], v[156:159], v[200:203], 0
	v_mfma_f32_16x16x32_bf16 v[22:25], v[148:151], v[208:211], 0
	v_mfma_f32_16x16x32_bf16 v[18:21], v[156:159], v[208:211], 0
	v_mfma_f32_16x16x32_bf16 v[62:65], v[152:155], v[184:187], v[62:65]
	v_mfma_f32_16x16x32_bf16 v[58:61], v[160:163], v[184:187], v[58:61]
	v_mfma_f32_16x16x32_bf16 v[54:57], v[152:155], v[196:199], v[54:57]
	v_mfma_f32_16x16x32_bf16 v[50:53], v[160:163], v[196:199], v[50:53]
	v_mfma_f32_16x16x32_bf16 v[38:41], v[152:155], v[204:207], v[38:41]
	v_mfma_f32_16x16x32_bf16 v[34:37], v[160:163], v[204:207], v[34:37]
	v_mfma_f32_16x16x32_bf16 v[22:25], v[152:155], v[212:215], v[22:25]
	v_mfma_f32_16x16x32_bf16 v[18:21], v[160:163], v[212:215], v[18:21]
	s_setprio 0
	s_setprio 1
	v_mfma_f32_16x16x32_bf16 v[46:49], v[164:167], v[180:183], 0
	v_mfma_f32_16x16x32_bf16 v[42:45], v[172:175], v[180:183], 0
	v_mfma_f32_16x16x32_bf16 v[30:33], v[164:167], v[188:191], 0
	v_mfma_f32_16x16x32_bf16 v[26:29], v[172:175], v[188:191], 0
	v_mfma_f32_16x16x32_bf16 v[14:17], v[164:167], v[200:203], 0
	v_mfma_f32_16x16x32_bf16 v[10:13], v[172:175], v[200:203], 0
	v_mfma_f32_16x16x32_bf16 v[6:9], v[164:167], v[208:211], 0
	v_mfma_f32_16x16x32_bf16 v[2:5], v[172:175], v[208:211], 0
	v_mfma_f32_16x16x32_bf16 v[46:49], v[168:171], v[184:187], v[46:49]
	v_mfma_f32_16x16x32_bf16 v[42:45], v[176:179], v[184:187], v[42:45]
	v_mfma_f32_16x16x32_bf16 v[30:33], v[168:171], v[196:199], v[30:33]
	v_mfma_f32_16x16x32_bf16 v[26:29], v[176:179], v[196:199], v[26:29]
	v_mfma_f32_16x16x32_bf16 v[14:17], v[168:171], v[204:207], v[14:17]
	v_mfma_f32_16x16x32_bf16 v[10:13], v[176:179], v[204:207], v[10:13]
	v_mfma_f32_16x16x32_bf16 v[6:9], v[168:171], v[212:215], v[6:9]
	v_mfma_f32_16x16x32_bf16 v[2:5], v[176:179], v[212:215], v[2:5]
	s_setprio 0
	s_barrier
	s_add_i32 s59, 0, 0x18000
	s_add_i32 s60, 0, 0x1c000
	v_add_u32_e32 v160, s59, v143
	v_add_u32_e32 v176, s60, v143
	ds_read_b128 v[148:151], v160
	ds_read_b128 v[152:155], v160 offset:1024
	ds_read_b128 v[156:159], v160 offset:2048
	ds_read_b128 v[160:163], v160 offset:3072
	ds_read_b128 v[164:167], v176
	ds_read_b128 v[168:171], v176 offset:1024
	ds_read_b128 v[172:175], v176 offset:2048
	ds_read_b128 v[176:179], v176 offset:3072
	s_add_u32 s38, s38, 0x80000
	s_addc_u32 s39, s39, 0
	s_mov_b32 m0, s42
	v_lshl_add_u64 v[222:223], s[38:39], 0, v[136:137]
	ds_read_b128 v[180:183], v147 offset:32768
	ds_read_b128 v[184:187], v147 offset:33792
	ds_read_b128 v[188:191], v147 offset:34816
	ds_read_b128 v[196:199], v147 offset:35840
	ds_read_b128 v[200:203], v147 offset:36864
	ds_read_b128 v[204:207], v147 offset:37888
	ds_read_b128 v[208:211], v147 offset:38912
	ds_read_b128 v[212:215], v147 offset:39936
	global_load_lds_dwordx4 v[222:223], off
	v_lshl_add_u64 v[222:223], s[38:39], 0, v[132:133]
	s_mov_b32 m0, s43
	s_nop 0
	global_load_lds_dwordx4 v[222:223], off
	s_waitcnt vmcnt(8)
	s_waitcnt lgkmcnt(0)
	s_barrier
	s_setprio 1
	s_waitcnt lgkmcnt(0)
	v_mfma_f32_16x16x32_bf16 v[126:129], v[148:151], v[180:183], v[126:129]
	v_mfma_f32_16x16x32_bf16 v[122:125], v[156:159], v[180:183], v[122:125]
	v_mfma_f32_16x16x32_bf16 v[118:121], v[148:151], v[188:191], v[118:121]
	v_mfma_f32_16x16x32_bf16 v[114:117], v[156:159], v[188:191], v[114:117]
	v_mfma_f32_16x16x32_bf16 v[102:105], v[148:151], v[200:203], v[102:105]
	v_mfma_f32_16x16x32_bf16 v[98:101], v[156:159], v[200:203], v[98:101]
	v_mfma_f32_16x16x32_bf16 v[86:89], v[148:151], v[208:211], v[86:89]
	v_mfma_f32_16x16x32_bf16 v[82:85], v[156:159], v[208:211], v[82:85]
	v_mfma_f32_16x16x32_bf16 v[126:129], v[152:155], v[184:187], v[126:129]
	v_mfma_f32_16x16x32_bf16 v[122:125], v[160:163], v[184:187], v[122:125]
	v_mfma_f32_16x16x32_bf16 v[118:121], v[152:155], v[196:199], v[118:121]
	v_mfma_f32_16x16x32_bf16 v[114:117], v[160:163], v[196:199], v[114:117]
	v_mfma_f32_16x16x32_bf16 v[102:105], v[152:155], v[204:207], v[102:105]
	v_mfma_f32_16x16x32_bf16 v[98:101], v[160:163], v[204:207], v[98:101]
	v_mfma_f32_16x16x32_bf16 v[86:89], v[152:155], v[212:215], v[86:89]
	v_mfma_f32_16x16x32_bf16 v[82:85], v[160:163], v[212:215], v[82:85]
	s_setprio 0
	s_setprio 1
	v_mfma_f32_16x16x32_bf16 v[110:113], v[164:167], v[180:183], v[110:113]
	v_mfma_f32_16x16x32_bf16 v[106:109], v[172:175], v[180:183], v[106:109]
	v_mfma_f32_16x16x32_bf16 v[94:97], v[164:167], v[188:191], v[94:97]
	v_mfma_f32_16x16x32_bf16 v[90:93], v[172:175], v[188:191], v[90:93]
	v_mfma_f32_16x16x32_bf16 v[78:81], v[164:167], v[200:203], v[78:81]
	v_mfma_f32_16x16x32_bf16 v[74:77], v[172:175], v[200:203], v[74:77]
	v_mfma_f32_16x16x32_bf16 v[70:73], v[164:167], v[208:211], v[70:73]
	v_mfma_f32_16x16x32_bf16 v[66:69], v[172:175], v[208:211], v[66:69]
	v_mfma_f32_16x16x32_bf16 v[110:113], v[168:171], v[184:187], v[110:113]
	v_mfma_f32_16x16x32_bf16 v[106:109], v[176:179], v[184:187], v[106:109]
	v_mfma_f32_16x16x32_bf16 v[94:97], v[168:171], v[196:199], v[94:97]
	v_mfma_f32_16x16x32_bf16 v[90:93], v[176:179], v[196:199], v[90:93]
	v_mfma_f32_16x16x32_bf16 v[78:81], v[168:171], v[204:207], v[78:81]
	v_mfma_f32_16x16x32_bf16 v[74:77], v[176:179], v[204:207], v[74:77]
	v_mfma_f32_16x16x32_bf16 v[70:73], v[168:171], v[212:215], v[70:73]
	v_mfma_f32_16x16x32_bf16 v[66:69], v[176:179], v[212:215], v[66:69]
	s_setprio 0
	s_barrier
	s_add_i32 s38, s59, s33
	v_lshl_add_u64 v[192:193], v[192:193], 0, s[6:7]
	s_mov_b32 m0, s38
	ds_read_b128 v[180:183], v147 offset:49152
	ds_read_b128 v[184:187], v147 offset:50176
	ds_read_b128 v[188:191], v147 offset:51200
	ds_read_b128 v[196:199], v147 offset:52224
	ds_read_b128 v[200:203], v147 offset:53248
	ds_read_b128 v[204:207], v147 offset:54272
	ds_read_b128 v[208:211], v147 offset:55296
	ds_read_b128 v[212:215], v147 offset:56320
	global_load_lds_dwordx4 v[192:193], off
	s_add_i32 m0, s38, 0x2000
	s_add_u32 s36, s36, 0x80080
	v_lshl_add_u64 v[192:193], v[216:217], 0, s[6:7]
	s_addc_u32 s37, s37, 0
	s_add_i32 s38, s60, s33
	global_load_lds_dwordx4 v[192:193], off
	v_lshl_add_u64 v[192:193], s[36:37], 0, v[134:135]
	s_mov_b32 m0, s38
	s_nop 0
	global_load_lds_dwordx4 v[192:193], off
	v_lshl_add_u64 v[192:193], s[36:37], 0, v[130:131]
	s_add_i32 m0, s38, 0x2000
	s_nop 0
	global_load_lds_dwordx4 v[192:193], off
	v_lshl_add_u64 v[192:193], v[218:219], 0, s[6:7]
	s_mov_b32 m0, s45
	s_nop 0
	global_load_lds_dwordx4 v[192:193], off
	v_lshl_add_u64 v[192:193], v[220:221], 0, s[6:7]
	s_mov_b32 m0, s46
	s_nop 0
	global_load_lds_dwordx4 v[192:193], off
	s_waitcnt vmcnt(8)
	s_waitcnt lgkmcnt(0)
	s_barrier
	s_setprio 1
	s_waitcnt lgkmcnt(0)
	v_mfma_f32_16x16x32_bf16 v[62:65], v[148:151], v[180:183], v[62:65]
	v_mfma_f32_16x16x32_bf16 v[58:61], v[156:159], v[180:183], v[58:61]
	v_mfma_f32_16x16x32_bf16 v[54:57], v[148:151], v[188:191], v[54:57]
	v_mfma_f32_16x16x32_bf16 v[50:53], v[156:159], v[188:191], v[50:53]
	v_mfma_f32_16x16x32_bf16 v[38:41], v[148:151], v[200:203], v[38:41]
	v_mfma_f32_16x16x32_bf16 v[34:37], v[156:159], v[200:203], v[34:37]
	v_mfma_f32_16x16x32_bf16 v[22:25], v[148:151], v[208:211], v[22:25]
	v_mfma_f32_16x16x32_bf16 v[18:21], v[156:159], v[208:211], v[18:21]
	v_mfma_f32_16x16x32_bf16 v[62:65], v[152:155], v[184:187], v[62:65]
	v_mfma_f32_16x16x32_bf16 v[58:61], v[160:163], v[184:187], v[58:61]
	v_mfma_f32_16x16x32_bf16 v[54:57], v[152:155], v[196:199], v[54:57]
	v_mfma_f32_16x16x32_bf16 v[50:53], v[160:163], v[196:199], v[50:53]
	v_mfma_f32_16x16x32_bf16 v[38:41], v[152:155], v[204:207], v[38:41]
	v_mfma_f32_16x16x32_bf16 v[34:37], v[160:163], v[204:207], v[34:37]
	v_mfma_f32_16x16x32_bf16 v[22:25], v[152:155], v[212:215], v[22:25]
	v_mfma_f32_16x16x32_bf16 v[18:21], v[160:163], v[212:215], v[18:21]
	s_setprio 0
	s_setprio 1
	v_mfma_f32_16x16x32_bf16 v[46:49], v[164:167], v[180:183], v[46:49]
	v_mfma_f32_16x16x32_bf16 v[42:45], v[172:175], v[180:183], v[42:45]
	v_mfma_f32_16x16x32_bf16 v[30:33], v[164:167], v[188:191], v[30:33]
	v_mfma_f32_16x16x32_bf16 v[26:29], v[172:175], v[188:191], v[26:29]
	v_mfma_f32_16x16x32_bf16 v[14:17], v[164:167], v[200:203], v[14:17]
	v_mfma_f32_16x16x32_bf16 v[10:13], v[172:175], v[200:203], v[10:13]
	v_mfma_f32_16x16x32_bf16 v[6:9], v[164:167], v[208:211], v[6:9]
	v_mfma_f32_16x16x32_bf16 v[2:5], v[172:175], v[208:211], v[2:5]
	v_mfma_f32_16x16x32_bf16 v[46:49], v[168:171], v[184:187], v[46:49]
	v_mfma_f32_16x16x32_bf16 v[42:45], v[176:179], v[184:187], v[42:45]
	v_mfma_f32_16x16x32_bf16 v[30:33], v[168:171], v[196:199], v[30:33]
	v_mfma_f32_16x16x32_bf16 v[26:29], v[176:179], v[196:199], v[26:29]
	v_mfma_f32_16x16x32_bf16 v[14:17], v[168:171], v[204:207], v[14:17]
	v_mfma_f32_16x16x32_bf16 v[10:13], v[176:179], v[204:207], v[10:13]
	v_mfma_f32_16x16x32_bf16 v[6:9], v[168:171], v[212:215], v[6:9]
	v_mfma_f32_16x16x32_bf16 v[2:5], v[176:179], v[212:215], v[2:5]
	s_setprio 0
	s_barrier
	s_add_i32 s58, s58, 2
	s_add_u32 s34, s34, 0x100
	s_addc_u32 s35, s35, 0
	s_add_u32 s56, s56, 0x100
	s_addc_u32 s57, s57, 0
	s_cmp_gt_u32 s58, 29
	s_cbranch_scc0 .LBB0_541
	s_branch .Lpeeldone_11

.Lpeeldone_11:
	s_and_b64 vcc, exec, s[8:9]
	s_cbranch_vccz .LBB0_544
	s_barrier

.Lpeel_10:
	ds_read_b128 v[150:153], v147
	ds_read_b128 v[154:157], v147 offset:1024
	ds_read_b128 v[158:161], v147 offset:2048
	ds_read_b128 v[162:165], v147 offset:3072
	ds_read_b128 v[166:169], v148
	ds_read_b128 v[170:173], v148 offset:1024
	ds_read_b128 v[174:177], v148 offset:2048
	ds_read_b128 v[178:181], v148 offset:3072
	s_add_u32 s28, s26, 0xfffe0080
	s_addc_u32 s29, s27, -1
	s_cmp_eq_u32 s50, 4
	s_cselect_b32 s31, s13, s29
	s_cselect_b32 s30, s46, s28
	s_cselect_b32 s29, s17, s49
	s_cselect_b32 s28, s47, s48
	v_lshl_add_u64 v[202:203], s[26:27], 0, v[138:139]
	s_add_i32 m0, s36, 0xc000
	ds_read_b128 v[182:185], v149
	ds_read_b128 v[186:189], v149 offset:1024
	ds_read_b128 v[190:193], v149 offset:2048
	ds_read_b128 v[198:201], v149 offset:3072
	ds_read_b128 v[210:213], v149 offset:4096
	ds_read_b128 v[214:217], v149 offset:5120
	ds_read_b128 v[218:221], v149 offset:6144
	ds_read_b128 v[222:225], v149 offset:7168
	global_load_lds_dwordx4 v[202:203], off
	v_lshl_add_u64 v[202:203], s[26:27], 0, v[140:141]
	s_add_i32 m0, s36, 0xe000
	s_nop 0
	global_load_lds_dwordx4 v[202:203], off
	s_waitcnt vmcnt(8)
	s_waitcnt lgkmcnt(0)
	s_barrier
	s_setprio 1
	s_waitcnt lgkmcnt(0)
	v_mfma_f32_16x16x32_bf16 v[126:129], v[150:153], v[182:185], 0
	v_mfma_f32_16x16x32_bf16 v[122:125], v[158:161], v[182:185], 0
	v_mfma_f32_16x16x32_bf16 v[118:121], v[150:153], v[190:193], 0
	v_mfma_f32_16x16x32_bf16 v[114:117], v[158:161], v[190:193], 0
	v_mfma_f32_16x16x32_bf16 v[102:105], v[150:153], v[210:213], 0
	v_mfma_f32_16x16x32_bf16 v[98:101], v[158:161], v[210:213], 0
	v_mfma_f32_16x16x32_bf16 v[86:89], v[150:153], v[218:221], 0
	v_mfma_f32_16x16x32_bf16 v[82:85], v[158:161], v[218:221], 0
	v_mfma_f32_16x16x32_bf16 v[126:129], v[154:157], v[186:189], v[126:129]
	v_mfma_f32_16x16x32_bf16 v[122:125], v[162:165], v[186:189], v[122:125]
	v_mfma_f32_16x16x32_bf16 v[118:121], v[154:157], v[198:201], v[118:121]
	v_mfma_f32_16x16x32_bf16 v[114:117], v[162:165], v[198:201], v[114:117]
	v_mfma_f32_16x16x32_bf16 v[102:105], v[154:157], v[214:217], v[102:105]
	v_mfma_f32_16x16x32_bf16 v[98:101], v[162:165], v[214:217], v[98:101]
	v_mfma_f32_16x16x32_bf16 v[86:89], v[154:157], v[222:225], v[86:89]
	v_mfma_f32_16x16x32_bf16 v[82:85], v[162:165], v[222:225], v[82:85]
	s_setprio 0
	s_setprio 1
	v_mfma_f32_16x16x32_bf16 v[110:113], v[166:169], v[182:185], 0
	v_mfma_f32_16x16x32_bf16 v[106:109], v[174:177], v[182:185], 0
	v_mfma_f32_16x16x32_bf16 v[94:97], v[166:169], v[190:193], 0
	v_mfma_f32_16x16x32_bf16 v[90:93], v[174:177], v[190:193], 0
	v_mfma_f32_16x16x32_bf16 v[78:81], v[166:169], v[210:213], 0
	v_mfma_f32_16x16x32_bf16 v[74:77], v[174:177], v[210:213], 0
	v_mfma_f32_16x16x32_bf16 v[70:73], v[166:169], v[218:221], 0
	v_mfma_f32_16x16x32_bf16 v[66:69], v[174:177], v[218:221], 0
	v_mfma_f32_16x16x32_bf16 v[110:113], v[170:173], v[186:189], v[110:113]
	v_mfma_f32_16x16x32_bf16 v[106:109], v[178:181], v[186:189], v[106:109]
	v_mfma_f32_16x16x32_bf16 v[94:97], v[170:173], v[198:201], v[94:97]
	v_mfma_f32_16x16x32_bf16 v[90:93], v[178:181], v[198:201], v[90:93]
	v_mfma_f32_16x16x32_bf16 v[78:81], v[170:173], v[214:217], v[78:81]
	v_mfma_f32_16x16x32_bf16 v[74:77], v[178:181], v[214:217], v[74:77]
	v_mfma_f32_16x16x32_bf16 v[70:73], v[170:173], v[222:225], v[70:73]
	v_mfma_f32_16x16x32_bf16 v[66:69], v[178:181], v[222:225], v[66:69]
	s_setprio 0
	s_barrier
	s_add_i32 s51, s43, s35
	v_lshl_add_u64 v[202:203], s[28:29], 0, v[132:133]
	s_mov_b32 m0, s51
	ds_read_b128 v[182:185], v149 offset:16384
	ds_read_b128 v[186:189], v149 offset:17408
	ds_read_b128 v[190:193], v149 offset:18432
	ds_read_b128 v[198:201], v149 offset:19456
	ds_read_b128 v[210:213], v149 offset:20480
	ds_read_b128 v[214:217], v149 offset:21504
	ds_read_b128 v[218:221], v149 offset:22528
	ds_read_b128 v[222:225], v149 offset:23552
	global_load_lds_dwordx4 v[202:203], off
	s_add_i32 m0, s51, 0x2000
	s_add_u32 s52, s28, 0x20000
	v_lshl_add_u64 v[206:207], s[28:29], 0, v[134:135]
	s_addc_u32 s53, s29, 0
	s_add_i32 s51, s44, s35
	global_load_lds_dwordx4 v[206:207], off
	v_lshl_add_u64 v[226:227], s[52:53], 0, v[132:133]
	s_mov_b32 m0, s51
	v_lshl_add_u64 v[228:229], s[30:31], 0, v[136:137]
	global_load_lds_dwordx4 v[226:227], off
	v_lshl_add_u64 v[226:227], s[52:53], 0, v[134:135]
	s_add_i32 m0, s51, 0x2000
	s_nop 0
	global_load_lds_dwordx4 v[226:227], off
	v_lshl_add_u64 v[226:227], s[30:31], 0, v[130:131]
	s_mov_b32 m0, s36
	s_nop 0
	global_load_lds_dwordx4 v[226:227], off
	s_mov_b32 m0, s37
	s_nop 0
	global_load_lds_dwordx4 v[228:229], off
	s_waitcnt vmcnt(8)
	s_waitcnt lgkmcnt(0)
	s_barrier
	s_setprio 1
	s_waitcnt lgkmcnt(0)
	v_mfma_f32_16x16x32_bf16 v[62:65], v[150:153], v[182:185], 0
	v_mfma_f32_16x16x32_bf16 v[58:61], v[158:161], v[182:185], 0
	v_mfma_f32_16x16x32_bf16 v[54:57], v[150:153], v[190:193], 0
	v_mfma_f32_16x16x32_bf16 v[50:53], v[158:161], v[190:193], 0
	v_mfma_f32_16x16x32_bf16 v[38:41], v[150:153], v[210:213], 0
	v_mfma_f32_16x16x32_bf16 v[34:37], v[158:161], v[210:213], 0
	v_mfma_f32_16x16x32_bf16 v[22:25], v[150:153], v[218:221], 0
	v_mfma_f32_16x16x32_bf16 v[18:21], v[158:161], v[218:221], 0
	v_mfma_f32_16x16x32_bf16 v[62:65], v[154:157], v[186:189], v[62:65]
	v_mfma_f32_16x16x32_bf16 v[58:61], v[162:165], v[186:189], v[58:61]
	v_mfma_f32_16x16x32_bf16 v[54:57], v[154:157], v[198:201], v[54:57]
	v_mfma_f32_16x16x32_bf16 v[50:53], v[162:165], v[198:201], v[50:53]
	v_mfma_f32_16x16x32_bf16 v[38:41], v[154:157], v[214:217], v[38:41]
	v_mfma_f32_16x16x32_bf16 v[34:37], v[162:165], v[214:217], v[34:37]
	v_mfma_f32_16x16x32_bf16 v[22:25], v[154:157], v[222:225], v[22:25]
	v_mfma_f32_16x16x32_bf16 v[18:21], v[162:165], v[222:225], v[18:21]
	s_setprio 0
	s_setprio 1
	v_mfma_f32_16x16x32_bf16 v[46:49], v[166:169], v[182:185], 0
	v_mfma_f32_16x16x32_bf16 v[42:45], v[174:177], v[182:185], 0
	v_mfma_f32_16x16x32_bf16 v[30:33], v[166:169], v[190:193], 0
	v_mfma_f32_16x16x32_bf16 v[26:29], v[174:177], v[190:193], 0
	v_mfma_f32_16x16x32_bf16 v[14:17], v[166:169], v[210:213], 0
	v_mfma_f32_16x16x32_bf16 v[10:13], v[174:177], v[210:213], 0
	v_mfma_f32_16x16x32_bf16 v[6:9], v[166:169], v[218:221], 0
	v_mfma_f32_16x16x32_bf16 v[2:5], v[174:177], v[218:221], 0
	v_mfma_f32_16x16x32_bf16 v[46:49], v[170:173], v[186:189], v[46:49]
	v_mfma_f32_16x16x32_bf16 v[42:45], v[178:181], v[186:189], v[42:45]
	v_mfma_f32_16x16x32_bf16 v[30:33], v[170:173], v[198:201], v[30:33]
	v_mfma_f32_16x16x32_bf16 v[26:29], v[178:181], v[198:201], v[26:29]
	v_mfma_f32_16x16x32_bf16 v[14:17], v[170:173], v[214:217], v[14:17]
	v_mfma_f32_16x16x32_bf16 v[10:13], v[178:181], v[214:217], v[10:13]
	v_mfma_f32_16x16x32_bf16 v[6:9], v[170:173], v[222:225], v[6:9]
	v_mfma_f32_16x16x32_bf16 v[2:5], v[178:181], v[222:225], v[2:5]
	s_setprio 0
	s_barrier
	s_add_i32 s51, 0, 0x18000
	s_add_i32 s52, 0, 0x1c000
	v_add_u32_e32 v162, s51, v145
	v_add_u32_e32 v178, s52, v145
	ds_read_b128 v[150:153], v162
	ds_read_b128 v[154:157], v162 offset:1024
	ds_read_b128 v[158:161], v162 offset:2048
	ds_read_b128 v[162:165], v162 offset:3072
	ds_read_b128 v[166:169], v178
	ds_read_b128 v[170:173], v178 offset:1024
	ds_read_b128 v[174:177], v178 offset:2048
	ds_read_b128 v[178:181], v178 offset:3072
	s_add_u32 s30, s30, 0x20000
	s_addc_u32 s31, s31, 0
	s_mov_b32 m0, s38
	v_lshl_add_u64 v[230:231], s[30:31], 0, v[130:131]
	ds_read_b128 v[182:185], v149 offset:32768
	ds_read_b128 v[186:189], v149 offset:33792
	ds_read_b128 v[190:193], v149 offset:34816
	ds_read_b128 v[198:201], v149 offset:35840
	ds_read_b128 v[210:213], v149 offset:36864
	ds_read_b128 v[214:217], v149 offset:37888
	ds_read_b128 v[218:221], v149 offset:38912
	ds_read_b128 v[222:225], v149 offset:39936
	global_load_lds_dwordx4 v[230:231], off
	v_lshl_add_u64 v[230:231], s[30:31], 0, v[136:137]
	s_mov_b32 m0, s39
	s_nop 0
	global_load_lds_dwordx4 v[230:231], off
	s_waitcnt vmcnt(8)
	s_waitcnt lgkmcnt(0)
	s_barrier
	s_setprio 1
	s_waitcnt lgkmcnt(0)
	v_mfma_f32_16x16x32_bf16 v[126:129], v[150:153], v[182:185], v[126:129]
	v_mfma_f32_16x16x32_bf16 v[122:125], v[158:161], v[182:185], v[122:125]
	v_mfma_f32_16x16x32_bf16 v[118:121], v[150:153], v[190:193], v[118:121]
	v_mfma_f32_16x16x32_bf16 v[114:117], v[158:161], v[190:193], v[114:117]
	v_mfma_f32_16x16x32_bf16 v[102:105], v[150:153], v[210:213], v[102:105]
	v_mfma_f32_16x16x32_bf16 v[98:101], v[158:161], v[210:213], v[98:101]
	v_mfma_f32_16x16x32_bf16 v[86:89], v[150:153], v[218:221], v[86:89]
	v_mfma_f32_16x16x32_bf16 v[82:85], v[158:161], v[218:221], v[82:85]
	v_mfma_f32_16x16x32_bf16 v[126:129], v[154:157], v[186:189], v[126:129]
	v_mfma_f32_16x16x32_bf16 v[122:125], v[162:165], v[186:189], v[122:125]
	v_mfma_f32_16x16x32_bf16 v[118:121], v[154:157], v[198:201], v[118:121]
	v_mfma_f32_16x16x32_bf16 v[114:117], v[162:165], v[198:201], v[114:117]
	v_mfma_f32_16x16x32_bf16 v[102:105], v[154:157], v[214:217], v[102:105]
	v_mfma_f32_16x16x32_bf16 v[98:101], v[162:165], v[214:217], v[98:101]
	v_mfma_f32_16x16x32_bf16 v[86:89], v[154:157], v[222:225], v[86:89]
	v_mfma_f32_16x16x32_bf16 v[82:85], v[162:165], v[222:225], v[82:85]
	s_setprio 0
	s_setprio 1
	v_mfma_f32_16x16x32_bf16 v[110:113], v[166:169], v[182:185], v[110:113]
	v_mfma_f32_16x16x32_bf16 v[106:109], v[174:177], v[182:185], v[106:109]
	v_mfma_f32_16x16x32_bf16 v[94:97], v[166:169], v[190:193], v[94:97]
	v_mfma_f32_16x16x32_bf16 v[90:93], v[174:177], v[190:193], v[90:93]
	v_mfma_f32_16x16x32_bf16 v[78:81], v[166:169], v[210:213], v[78:81]
	v_mfma_f32_16x16x32_bf16 v[74:77], v[174:177], v[210:213], v[74:77]
	v_mfma_f32_16x16x32_bf16 v[70:73], v[166:169], v[218:221], v[70:73]
	v_mfma_f32_16x16x32_bf16 v[66:69], v[174:177], v[218:221], v[66:69]
	v_mfma_f32_16x16x32_bf16 v[110:113], v[170:173], v[186:189], v[110:113]
	v_mfma_f32_16x16x32_bf16 v[106:109], v[178:181], v[186:189], v[106:109]
	v_mfma_f32_16x16x32_bf16 v[94:97], v[170:173], v[198:201], v[94:97]
	v_mfma_f32_16x16x32_bf16 v[90:93], v[178:181], v[198:201], v[90:93]
	v_mfma_f32_16x16x32_bf16 v[78:81], v[170:173], v[214:217], v[78:81]
	v_mfma_f32_16x16x32_bf16 v[74:77], v[178:181], v[214:217], v[74:77]
	v_mfma_f32_16x16x32_bf16 v[70:73], v[170:173], v[222:225], v[70:73]
	v_mfma_f32_16x16x32_bf16 v[66:69], v[178:181], v[222:225], v[66:69]
	s_setprio 0
	s_barrier
	s_add_i32 s30, s51, s35
	v_lshl_add_u64 v[202:203], v[202:203], 0, s[8:9]
	s_mov_b32 m0, s30
	ds_read_b128 v[182:185], v149 offset:49152
	ds_read_b128 v[186:189], v149 offset:50176
	ds_read_b128 v[190:193], v149 offset:51200
	ds_read_b128 v[198:201], v149 offset:52224
	ds_read_b128 v[210:213], v149 offset:53248
	ds_read_b128 v[214:217], v149 offset:54272
	ds_read_b128 v[218:221], v149 offset:55296
	ds_read_b128 v[222:225], v149 offset:56320
	global_load_lds_dwordx4 v[202:203], off
	s_add_i32 m0, s30, 0x2000
	s_add_u32 s28, s28, 0x20080
	v_lshl_add_u64 v[202:203], v[206:207], 0, s[8:9]
	s_addc_u32 s29, s29, 0
	s_add_i32 s30, s52, s35
	global_load_lds_dwordx4 v[202:203], off
	v_lshl_add_u64 v[202:203], s[28:29], 0, v[132:133]
	s_mov_b32 m0, s30
	s_nop 0
	global_load_lds_dwordx4 v[202:203], off
	v_lshl_add_u64 v[202:203], s[28:29], 0, v[134:135]
	s_add_i32 m0, s30, 0x2000
	s_nop 0
	global_load_lds_dwordx4 v[202:203], off
	v_lshl_add_u64 v[202:203], v[226:227], 0, s[8:9]
	s_mov_b32 m0, s41
	s_nop 0
	global_load_lds_dwordx4 v[202:203], off
	v_lshl_add_u64 v[202:203], v[228:229], 0, s[8:9]
	s_mov_b32 m0, s42
	s_nop 0
	global_load_lds_dwordx4 v[202:203], off
	s_waitcnt vmcnt(8)
	s_waitcnt lgkmcnt(0)
	s_barrier
	s_setprio 1
	s_waitcnt lgkmcnt(0)
	v_mfma_f32_16x16x32_bf16 v[62:65], v[150:153], v[182:185], v[62:65]
	v_mfma_f32_16x16x32_bf16 v[58:61], v[158:161], v[182:185], v[58:61]
	v_mfma_f32_16x16x32_bf16 v[54:57], v[150:153], v[190:193], v[54:57]
	v_mfma_f32_16x16x32_bf16 v[50:53], v[158:161], v[190:193], v[50:53]
	v_mfma_f32_16x16x32_bf16 v[38:41], v[150:153], v[210:213], v[38:41]
	v_mfma_f32_16x16x32_bf16 v[34:37], v[158:161], v[210:213], v[34:37]
	v_mfma_f32_16x16x32_bf16 v[22:25], v[150:153], v[218:221], v[22:25]
	v_mfma_f32_16x16x32_bf16 v[18:21], v[158:161], v[218:221], v[18:21]
	v_mfma_f32_16x16x32_bf16 v[62:65], v[154:157], v[186:189], v[62:65]
	v_mfma_f32_16x16x32_bf16 v[58:61], v[162:165], v[186:189], v[58:61]
	v_mfma_f32_16x16x32_bf16 v[54:57], v[154:157], v[198:201], v[54:57]
	v_mfma_f32_16x16x32_bf16 v[50:53], v[162:165], v[198:201], v[50:53]
	v_mfma_f32_16x16x32_bf16 v[38:41], v[154:157], v[214:217], v[38:41]
	v_mfma_f32_16x16x32_bf16 v[34:37], v[162:165], v[214:217], v[34:37]
	v_mfma_f32_16x16x32_bf16 v[22:25], v[154:157], v[222:225], v[22:25]
	v_mfma_f32_16x16x32_bf16 v[18:21], v[162:165], v[222:225], v[18:21]
	s_setprio 0
	s_setprio 1
	v_mfma_f32_16x16x32_bf16 v[46:49], v[166:169], v[182:185], v[46:49]
	v_mfma_f32_16x16x32_bf16 v[42:45], v[174:177], v[182:185], v[42:45]
	v_mfma_f32_16x16x32_bf16 v[30:33], v[166:169], v[190:193], v[30:33]
	v_mfma_f32_16x16x32_bf16 v[26:29], v[174:177], v[190:193], v[26:29]
	v_mfma_f32_16x16x32_bf16 v[14:17], v[166:169], v[210:213], v[14:17]
	v_mfma_f32_16x16x32_bf16 v[10:13], v[174:177], v[210:213], v[10:13]
	v_mfma_f32_16x16x32_bf16 v[6:9], v[166:169], v[218:221], v[6:9]
	v_mfma_f32_16x16x32_bf16 v[2:5], v[174:177], v[218:221], v[2:5]
	v_mfma_f32_16x16x32_bf16 v[46:49], v[170:173], v[186:189], v[46:49]
	v_mfma_f32_16x16x32_bf16 v[42:45], v[178:181], v[186:189], v[42:45]
	v_mfma_f32_16x16x32_bf16 v[30:33], v[170:173], v[198:201], v[30:33]
	v_mfma_f32_16x16x32_bf16 v[26:29], v[178:181], v[198:201], v[26:29]
	v_mfma_f32_16x16x32_bf16 v[14:17], v[170:173], v[214:217], v[14:17]
	v_mfma_f32_16x16x32_bf16 v[10:13], v[178:181], v[214:217], v[10:13]
	v_mfma_f32_16x16x32_bf16 v[6:9], v[170:173], v[222:225], v[6:9]
	v_mfma_f32_16x16x32_bf16 v[2:5], v[178:181], v[222:225], v[2:5]
	s_setprio 0
	s_barrier
	s_add_i32 s50, s50, 2
	s_add_u32 s26, s26, 0x100
	s_addc_u32 s27, s27, 0
	s_add_u32 s48, s48, 0x100
	s_addc_u32 s49, s49, 0
	s_cmp_gt_u32 s50, 5
	s_cbranch_scc0 .LBB0_690
	s_branch .Lpeeldone_10

.Lpeeldone_10:
	s_and_b64 vcc, exec, s[10:11]
	s_cbranch_vccz .LBB0_693
	s_barrier

.Lpeel_9:
	ds_read_b128 v[144:147], v140
	ds_read_b128 v[148:151], v140 offset:1024
	ds_read_b128 v[152:155], v140 offset:2048
	ds_read_b128 v[156:159], v140 offset:3072
	ds_read_b128 v[160:163], v141
	ds_read_b128 v[164:167], v141 offset:1024
	ds_read_b128 v[168:171], v141 offset:2048
	ds_read_b128 v[172:175], v141 offset:3072
	s_add_u32 s36, s34, 0xfffe0080
	s_addc_u32 s37, s35, -1
	s_cmp_eq_u32 s59, 4
	s_cselect_b32 s39, s21, s37
	s_cselect_b32 s38, s55, s36
	s_cselect_b32 s37, s25, s58
	s_cselect_b32 s36, s56, s57
	v_lshl_add_u64 v[192:193], s[34:35], 0, v[130:131]
	s_add_i32 m0, s27, 0xc000
	ds_read_b128 v[176:179], v142
	ds_read_b128 v[180:183], v142 offset:1024
	ds_read_b128 v[184:187], v142 offset:2048
	ds_read_b128 v[188:191], v142 offset:3072
	ds_read_b128 v[198:201], v142 offset:4096
	ds_read_b128 v[210:213], v142 offset:5120
	ds_read_b128 v[214:217], v142 offset:6144
	ds_read_b128 v[218:221], v142 offset:7168
	global_load_lds_dwordx4 v[192:193], off
	v_lshl_add_u64 v[192:193], s[34:35], 0, v[136:137]
	s_add_i32 m0, s27, 0xe000
	s_nop 0
	global_load_lds_dwordx4 v[192:193], off
	s_waitcnt vmcnt(8)
	s_waitcnt lgkmcnt(0)
	s_barrier
	s_setprio 1
	s_waitcnt lgkmcnt(0)
	v_mfma_f32_16x16x32_bf16 v[126:129], v[144:147], v[176:179], 0
	v_mfma_f32_16x16x32_bf16 v[122:125], v[152:155], v[176:179], 0
	v_mfma_f32_16x16x32_bf16 v[118:121], v[144:147], v[184:187], 0
	v_mfma_f32_16x16x32_bf16 v[114:117], v[152:155], v[184:187], 0
	v_mfma_f32_16x16x32_bf16 v[102:105], v[144:147], v[198:201], 0
	v_mfma_f32_16x16x32_bf16 v[98:101], v[152:155], v[198:201], 0
	v_mfma_f32_16x16x32_bf16 v[86:89], v[144:147], v[214:217], 0
	v_mfma_f32_16x16x32_bf16 v[82:85], v[152:155], v[214:217], 0
	v_mfma_f32_16x16x32_bf16 v[126:129], v[148:151], v[180:183], v[126:129]
	v_mfma_f32_16x16x32_bf16 v[122:125], v[156:159], v[180:183], v[122:125]
	v_mfma_f32_16x16x32_bf16 v[118:121], v[148:151], v[188:191], v[118:121]
	v_mfma_f32_16x16x32_bf16 v[114:117], v[156:159], v[188:191], v[114:117]
	v_mfma_f32_16x16x32_bf16 v[102:105], v[148:151], v[210:213], v[102:105]
	v_mfma_f32_16x16x32_bf16 v[98:101], v[156:159], v[210:213], v[98:101]
	v_mfma_f32_16x16x32_bf16 v[86:89], v[148:151], v[218:221], v[86:89]
	v_mfma_f32_16x16x32_bf16 v[82:85], v[156:159], v[218:221], v[82:85]
	s_setprio 0
	s_setprio 1
	v_mfma_f32_16x16x32_bf16 v[110:113], v[160:163], v[176:179], 0
	v_mfma_f32_16x16x32_bf16 v[106:109], v[168:171], v[176:179], 0
	v_mfma_f32_16x16x32_bf16 v[94:97], v[160:163], v[184:187], 0
	v_mfma_f32_16x16x32_bf16 v[90:93], v[168:171], v[184:187], 0
	v_mfma_f32_16x16x32_bf16 v[78:81], v[160:163], v[198:201], 0
	v_mfma_f32_16x16x32_bf16 v[74:77], v[168:171], v[198:201], 0
	v_mfma_f32_16x16x32_bf16 v[70:73], v[160:163], v[214:217], 0
	v_mfma_f32_16x16x32_bf16 v[66:69], v[168:171], v[214:217], 0
	v_mfma_f32_16x16x32_bf16 v[110:113], v[164:167], v[180:183], v[110:113]
	v_mfma_f32_16x16x32_bf16 v[106:109], v[172:175], v[180:183], v[106:109]
	v_mfma_f32_16x16x32_bf16 v[94:97], v[164:167], v[188:191], v[94:97]
	v_mfma_f32_16x16x32_bf16 v[90:93], v[172:175], v[188:191], v[90:93]
	v_mfma_f32_16x16x32_bf16 v[78:81], v[164:167], v[210:213], v[78:81]
	v_mfma_f32_16x16x32_bf16 v[74:77], v[172:175], v[210:213], v[74:77]
	v_mfma_f32_16x16x32_bf16 v[70:73], v[164:167], v[218:221], v[70:73]
	v_mfma_f32_16x16x32_bf16 v[66:69], v[172:175], v[218:221], v[66:69]
	s_setprio 0
	s_barrier
	s_add_i32 s60, s48, s41
	v_lshl_add_u64 v[192:193], s[36:37], 0, v[132:133]
	s_mov_b32 m0, s60
	ds_read_b128 v[176:179], v142 offset:16384
	ds_read_b128 v[180:183], v142 offset:17408
	ds_read_b128 v[184:187], v142 offset:18432
	ds_read_b128 v[188:191], v142 offset:19456
	ds_read_b128 v[198:201], v142 offset:20480
	ds_read_b128 v[210:213], v142 offset:21504
	ds_read_b128 v[214:217], v142 offset:22528
	ds_read_b128 v[218:221], v142 offset:23552
	global_load_lds_dwordx4 v[192:193], off
	s_add_i32 m0, s60, 0x2000
	s_add_u32 s60, s36, 0x20000
	v_lshl_add_u64 v[202:203], s[36:37], 0, v[134:135]
	s_addc_u32 s61, s37, 0
	s_add_i32 s62, s49, s41
	global_load_lds_dwordx4 v[202:203], off
	v_lshl_add_u64 v[206:207], s[60:61], 0, v[132:133]
	s_mov_b32 m0, s62
	v_lshl_add_u64 v[222:223], s[38:39], 0, v[136:137]
	global_load_lds_dwordx4 v[206:207], off
	v_lshl_add_u64 v[206:207], s[60:61], 0, v[134:135]
	s_add_i32 m0, s62, 0x2000
	s_nop 0
	global_load_lds_dwordx4 v[206:207], off
	v_lshl_add_u64 v[206:207], s[38:39], 0, v[130:131]
	s_mov_b32 m0, s27
	s_nop 0
	global_load_lds_dwordx4 v[206:207], off
	s_mov_b32 m0, s42
	s_nop 0
	global_load_lds_dwordx4 v[222:223], off
	s_waitcnt vmcnt(8)
	s_waitcnt lgkmcnt(0)
	s_barrier
	s_setprio 1
	s_waitcnt lgkmcnt(0)
	v_mfma_f32_16x16x32_bf16 v[62:65], v[144:147], v[176:179], 0
	v_mfma_f32_16x16x32_bf16 v[58:61], v[152:155], v[176:179], 0
	v_mfma_f32_16x16x32_bf16 v[54:57], v[144:147], v[184:187], 0
	v_mfma_f32_16x16x32_bf16 v[50:53], v[152:155], v[184:187], 0
	v_mfma_f32_16x16x32_bf16 v[38:41], v[144:147], v[198:201], 0
	v_mfma_f32_16x16x32_bf16 v[34:37], v[152:155], v[198:201], 0
	v_mfma_f32_16x16x32_bf16 v[22:25], v[144:147], v[214:217], 0
	v_mfma_f32_16x16x32_bf16 v[18:21], v[152:155], v[214:217], 0
	v_mfma_f32_16x16x32_bf16 v[62:65], v[148:151], v[180:183], v[62:65]
	v_mfma_f32_16x16x32_bf16 v[58:61], v[156:159], v[180:183], v[58:61]
	v_mfma_f32_16x16x32_bf16 v[54:57], v[148:151], v[188:191], v[54:57]
	v_mfma_f32_16x16x32_bf16 v[50:53], v[156:159], v[188:191], v[50:53]
	v_mfma_f32_16x16x32_bf16 v[38:41], v[148:151], v[210:213], v[38:41]
	v_mfma_f32_16x16x32_bf16 v[34:37], v[156:159], v[210:213], v[34:37]
	v_mfma_f32_16x16x32_bf16 v[22:25], v[148:151], v[218:221], v[22:25]
	v_mfma_f32_16x16x32_bf16 v[18:21], v[156:159], v[218:221], v[18:21]
	s_setprio 0
	s_setprio 1
	v_mfma_f32_16x16x32_bf16 v[46:49], v[160:163], v[176:179], 0
	v_mfma_f32_16x16x32_bf16 v[42:45], v[168:171], v[176:179], 0
	v_mfma_f32_16x16x32_bf16 v[30:33], v[160:163], v[184:187], 0
	v_mfma_f32_16x16x32_bf16 v[26:29], v[168:171], v[184:187], 0
	v_mfma_f32_16x16x32_bf16 v[14:17], v[160:163], v[198:201], 0
	v_mfma_f32_16x16x32_bf16 v[10:13], v[168:171], v[198:201], 0
	v_mfma_f32_16x16x32_bf16 v[6:9], v[160:163], v[214:217], 0
	v_mfma_f32_16x16x32_bf16 v[2:5], v[168:171], v[214:217], 0
	v_mfma_f32_16x16x32_bf16 v[46:49], v[164:167], v[180:183], v[46:49]
	v_mfma_f32_16x16x32_bf16 v[42:45], v[172:175], v[180:183], v[42:45]
	v_mfma_f32_16x16x32_bf16 v[30:33], v[164:167], v[188:191], v[30:33]
	v_mfma_f32_16x16x32_bf16 v[26:29], v[172:175], v[188:191], v[26:29]
	v_mfma_f32_16x16x32_bf16 v[14:17], v[164:167], v[210:213], v[14:17]
	v_mfma_f32_16x16x32_bf16 v[10:13], v[172:175], v[210:213], v[10:13]
	v_mfma_f32_16x16x32_bf16 v[6:9], v[164:167], v[218:221], v[6:9]
	v_mfma_f32_16x16x32_bf16 v[2:5], v[172:175], v[218:221], v[2:5]
	s_setprio 0
	s_barrier
	s_add_i32 s60, 0, 0x18000
	v_add_u32_e32 v143, s60, v139
	s_add_i32 s61, 0, 0x1c000
	ds_read_b128 v[144:147], v143
	ds_read_b128 v[148:151], v143 offset:1024
	ds_read_b128 v[152:155], v143 offset:2048
	ds_read_b128 v[156:159], v143 offset:3072
	v_add_u32_e32 v143, s61, v139
	ds_read_b128 v[160:163], v143
	ds_read_b128 v[164:167], v143 offset:1024
	ds_read_b128 v[168:171], v143 offset:2048
	ds_read_b128 v[172:175], v143 offset:3072
	s_add_u32 s38, s38, 0x20000
	s_addc_u32 s39, s39, 0
	s_mov_b32 m0, s43
	v_lshl_add_u64 v[224:225], s[38:39], 0, v[130:131]
	ds_read_b128 v[176:179], v142 offset:32768
	ds_read_b128 v[180:183], v142 offset:33792
	ds_read_b128 v[184:187], v142 offset:34816
	ds_read_b128 v[188:191], v142 offset:35840
	ds_read_b128 v[198:201], v142 offset:36864
	ds_read_b128 v[210:213], v142 offset:37888
	ds_read_b128 v[214:217], v142 offset:38912
	ds_read_b128 v[218:221], v142 offset:39936
	global_load_lds_dwordx4 v[224:225], off
	v_lshl_add_u64 v[224:225], s[38:39], 0, v[136:137]
	s_mov_b32 m0, s44
	s_nop 0
	global_load_lds_dwordx4 v[224:225], off
	s_waitcnt vmcnt(8)
	s_waitcnt lgkmcnt(0)
	s_barrier
	s_setprio 1
	s_waitcnt lgkmcnt(0)
	v_mfma_f32_16x16x32_bf16 v[126:129], v[144:147], v[176:179], v[126:129]
	v_mfma_f32_16x16x32_bf16 v[122:125], v[152:155], v[176:179], v[122:125]
	v_mfma_f32_16x16x32_bf16 v[118:121], v[144:147], v[184:187], v[118:121]
	v_mfma_f32_16x16x32_bf16 v[114:117], v[152:155], v[184:187], v[114:117]
	v_mfma_f32_16x16x32_bf16 v[102:105], v[144:147], v[198:201], v[102:105]
	v_mfma_f32_16x16x32_bf16 v[98:101], v[152:155], v[198:201], v[98:101]
	v_mfma_f32_16x16x32_bf16 v[86:89], v[144:147], v[214:217], v[86:89]
	v_mfma_f32_16x16x32_bf16 v[82:85], v[152:155], v[214:217], v[82:85]
	v_mfma_f32_16x16x32_bf16 v[126:129], v[148:151], v[180:183], v[126:129]
	v_mfma_f32_16x16x32_bf16 v[122:125], v[156:159], v[180:183], v[122:125]
	v_mfma_f32_16x16x32_bf16 v[118:121], v[148:151], v[188:191], v[118:121]
	v_mfma_f32_16x16x32_bf16 v[114:117], v[156:159], v[188:191], v[114:117]
	v_mfma_f32_16x16x32_bf16 v[102:105], v[148:151], v[210:213], v[102:105]
	v_mfma_f32_16x16x32_bf16 v[98:101], v[156:159], v[210:213], v[98:101]
	v_mfma_f32_16x16x32_bf16 v[86:89], v[148:151], v[218:221], v[86:89]
	v_mfma_f32_16x16x32_bf16 v[82:85], v[156:159], v[218:221], v[82:85]
	s_setprio 0
	s_setprio 1
	v_mfma_f32_16x16x32_bf16 v[110:113], v[160:163], v[176:179], v[110:113]
	v_mfma_f32_16x16x32_bf16 v[106:109], v[168:171], v[176:179], v[106:109]
	v_mfma_f32_16x16x32_bf16 v[94:97], v[160:163], v[184:187], v[94:97]
	v_mfma_f32_16x16x32_bf16 v[90:93], v[168:171], v[184:187], v[90:93]
	v_mfma_f32_16x16x32_bf16 v[78:81], v[160:163], v[198:201], v[78:81]
	v_mfma_f32_16x16x32_bf16 v[74:77], v[168:171], v[198:201], v[74:77]
	v_mfma_f32_16x16x32_bf16 v[70:73], v[160:163], v[214:217], v[70:73]
	v_mfma_f32_16x16x32_bf16 v[66:69], v[168:171], v[214:217], v[66:69]
	v_mfma_f32_16x16x32_bf16 v[110:113], v[164:167], v[180:183], v[110:113]
	v_mfma_f32_16x16x32_bf16 v[106:109], v[172:175], v[180:183], v[106:109]
	v_mfma_f32_16x16x32_bf16 v[94:97], v[164:167], v[188:191], v[94:97]
	v_mfma_f32_16x16x32_bf16 v[90:93], v[172:175], v[188:191], v[90:93]
	v_mfma_f32_16x16x32_bf16 v[78:81], v[164:167], v[210:213], v[78:81]
	v_mfma_f32_16x16x32_bf16 v[74:77], v[172:175], v[210:213], v[74:77]
	v_mfma_f32_16x16x32_bf16 v[70:73], v[164:167], v[218:221], v[70:73]
	v_mfma_f32_16x16x32_bf16 v[66:69], v[172:175], v[218:221], v[66:69]
	s_setprio 0
	s_barrier
	s_add_i32 s38, s60, s41
	v_lshl_add_u64 v[192:193], v[192:193], 0, s[6:7]
	s_mov_b32 m0, s38
	ds_read_b128 v[176:179], v142 offset:49152
	ds_read_b128 v[180:183], v142 offset:50176
	ds_read_b128 v[184:187], v142 offset:51200
	ds_read_b128 v[188:191], v142 offset:52224
	ds_read_b128 v[198:201], v142 offset:53248
	ds_read_b128 v[210:213], v142 offset:54272
	ds_read_b128 v[214:217], v142 offset:55296
	ds_read_b128 v[218:221], v142 offset:56320
	global_load_lds_dwordx4 v[192:193], off
	s_add_i32 m0, s38, 0x2000
	s_add_u32 s36, s36, 0x20080
	v_lshl_add_u64 v[192:193], v[202:203], 0, s[6:7]
	s_addc_u32 s37, s37, 0
	s_add_i32 s38, s61, s41
	global_load_lds_dwordx4 v[192:193], off
	v_lshl_add_u64 v[192:193], s[36:37], 0, v[132:133]
	s_mov_b32 m0, s38
	s_nop 0
	global_load_lds_dwordx4 v[192:193], off
	v_lshl_add_u64 v[192:193], s[36:37], 0, v[134:135]
	s_add_i32 m0, s38, 0x2000
	s_nop 0
	global_load_lds_dwordx4 v[192:193], off
	v_lshl_add_u64 v[192:193], v[206:207], 0, s[6:7]
	s_mov_b32 m0, s46
	s_nop 0
	global_load_lds_dwordx4 v[192:193], off
	v_lshl_add_u64 v[192:193], v[222:223], 0, s[6:7]
	s_mov_b32 m0, s47
	s_nop 0
	global_load_lds_dwordx4 v[192:193], off
	s_waitcnt vmcnt(8)
	s_waitcnt lgkmcnt(0)
	s_barrier
	s_setprio 1
	s_waitcnt lgkmcnt(0)
	v_mfma_f32_16x16x32_bf16 v[62:65], v[144:147], v[176:179], v[62:65]
	v_mfma_f32_16x16x32_bf16 v[58:61], v[152:155], v[176:179], v[58:61]
	v_mfma_f32_16x16x32_bf16 v[54:57], v[144:147], v[184:187], v[54:57]
	v_mfma_f32_16x16x32_bf16 v[50:53], v[152:155], v[184:187], v[50:53]
	v_mfma_f32_16x16x32_bf16 v[38:41], v[144:147], v[198:201], v[38:41]
	v_mfma_f32_16x16x32_bf16 v[34:37], v[152:155], v[198:201], v[34:37]
	v_mfma_f32_16x16x32_bf16 v[22:25], v[144:147], v[214:217], v[22:25]
	v_mfma_f32_16x16x32_bf16 v[18:21], v[152:155], v[214:217], v[18:21]
	v_mfma_f32_16x16x32_bf16 v[62:65], v[148:151], v[180:183], v[62:65]
	v_mfma_f32_16x16x32_bf16 v[58:61], v[156:159], v[180:183], v[58:61]
	v_mfma_f32_16x16x32_bf16 v[54:57], v[148:151], v[188:191], v[54:57]
	v_mfma_f32_16x16x32_bf16 v[50:53], v[156:159], v[188:191], v[50:53]
	v_mfma_f32_16x16x32_bf16 v[38:41], v[148:151], v[210:213], v[38:41]
	v_mfma_f32_16x16x32_bf16 v[34:37], v[156:159], v[210:213], v[34:37]
	v_mfma_f32_16x16x32_bf16 v[22:25], v[148:151], v[218:221], v[22:25]
	v_mfma_f32_16x16x32_bf16 v[18:21], v[156:159], v[218:221], v[18:21]
	s_setprio 0
	s_setprio 1
	v_mfma_f32_16x16x32_bf16 v[46:49], v[160:163], v[176:179], v[46:49]
	v_mfma_f32_16x16x32_bf16 v[42:45], v[168:171], v[176:179], v[42:45]
	v_mfma_f32_16x16x32_bf16 v[30:33], v[160:163], v[184:187], v[30:33]
	v_mfma_f32_16x16x32_bf16 v[26:29], v[168:171], v[184:187], v[26:29]
	v_mfma_f32_16x16x32_bf16 v[14:17], v[160:163], v[198:201], v[14:17]
	v_mfma_f32_16x16x32_bf16 v[10:13], v[168:171], v[198:201], v[10:13]
	v_mfma_f32_16x16x32_bf16 v[6:9], v[160:163], v[214:217], v[6:9]
	v_mfma_f32_16x16x32_bf16 v[2:5], v[168:171], v[214:217], v[2:5]
	v_mfma_f32_16x16x32_bf16 v[46:49], v[164:167], v[180:183], v[46:49]
	v_mfma_f32_16x16x32_bf16 v[42:45], v[172:175], v[180:183], v[42:45]
	v_mfma_f32_16x16x32_bf16 v[30:33], v[164:167], v[188:191], v[30:33]
	v_mfma_f32_16x16x32_bf16 v[26:29], v[172:175], v[188:191], v[26:29]
	v_mfma_f32_16x16x32_bf16 v[14:17], v[164:167], v[210:213], v[14:17]
	v_mfma_f32_16x16x32_bf16 v[10:13], v[172:175], v[210:213], v[10:13]
	v_mfma_f32_16x16x32_bf16 v[6:9], v[164:167], v[218:221], v[6:9]
	v_mfma_f32_16x16x32_bf16 v[2:5], v[172:175], v[218:221], v[2:5]
	s_setprio 0
	s_barrier
	s_add_i32 s59, s59, 2
	s_add_u32 s34, s34, 0x100
	s_addc_u32 s35, s35, 0
	s_add_u32 s57, s57, 0x100
	s_addc_u32 s58, s58, 0
	s_cmp_gt_u32 s59, 5
	s_cbranch_scc0 .LBB0_714
	s_branch .Lpeeldone_9

.Lpeel_8:
	ds_read_b128 v[130:133], v170
	ds_read_b128 v[134:137], v170 offset:1024
	ds_read_b128 v[138:141], v170 offset:2048
	ds_read_b128 v[142:145], v170 offset:3072
	ds_read_b128 v[160:163], v171
	ds_read_b128 v[164:167], v171 offset:1024
	ds_read_b128 v[174:177], v171 offset:2048
	ds_read_b128 v[178:181], v171 offset:3072
	s_add_i32 s31, s21, 2
	s_add_u32 s36, s34, 0xfff80080
	s_addc_u32 s37, s35, -1
	s_cmp_eq_u32 s30, s21
	s_cselect_b32 s39, s23, s37
	s_cselect_b32 s38, s22, s36
	s_cselect_b32 s37, s25, s19
	s_cselect_b32 s36, s24, s17
	v_lshl_add_u64 v[202:203], s[34:35], 0, v[156:157]
	s_add_i32 m0, s27, 0xc000
	ds_read_b128 v[182:185], v172
	ds_read_b128 v[186:189], v172 offset:1024
	ds_read_b128 v[190:193], v172 offset:2048
	ds_read_b128 v[198:201], v172 offset:3072
	ds_read_b128 v[210:213], v172 offset:4096
	ds_read_b128 v[214:217], v172 offset:5120
	ds_read_b128 v[218:221], v172 offset:6144
	ds_read_b128 v[222:225], v172 offset:7168
	global_load_lds_dwordx4 v[202:203], off
	v_lshl_add_u64 v[202:203], s[34:35], 0, v[158:159]
	s_add_i32 m0, s27, 0xe000
	s_nop 0
	global_load_lds_dwordx4 v[202:203], off
	s_waitcnt vmcnt(8)
	s_waitcnt lgkmcnt(0)
	s_barrier
	s_setprio 1
	s_waitcnt lgkmcnt(0)
	v_mfma_f32_16x16x32_bf16 v[126:129], v[130:133], v[182:185], 0
	v_mfma_f32_16x16x32_bf16 v[122:125], v[138:141], v[182:185], 0
	v_mfma_f32_16x16x32_bf16 v[118:121], v[130:133], v[190:193], 0
	v_mfma_f32_16x16x32_bf16 v[110:113], v[138:141], v[190:193], 0
	v_mfma_f32_16x16x32_bf16 v[94:97], v[130:133], v[210:213], 0
	v_mfma_f32_16x16x32_bf16 v[90:93], v[138:141], v[210:213], 0
	v_mfma_f32_16x16x32_bf16 v[78:81], v[130:133], v[218:221], 0
	v_mfma_f32_16x16x32_bf16 v[74:77], v[138:141], v[218:221], 0
	v_mfma_f32_16x16x32_bf16 v[126:129], v[134:137], v[186:189], v[126:129]
	v_mfma_f32_16x16x32_bf16 v[122:125], v[142:145], v[186:189], v[122:125]
	v_mfma_f32_16x16x32_bf16 v[118:121], v[134:137], v[198:201], v[118:121]
	v_mfma_f32_16x16x32_bf16 v[110:113], v[142:145], v[198:201], v[110:113]
	v_mfma_f32_16x16x32_bf16 v[94:97], v[134:137], v[214:217], v[94:97]
	v_mfma_f32_16x16x32_bf16 v[90:93], v[142:145], v[214:217], v[90:93]
	v_mfma_f32_16x16x32_bf16 v[78:81], v[134:137], v[222:225], v[78:81]
	v_mfma_f32_16x16x32_bf16 v[74:77], v[142:145], v[222:225], v[74:77]
	s_setprio 0
	s_setprio 1
	v_mfma_f32_16x16x32_bf16 v[114:117], v[160:163], v[182:185], 0
	v_mfma_f32_16x16x32_bf16 v[106:109], v[174:177], v[182:185], 0
	v_mfma_f32_16x16x32_bf16 v[102:105], v[160:163], v[190:193], 0
	v_mfma_f32_16x16x32_bf16 v[98:101], v[174:177], v[190:193], 0
	v_mfma_f32_16x16x32_bf16 v[86:89], v[160:163], v[210:213], 0
	v_mfma_f32_16x16x32_bf16 v[82:85], v[174:177], v[210:213], 0
	v_mfma_f32_16x16x32_bf16 v[70:73], v[160:163], v[218:221], 0
	v_mfma_f32_16x16x32_bf16 v[66:69], v[174:177], v[218:221], 0
	v_mfma_f32_16x16x32_bf16 v[114:117], v[164:167], v[186:189], v[114:117]
	v_mfma_f32_16x16x32_bf16 v[106:109], v[178:181], v[186:189], v[106:109]
	v_mfma_f32_16x16x32_bf16 v[102:105], v[164:167], v[198:201], v[102:105]
	v_mfma_f32_16x16x32_bf16 v[98:101], v[178:181], v[198:201], v[98:101]
	v_mfma_f32_16x16x32_bf16 v[86:89], v[164:167], v[214:217], v[86:89]
	v_mfma_f32_16x16x32_bf16 v[82:85], v[178:181], v[214:217], v[82:85]
	v_mfma_f32_16x16x32_bf16 v[70:73], v[164:167], v[222:225], v[70:73]
	v_mfma_f32_16x16x32_bf16 v[66:69], v[178:181], v[222:225], v[66:69]
	s_setprio 0
	s_barrier
	s_add_i32 s21, s63, s33
	v_lshl_add_u64 v[202:203], s[36:37], 0, v[148:149]
	s_mov_b32 m0, s21
	ds_read_b128 v[182:185], v172 offset:16384
	ds_read_b128 v[186:189], v172 offset:17408
	ds_read_b128 v[190:193], v172 offset:18432
	ds_read_b128 v[198:201], v172 offset:19456
	ds_read_b128 v[210:213], v172 offset:20480
	ds_read_b128 v[214:217], v172 offset:21504
	ds_read_b128 v[218:221], v172 offset:22528
	ds_read_b128 v[222:225], v172 offset:23552
	global_load_lds_dwordx4 v[202:203], off
	s_add_i32 m0, s21, 0x2000
	s_add_u32 s40, s36, 0x80000
	v_lshl_add_u64 v[206:207], s[36:37], 0, v[152:153]
	s_addc_u32 s41, s37, 0
	s_add_i32 s21, s64, s33
	global_load_lds_dwordx4 v[206:207], off
	v_lshl_add_u64 v[226:227], s[40:41], 0, v[148:149]
	s_mov_b32 m0, s21
	v_lshl_add_u64 v[228:229], s[38:39], 0, v[150:151]
	global_load_lds_dwordx4 v[226:227], off
	v_lshl_add_u64 v[226:227], s[40:41], 0, v[152:153]
	s_add_i32 m0, s21, 0x2000
	s_nop 0
	global_load_lds_dwordx4 v[226:227], off
	v_lshl_add_u64 v[226:227], s[38:39], 0, v[146:147]
	s_mov_b32 m0, s27
	s_nop 0
	global_load_lds_dwordx4 v[226:227], off
	s_mov_b32 m0, s29
	s_nop 0
	global_load_lds_dwordx4 v[228:229], off
	s_waitcnt vmcnt(8)
	s_waitcnt lgkmcnt(0)
	s_barrier
	s_setprio 1
	s_waitcnt lgkmcnt(0)
	v_mfma_f32_16x16x32_bf16 v[62:65], v[130:133], v[182:185], 0
	v_mfma_f32_16x16x32_bf16 v[58:61], v[138:141], v[182:185], 0
	v_mfma_f32_16x16x32_bf16 v[46:49], v[130:133], v[190:193], 0
	v_mfma_f32_16x16x32_bf16 v[42:45], v[138:141], v[190:193], 0
	v_mfma_f32_16x16x32_bf16 v[30:33], v[130:133], v[210:213], 0
	v_mfma_f32_16x16x32_bf16 v[26:29], v[138:141], v[210:213], 0
	v_mfma_f32_16x16x32_bf16 v[14:17], v[130:133], v[218:221], 0
	v_mfma_f32_16x16x32_bf16 v[10:13], v[138:141], v[218:221], 0
	v_mfma_f32_16x16x32_bf16 v[62:65], v[134:137], v[186:189], v[62:65]
	v_mfma_f32_16x16x32_bf16 v[58:61], v[142:145], v[186:189], v[58:61]
	v_mfma_f32_16x16x32_bf16 v[46:49], v[134:137], v[198:201], v[46:49]
	v_mfma_f32_16x16x32_bf16 v[42:45], v[142:145], v[198:201], v[42:45]
	v_mfma_f32_16x16x32_bf16 v[30:33], v[134:137], v[214:217], v[30:33]
	v_mfma_f32_16x16x32_bf16 v[26:29], v[142:145], v[214:217], v[26:29]
	v_mfma_f32_16x16x32_bf16 v[14:17], v[134:137], v[222:225], v[14:17]
	v_mfma_f32_16x16x32_bf16 v[10:13], v[142:145], v[222:225], v[10:13]
	s_setprio 0
	s_setprio 1
	v_mfma_f32_16x16x32_bf16 v[54:57], v[160:163], v[182:185], 0
	v_mfma_f32_16x16x32_bf16 v[50:53], v[174:177], v[182:185], 0
	v_mfma_f32_16x16x32_bf16 v[38:41], v[160:163], v[190:193], 0
	v_mfma_f32_16x16x32_bf16 v[34:37], v[174:177], v[190:193], 0
	v_mfma_f32_16x16x32_bf16 v[22:25], v[160:163], v[210:213], 0
	v_mfma_f32_16x16x32_bf16 v[18:21], v[174:177], v[210:213], 0
	v_mfma_f32_16x16x32_bf16 v[6:9], v[160:163], v[218:221], 0
	v_mfma_f32_16x16x32_bf16 v[2:5], v[174:177], v[218:221], 0
	v_mfma_f32_16x16x32_bf16 v[54:57], v[164:167], v[186:189], v[54:57]
	v_mfma_f32_16x16x32_bf16 v[50:53], v[178:181], v[186:189], v[50:53]
	v_mfma_f32_16x16x32_bf16 v[38:41], v[164:167], v[198:201], v[38:41]
	v_mfma_f32_16x16x32_bf16 v[34:37], v[178:181], v[198:201], v[34:37]
	v_mfma_f32_16x16x32_bf16 v[22:25], v[164:167], v[214:217], v[22:25]
	v_mfma_f32_16x16x32_bf16 v[18:21], v[178:181], v[214:217], v[18:21]
	v_mfma_f32_16x16x32_bf16 v[6:9], v[164:167], v[222:225], v[6:9]
	v_mfma_f32_16x16x32_bf16 v[2:5], v[178:181], v[222:225], v[2:5]
	s_setprio 0
	s_barrier
	s_add_i32 s21, 0, 0x18000
	s_add_i32 s40, 0, 0x1c000
	v_add_u32_e32 v142, s21, v168
	v_add_u32_e32 v173, s40, v168
	ds_read_b128 v[130:133], v142
	ds_read_b128 v[134:137], v142 offset:1024
	ds_read_b128 v[138:141], v142 offset:2048
	ds_read_b128 v[142:145], v142 offset:3072
	ds_read_b128 v[160:163], v173
	ds_read_b128 v[164:167], v173 offset:1024
	ds_read_b128 v[174:177], v173 offset:2048
	ds_read_b128 v[178:181], v173 offset:3072
	s_add_u32 s38, s38, 0x80000
	s_addc_u32 s39, s39, 0
	s_mov_b32 m0, s42
	v_lshl_add_u64 v[230:231], s[38:39], 0, v[146:147]
	ds_read_b128 v[182:185], v172 offset:32768
	ds_read_b128 v[186:189], v172 offset:33792
	ds_read_b128 v[190:193], v172 offset:34816
	ds_read_b128 v[198:201], v172 offset:35840
	ds_read_b128 v[210:213], v172 offset:36864
	ds_read_b128 v[214:217], v172 offset:37888
	ds_read_b128 v[218:221], v172 offset:38912
	ds_read_b128 v[222:225], v172 offset:39936
	global_load_lds_dwordx4 v[230:231], off
	v_lshl_add_u64 v[230:231], s[38:39], 0, v[150:151]
	s_mov_b32 m0, s43
	s_nop 0
	global_load_lds_dwordx4 v[230:231], off
	s_waitcnt vmcnt(8)
	s_waitcnt lgkmcnt(0)
	s_barrier
	s_setprio 1
	s_waitcnt lgkmcnt(0)
	v_mfma_f32_16x16x32_bf16 v[126:129], v[130:133], v[182:185], v[126:129]
	v_mfma_f32_16x16x32_bf16 v[122:125], v[138:141], v[182:185], v[122:125]
	v_mfma_f32_16x16x32_bf16 v[118:121], v[130:133], v[190:193], v[118:121]
	v_mfma_f32_16x16x32_bf16 v[110:113], v[138:141], v[190:193], v[110:113]
	v_mfma_f32_16x16x32_bf16 v[94:97], v[130:133], v[210:213], v[94:97]
	v_mfma_f32_16x16x32_bf16 v[90:93], v[138:141], v[210:213], v[90:93]
	v_mfma_f32_16x16x32_bf16 v[78:81], v[130:133], v[218:221], v[78:81]
	v_mfma_f32_16x16x32_bf16 v[74:77], v[138:141], v[218:221], v[74:77]
	v_mfma_f32_16x16x32_bf16 v[126:129], v[134:137], v[186:189], v[126:129]
	v_mfma_f32_16x16x32_bf16 v[122:125], v[142:145], v[186:189], v[122:125]
	v_mfma_f32_16x16x32_bf16 v[118:121], v[134:137], v[198:201], v[118:121]
	v_mfma_f32_16x16x32_bf16 v[110:113], v[142:145], v[198:201], v[110:113]
	v_mfma_f32_16x16x32_bf16 v[94:97], v[134:137], v[214:217], v[94:97]
	v_mfma_f32_16x16x32_bf16 v[90:93], v[142:145], v[214:217], v[90:93]
	v_mfma_f32_16x16x32_bf16 v[78:81], v[134:137], v[222:225], v[78:81]
	v_mfma_f32_16x16x32_bf16 v[74:77], v[142:145], v[222:225], v[74:77]
	s_setprio 0
	s_setprio 1
	v_mfma_f32_16x16x32_bf16 v[114:117], v[160:163], v[182:185], v[114:117]
	v_mfma_f32_16x16x32_bf16 v[106:109], v[174:177], v[182:185], v[106:109]
	v_mfma_f32_16x16x32_bf16 v[102:105], v[160:163], v[190:193], v[102:105]
	v_mfma_f32_16x16x32_bf16 v[98:101], v[174:177], v[190:193], v[98:101]
	v_mfma_f32_16x16x32_bf16 v[86:89], v[160:163], v[210:213], v[86:89]
	v_mfma_f32_16x16x32_bf16 v[82:85], v[174:177], v[210:213], v[82:85]
	v_mfma_f32_16x16x32_bf16 v[70:73], v[160:163], v[218:221], v[70:73]
	v_mfma_f32_16x16x32_bf16 v[66:69], v[174:177], v[218:221], v[66:69]
	v_mfma_f32_16x16x32_bf16 v[114:117], v[164:167], v[186:189], v[114:117]
	v_mfma_f32_16x16x32_bf16 v[106:109], v[178:181], v[186:189], v[106:109]
	v_mfma_f32_16x16x32_bf16 v[102:105], v[164:167], v[198:201], v[102:105]
	v_mfma_f32_16x16x32_bf16 v[98:101], v[178:181], v[198:201], v[98:101]
	v_mfma_f32_16x16x32_bf16 v[86:89], v[164:167], v[214:217], v[86:89]
	v_mfma_f32_16x16x32_bf16 v[82:85], v[178:181], v[214:217], v[82:85]
	v_mfma_f32_16x16x32_bf16 v[70:73], v[164:167], v[222:225], v[70:73]
	v_mfma_f32_16x16x32_bf16 v[66:69], v[178:181], v[222:225], v[66:69]
	s_setprio 0
	s_barrier
	s_add_i32 s21, s21, s33
	v_lshl_add_u64 v[202:203], v[202:203], 0, s[12:13]
	s_mov_b32 m0, s21
	ds_read_b128 v[182:185], v172 offset:49152
	ds_read_b128 v[186:189], v172 offset:50176
	ds_read_b128 v[190:193], v172 offset:51200
	ds_read_b128 v[198:201], v172 offset:52224
	ds_read_b128 v[210:213], v172 offset:53248
	ds_read_b128 v[214:217], v172 offset:54272
	ds_read_b128 v[218:221], v172 offset:55296
	ds_read_b128 v[222:225], v172 offset:56320
	global_load_lds_dwordx4 v[202:203], off
	s_add_i32 m0, s21, 0x2000
	s_add_u32 s36, s36, 0x80080
	v_lshl_add_u64 v[202:203], v[206:207], 0, s[12:13]
	s_addc_u32 s37, s37, 0
	s_add_i32 s21, s40, s33
	global_load_lds_dwordx4 v[202:203], off
	v_lshl_add_u64 v[202:203], s[36:37], 0, v[148:149]
	s_mov_b32 m0, s21
	s_nop 0
	global_load_lds_dwordx4 v[202:203], off
	v_lshl_add_u64 v[202:203], s[36:37], 0, v[152:153]
	s_add_i32 m0, s21, 0x2000
	s_nop 0
	global_load_lds_dwordx4 v[202:203], off
	v_lshl_add_u64 v[202:203], v[226:227], 0, s[12:13]
	s_mov_b32 m0, s53
	s_nop 0
	global_load_lds_dwordx4 v[202:203], off
	v_lshl_add_u64 v[202:203], v[228:229], 0, s[12:13]
	s_mov_b32 m0, s54
	s_nop 0
	global_load_lds_dwordx4 v[202:203], off
	s_waitcnt vmcnt(8)
	s_waitcnt lgkmcnt(0)
	s_barrier
	s_setprio 1
	s_waitcnt lgkmcnt(0)
	v_mfma_f32_16x16x32_bf16 v[62:65], v[130:133], v[182:185], v[62:65]
	v_mfma_f32_16x16x32_bf16 v[58:61], v[138:141], v[182:185], v[58:61]
	v_mfma_f32_16x16x32_bf16 v[46:49], v[130:133], v[190:193], v[46:49]
	v_mfma_f32_16x16x32_bf16 v[42:45], v[138:141], v[190:193], v[42:45]
	v_mfma_f32_16x16x32_bf16 v[30:33], v[130:133], v[210:213], v[30:33]
	v_mfma_f32_16x16x32_bf16 v[26:29], v[138:141], v[210:213], v[26:29]
	v_mfma_f32_16x16x32_bf16 v[14:17], v[130:133], v[218:221], v[14:17]
	v_mfma_f32_16x16x32_bf16 v[10:13], v[138:141], v[218:221], v[10:13]
	v_mfma_f32_16x16x32_bf16 v[62:65], v[134:137], v[186:189], v[62:65]
	v_mfma_f32_16x16x32_bf16 v[58:61], v[142:145], v[186:189], v[58:61]
	v_mfma_f32_16x16x32_bf16 v[46:49], v[134:137], v[198:201], v[46:49]
	v_mfma_f32_16x16x32_bf16 v[42:45], v[142:145], v[198:201], v[42:45]
	v_mfma_f32_16x16x32_bf16 v[30:33], v[134:137], v[214:217], v[30:33]
	v_mfma_f32_16x16x32_bf16 v[26:29], v[142:145], v[214:217], v[26:29]
	v_mfma_f32_16x16x32_bf16 v[14:17], v[134:137], v[222:225], v[14:17]
	v_mfma_f32_16x16x32_bf16 v[10:13], v[142:145], v[222:225], v[10:13]
	s_setprio 0
	s_setprio 1
	v_mfma_f32_16x16x32_bf16 v[54:57], v[160:163], v[182:185], v[54:57]
	v_mfma_f32_16x16x32_bf16 v[50:53], v[174:177], v[182:185], v[50:53]
	v_mfma_f32_16x16x32_bf16 v[38:41], v[160:163], v[190:193], v[38:41]
	v_mfma_f32_16x16x32_bf16 v[34:37], v[174:177], v[190:193], v[34:37]
	v_mfma_f32_16x16x32_bf16 v[22:25], v[160:163], v[210:213], v[22:25]
	v_mfma_f32_16x16x32_bf16 v[18:21], v[174:177], v[210:213], v[18:21]
	v_mfma_f32_16x16x32_bf16 v[6:9], v[160:163], v[218:221], v[6:9]
	v_mfma_f32_16x16x32_bf16 v[2:5], v[174:177], v[218:221], v[2:5]
	v_mfma_f32_16x16x32_bf16 v[54:57], v[164:167], v[186:189], v[54:57]
	v_mfma_f32_16x16x32_bf16 v[50:53], v[178:181], v[186:189], v[50:53]
	v_mfma_f32_16x16x32_bf16 v[38:41], v[164:167], v[198:201], v[38:41]
	v_mfma_f32_16x16x32_bf16 v[34:37], v[178:181], v[198:201], v[34:37]
	v_mfma_f32_16x16x32_bf16 v[22:25], v[164:167], v[214:217], v[22:25]
	v_mfma_f32_16x16x32_bf16 v[18:21], v[178:181], v[214:217], v[18:21]
	v_mfma_f32_16x16x32_bf16 v[6:9], v[164:167], v[222:225], v[6:9]
	v_mfma_f32_16x16x32_bf16 v[2:5], v[178:181], v[222:225], v[2:5]
	s_setprio 0
	s_barrier
	s_add_u32 s34, s34, 0x100
	s_addc_u32 s35, s35, 0
	s_add_u32 s17, s17, 0x100
	s_addc_u32 s19, s19, 0
	s_cmp_ge_i32 s31, s69
	s_mov_b32 s21, s31
	s_cbranch_scc0 .LBB0_1122
	s_branch .Lpeeldone_8

.Lpeeldone_8:
	s_and_b64 vcc, exec, s[14:15]
	s_cbranch_vccnz .LBB0_1130
	s_cmp_gt_i32 s6, -1
	s_mov_b64 s[30:31], -1
	s_cbranch_scc1 .LBB0_1131

.Lpeel_7:
	ds_read_b128 v[152:155], v148
	ds_read_b128 v[156:159], v148 offset:1024
	ds_read_b128 v[160:163], v148 offset:2048
	ds_read_b128 v[164:167], v148 offset:3072
	ds_read_b128 v[168:171], v149
	ds_read_b128 v[172:175], v149 offset:1024
	ds_read_b128 v[176:179], v149 offset:2048
	ds_read_b128 v[180:183], v149 offset:3072
	s_add_i32 s29, s19, 2
	s_add_u32 s34, s30, 0xfff80080
	s_addc_u32 s35, s31, -1
	s_cmp_eq_u32 s28, s19
	s_cselect_b32 s37, s21, s35
	s_cselect_b32 s36, s20, s34
	s_cselect_b32 s35, s23, s17
	s_cselect_b32 s34, s22, s15
	v_lshl_add_u64 v[144:145], s[30:31], 0, v[140:141]
	s_add_i32 m0, s27, 0xc000
	ds_read_b128 v[184:187], v150
	ds_read_b128 v[188:191], v150 offset:1024
	ds_read_b128 v[198:201], v150 offset:2048
	ds_read_b128 v[210:213], v150 offset:3072
	ds_read_b128 v[214:217], v150 offset:4096
	ds_read_b128 v[218:221], v150 offset:5120
	ds_read_b128 v[222:225], v150 offset:6144
	ds_read_b128 v[226:229], v150 offset:7168
	global_load_lds_dwordx4 v[144:145], off
	v_lshl_add_u64 v[144:145], s[30:31], 0, v[142:143]
	s_add_i32 m0, s27, 0xe000
	s_nop 0
	global_load_lds_dwordx4 v[144:145], off
	s_waitcnt vmcnt(8)
	s_waitcnt lgkmcnt(0)
	s_barrier
	s_setprio 1
	s_waitcnt lgkmcnt(0)
	v_mfma_f32_16x16x32_bf16 v[126:129], v[152:155], v[184:187], 0
	v_mfma_f32_16x16x32_bf16 v[122:125], v[160:163], v[184:187], 0
	v_mfma_f32_16x16x32_bf16 v[110:113], v[152:155], v[198:201], 0
	v_mfma_f32_16x16x32_bf16 v[106:109], v[160:163], v[198:201], 0
	v_mfma_f32_16x16x32_bf16 v[94:97], v[152:155], v[214:217], 0
	v_mfma_f32_16x16x32_bf16 v[90:93], v[160:163], v[214:217], 0
	v_mfma_f32_16x16x32_bf16 v[78:81], v[152:155], v[222:225], 0
	v_mfma_f32_16x16x32_bf16 v[74:77], v[160:163], v[222:225], 0
	v_mfma_f32_16x16x32_bf16 v[126:129], v[156:159], v[188:191], v[126:129]
	v_mfma_f32_16x16x32_bf16 v[122:125], v[164:167], v[188:191], v[122:125]
	v_mfma_f32_16x16x32_bf16 v[110:113], v[156:159], v[210:213], v[110:113]
	v_mfma_f32_16x16x32_bf16 v[106:109], v[164:167], v[210:213], v[106:109]
	v_mfma_f32_16x16x32_bf16 v[94:97], v[156:159], v[218:221], v[94:97]
	v_mfma_f32_16x16x32_bf16 v[90:93], v[164:167], v[218:221], v[90:93]
	v_mfma_f32_16x16x32_bf16 v[78:81], v[156:159], v[226:229], v[78:81]
	v_mfma_f32_16x16x32_bf16 v[74:77], v[164:167], v[226:229], v[74:77]
	s_setprio 0
	s_setprio 1
	v_mfma_f32_16x16x32_bf16 v[118:121], v[168:171], v[184:187], 0
	v_mfma_f32_16x16x32_bf16 v[114:117], v[176:179], v[184:187], 0
	v_mfma_f32_16x16x32_bf16 v[102:105], v[168:171], v[198:201], 0
	v_mfma_f32_16x16x32_bf16 v[98:101], v[176:179], v[198:201], 0
	v_mfma_f32_16x16x32_bf16 v[86:89], v[168:171], v[214:217], 0
	v_mfma_f32_16x16x32_bf16 v[82:85], v[176:179], v[214:217], 0
	v_mfma_f32_16x16x32_bf16 v[70:73], v[168:171], v[222:225], 0
	v_mfma_f32_16x16x32_bf16 v[66:69], v[176:179], v[222:225], 0
	v_mfma_f32_16x16x32_bf16 v[118:121], v[172:175], v[188:191], v[118:121]
	v_mfma_f32_16x16x32_bf16 v[114:117], v[180:183], v[188:191], v[114:117]
	v_mfma_f32_16x16x32_bf16 v[102:105], v[172:175], v[210:213], v[102:105]
	v_mfma_f32_16x16x32_bf16 v[98:101], v[180:183], v[210:213], v[98:101]
	v_mfma_f32_16x16x32_bf16 v[86:89], v[172:175], v[218:221], v[86:89]
	v_mfma_f32_16x16x32_bf16 v[82:85], v[180:183], v[218:221], v[82:85]
	v_mfma_f32_16x16x32_bf16 v[70:73], v[172:175], v[226:229], v[70:73]
	v_mfma_f32_16x16x32_bf16 v[66:69], v[180:183], v[226:229], v[66:69]
	s_setprio 0
	s_barrier
	s_add_i32 s19, s60, s33
	v_lshl_add_u64 v[144:145], s[34:35], 0, v[132:133]
	s_mov_b32 m0, s19
	ds_read_b128 v[184:187], v150 offset:16384
	ds_read_b128 v[188:191], v150 offset:17408
	ds_read_b128 v[198:201], v150 offset:18432
	ds_read_b128 v[210:213], v150 offset:19456
	ds_read_b128 v[214:217], v150 offset:20480
	ds_read_b128 v[218:221], v150 offset:21504
	ds_read_b128 v[222:225], v150 offset:22528
	ds_read_b128 v[226:229], v150 offset:23552
	global_load_lds_dwordx4 v[144:145], off
	s_add_i32 m0, s19, 0x2000
	s_add_u32 s38, s34, 0x80000
	v_lshl_add_u64 v[192:193], s[34:35], 0, v[136:137]
	s_addc_u32 s39, s35, 0
	s_add_i32 s19, s61, s33
	global_load_lds_dwordx4 v[192:193], off
	v_lshl_add_u64 v[202:203], s[38:39], 0, v[132:133]
	s_mov_b32 m0, s19
	v_lshl_add_u64 v[206:207], s[36:37], 0, v[134:135]
	global_load_lds_dwordx4 v[202:203], off
	v_lshl_add_u64 v[202:203], s[38:39], 0, v[136:137]
	s_add_i32 m0, s19, 0x2000
	s_nop 0
	global_load_lds_dwordx4 v[202:203], off
	v_lshl_add_u64 v[202:203], s[36:37], 0, v[130:131]
	s_mov_b32 m0, s27
	s_nop 0
	global_load_lds_dwordx4 v[202:203], off
	s_mov_b32 m0, s41
	s_nop 0
	global_load_lds_dwordx4 v[206:207], off
	s_waitcnt vmcnt(8)
	s_waitcnt lgkmcnt(0)
	s_barrier
	s_setprio 1
	s_waitcnt lgkmcnt(0)
	v_mfma_f32_16x16x32_bf16 v[62:65], v[152:155], v[184:187], 0
	v_mfma_f32_16x16x32_bf16 v[58:61], v[160:163], v[184:187], 0
	v_mfma_f32_16x16x32_bf16 v[46:49], v[152:155], v[198:201], 0
	v_mfma_f32_16x16x32_bf16 v[42:45], v[160:163], v[198:201], 0
	v_mfma_f32_16x16x32_bf16 v[30:33], v[152:155], v[214:217], 0
	v_mfma_f32_16x16x32_bf16 v[26:29], v[160:163], v[214:217], 0
	v_mfma_f32_16x16x32_bf16 v[14:17], v[152:155], v[222:225], 0
	v_mfma_f32_16x16x32_bf16 v[10:13], v[160:163], v[222:225], 0
	v_mfma_f32_16x16x32_bf16 v[62:65], v[156:159], v[188:191], v[62:65]
	v_mfma_f32_16x16x32_bf16 v[58:61], v[164:167], v[188:191], v[58:61]
	v_mfma_f32_16x16x32_bf16 v[46:49], v[156:159], v[210:213], v[46:49]
	v_mfma_f32_16x16x32_bf16 v[42:45], v[164:167], v[210:213], v[42:45]
	v_mfma_f32_16x16x32_bf16 v[30:33], v[156:159], v[218:221], v[30:33]
	v_mfma_f32_16x16x32_bf16 v[26:29], v[164:167], v[218:221], v[26:29]
	v_mfma_f32_16x16x32_bf16 v[14:17], v[156:159], v[226:229], v[14:17]
	v_mfma_f32_16x16x32_bf16 v[10:13], v[164:167], v[226:229], v[10:13]
	s_setprio 0
	s_setprio 1
	v_mfma_f32_16x16x32_bf16 v[54:57], v[168:171], v[184:187], 0
	v_mfma_f32_16x16x32_bf16 v[50:53], v[176:179], v[184:187], 0
	v_mfma_f32_16x16x32_bf16 v[38:41], v[168:171], v[198:201], 0
	v_mfma_f32_16x16x32_bf16 v[34:37], v[176:179], v[198:201], 0
	v_mfma_f32_16x16x32_bf16 v[22:25], v[168:171], v[214:217], 0
	v_mfma_f32_16x16x32_bf16 v[18:21], v[176:179], v[214:217], 0
	v_mfma_f32_16x16x32_bf16 v[6:9], v[168:171], v[222:225], 0
	v_mfma_f32_16x16x32_bf16 v[2:5], v[176:179], v[222:225], 0
	v_mfma_f32_16x16x32_bf16 v[54:57], v[172:175], v[188:191], v[54:57]
	v_mfma_f32_16x16x32_bf16 v[50:53], v[180:183], v[188:191], v[50:53]
	v_mfma_f32_16x16x32_bf16 v[38:41], v[172:175], v[210:213], v[38:41]
	v_mfma_f32_16x16x32_bf16 v[34:37], v[180:183], v[210:213], v[34:37]
	v_mfma_f32_16x16x32_bf16 v[22:25], v[172:175], v[218:221], v[22:25]
	v_mfma_f32_16x16x32_bf16 v[18:21], v[180:183], v[218:221], v[18:21]
	v_mfma_f32_16x16x32_bf16 v[6:9], v[172:175], v[226:229], v[6:9]
	v_mfma_f32_16x16x32_bf16 v[2:5], v[180:183], v[226:229], v[2:5]
	s_setprio 0
	s_barrier
	s_add_i32 s19, 0, 0x18000
	v_add_u32_e32 v151, s19, v146
	s_add_i32 s38, 0, 0x1c000
	ds_read_b128 v[152:155], v151
	ds_read_b128 v[156:159], v151 offset:1024
	ds_read_b128 v[160:163], v151 offset:2048
	ds_read_b128 v[164:167], v151 offset:3072
	v_add_u32_e32 v151, s38, v146
	ds_read_b128 v[168:171], v151
	ds_read_b128 v[172:175], v151 offset:1024
	ds_read_b128 v[176:179], v151 offset:2048
	ds_read_b128 v[180:183], v151 offset:3072
	s_add_u32 s36, s36, 0x80000
	s_addc_u32 s37, s37, 0
	s_mov_b32 m0, s42
	v_lshl_add_u64 v[230:231], s[36:37], 0, v[130:131]
	ds_read_b128 v[184:187], v150 offset:32768
	ds_read_b128 v[188:191], v150 offset:33792
	ds_read_b128 v[198:201], v150 offset:34816
	ds_read_b128 v[210:213], v150 offset:35840
	ds_read_b128 v[214:217], v150 offset:36864
	ds_read_b128 v[218:221], v150 offset:37888
	ds_read_b128 v[222:225], v150 offset:38912
	ds_read_b128 v[226:229], v150 offset:39936
	global_load_lds_dwordx4 v[230:231], off
	v_lshl_add_u64 v[230:231], s[36:37], 0, v[134:135]
	s_mov_b32 m0, s43
	s_nop 0
	global_load_lds_dwordx4 v[230:231], off
	s_waitcnt vmcnt(8)
	s_waitcnt lgkmcnt(0)
	s_barrier
	s_setprio 1
	s_waitcnt lgkmcnt(0)
	v_mfma_f32_16x16x32_bf16 v[126:129], v[152:155], v[184:187], v[126:129]
	v_mfma_f32_16x16x32_bf16 v[122:125], v[160:163], v[184:187], v[122:125]
	v_mfma_f32_16x16x32_bf16 v[110:113], v[152:155], v[198:201], v[110:113]
	v_mfma_f32_16x16x32_bf16 v[106:109], v[160:163], v[198:201], v[106:109]
	v_mfma_f32_16x16x32_bf16 v[94:97], v[152:155], v[214:217], v[94:97]
	v_mfma_f32_16x16x32_bf16 v[90:93], v[160:163], v[214:217], v[90:93]
	v_mfma_f32_16x16x32_bf16 v[78:81], v[152:155], v[222:225], v[78:81]
	v_mfma_f32_16x16x32_bf16 v[74:77], v[160:163], v[222:225], v[74:77]
	v_mfma_f32_16x16x32_bf16 v[126:129], v[156:159], v[188:191], v[126:129]
	v_mfma_f32_16x16x32_bf16 v[122:125], v[164:167], v[188:191], v[122:125]
	v_mfma_f32_16x16x32_bf16 v[110:113], v[156:159], v[210:213], v[110:113]
	v_mfma_f32_16x16x32_bf16 v[106:109], v[164:167], v[210:213], v[106:109]
	v_mfma_f32_16x16x32_bf16 v[94:97], v[156:159], v[218:221], v[94:97]
	v_mfma_f32_16x16x32_bf16 v[90:93], v[164:167], v[218:221], v[90:93]
	v_mfma_f32_16x16x32_bf16 v[78:81], v[156:159], v[226:229], v[78:81]
	v_mfma_f32_16x16x32_bf16 v[74:77], v[164:167], v[226:229], v[74:77]
	s_setprio 0
	s_setprio 1
	v_mfma_f32_16x16x32_bf16 v[118:121], v[168:171], v[184:187], v[118:121]
	v_mfma_f32_16x16x32_bf16 v[114:117], v[176:179], v[184:187], v[114:117]
	v_mfma_f32_16x16x32_bf16 v[102:105], v[168:171], v[198:201], v[102:105]
	v_mfma_f32_16x16x32_bf16 v[98:101], v[176:179], v[198:201], v[98:101]
	v_mfma_f32_16x16x32_bf16 v[86:89], v[168:171], v[214:217], v[86:89]
	v_mfma_f32_16x16x32_bf16 v[82:85], v[176:179], v[214:217], v[82:85]
	v_mfma_f32_16x16x32_bf16 v[70:73], v[168:171], v[222:225], v[70:73]
	v_mfma_f32_16x16x32_bf16 v[66:69], v[176:179], v[222:225], v[66:69]
	v_mfma_f32_16x16x32_bf16 v[118:121], v[172:175], v[188:191], v[118:121]
	v_mfma_f32_16x16x32_bf16 v[114:117], v[180:183], v[188:191], v[114:117]
	v_mfma_f32_16x16x32_bf16 v[102:105], v[172:175], v[210:213], v[102:105]
	v_mfma_f32_16x16x32_bf16 v[98:101], v[180:183], v[210:213], v[98:101]
	v_mfma_f32_16x16x32_bf16 v[86:89], v[172:175], v[218:221], v[86:89]
	v_mfma_f32_16x16x32_bf16 v[82:85], v[180:183], v[218:221], v[82:85]
	v_mfma_f32_16x16x32_bf16 v[70:73], v[172:175], v[226:229], v[70:73]
	v_mfma_f32_16x16x32_bf16 v[66:69], v[180:183], v[226:229], v[66:69]
	s_setprio 0
	s_barrier
	s_add_i32 s19, s19, s33
	v_lshl_add_u64 v[144:145], v[144:145], 0, s[10:11]
	s_mov_b32 m0, s19
	ds_read_b128 v[184:187], v150 offset:49152
	ds_read_b128 v[188:191], v150 offset:50176
	ds_read_b128 v[198:201], v150 offset:51200
	ds_read_b128 v[210:213], v150 offset:52224
	ds_read_b128 v[214:217], v150 offset:53248
	ds_read_b128 v[218:221], v150 offset:54272
	ds_read_b128 v[222:225], v150 offset:55296
	ds_read_b128 v[226:229], v150 offset:56320
	global_load_lds_dwordx4 v[144:145], off
	s_add_i32 m0, s19, 0x2000
	s_add_u32 s34, s34, 0x80080
	v_lshl_add_u64 v[144:145], v[192:193], 0, s[10:11]
	s_addc_u32 s35, s35, 0
	s_add_i32 s19, s38, s33
	global_load_lds_dwordx4 v[144:145], off
	v_lshl_add_u64 v[144:145], s[34:35], 0, v[132:133]
	s_mov_b32 m0, s19
	s_nop 0
	global_load_lds_dwordx4 v[144:145], off
	v_lshl_add_u64 v[144:145], s[34:35], 0, v[136:137]
	s_add_i32 m0, s19, 0x2000
	s_nop 0
	global_load_lds_dwordx4 v[144:145], off
	v_lshl_add_u64 v[144:145], v[202:203], 0, s[10:11]
	s_mov_b32 m0, s51
	s_nop 0
	global_load_lds_dwordx4 v[144:145], off
	v_lshl_add_u64 v[144:145], v[206:207], 0, s[10:11]
	s_mov_b32 m0, s52
	s_nop 0
	global_load_lds_dwordx4 v[144:145], off
	s_waitcnt vmcnt(8)
	s_waitcnt lgkmcnt(0)
	s_barrier
	s_setprio 1
	s_waitcnt lgkmcnt(0)
	v_mfma_f32_16x16x32_bf16 v[62:65], v[152:155], v[184:187], v[62:65]
	v_mfma_f32_16x16x32_bf16 v[58:61], v[160:163], v[184:187], v[58:61]
	v_mfma_f32_16x16x32_bf16 v[46:49], v[152:155], v[198:201], v[46:49]
	v_mfma_f32_16x16x32_bf16 v[42:45], v[160:163], v[198:201], v[42:45]
	v_mfma_f32_16x16x32_bf16 v[30:33], v[152:155], v[214:217], v[30:33]
	v_mfma_f32_16x16x32_bf16 v[26:29], v[160:163], v[214:217], v[26:29]
	v_mfma_f32_16x16x32_bf16 v[14:17], v[152:155], v[222:225], v[14:17]
	v_mfma_f32_16x16x32_bf16 v[10:13], v[160:163], v[222:225], v[10:13]
	v_mfma_f32_16x16x32_bf16 v[62:65], v[156:159], v[188:191], v[62:65]
	v_mfma_f32_16x16x32_bf16 v[58:61], v[164:167], v[188:191], v[58:61]
	v_mfma_f32_16x16x32_bf16 v[46:49], v[156:159], v[210:213], v[46:49]
	v_mfma_f32_16x16x32_bf16 v[42:45], v[164:167], v[210:213], v[42:45]
	v_mfma_f32_16x16x32_bf16 v[30:33], v[156:159], v[218:221], v[30:33]
	v_mfma_f32_16x16x32_bf16 v[26:29], v[164:167], v[218:221], v[26:29]
	v_mfma_f32_16x16x32_bf16 v[14:17], v[156:159], v[226:229], v[14:17]
	v_mfma_f32_16x16x32_bf16 v[10:13], v[164:167], v[226:229], v[10:13]
	s_setprio 0
	s_setprio 1
	v_mfma_f32_16x16x32_bf16 v[54:57], v[168:171], v[184:187], v[54:57]
	v_mfma_f32_16x16x32_bf16 v[50:53], v[176:179], v[184:187], v[50:53]
	v_mfma_f32_16x16x32_bf16 v[38:41], v[168:171], v[198:201], v[38:41]
	v_mfma_f32_16x16x32_bf16 v[34:37], v[176:179], v[198:201], v[34:37]
	v_mfma_f32_16x16x32_bf16 v[22:25], v[168:171], v[214:217], v[22:25]
	v_mfma_f32_16x16x32_bf16 v[18:21], v[176:179], v[214:217], v[18:21]
	v_mfma_f32_16x16x32_bf16 v[6:9], v[168:171], v[222:225], v[6:9]
	v_mfma_f32_16x16x32_bf16 v[2:5], v[176:179], v[222:225], v[2:5]
	v_mfma_f32_16x16x32_bf16 v[54:57], v[172:175], v[188:191], v[54:57]
	v_mfma_f32_16x16x32_bf16 v[50:53], v[180:183], v[188:191], v[50:53]
	v_mfma_f32_16x16x32_bf16 v[38:41], v[172:175], v[210:213], v[38:41]
	v_mfma_f32_16x16x32_bf16 v[34:37], v[180:183], v[210:213], v[34:37]
	v_mfma_f32_16x16x32_bf16 v[22:25], v[172:175], v[218:221], v[22:25]
	v_mfma_f32_16x16x32_bf16 v[18:21], v[180:183], v[218:221], v[18:21]
	v_mfma_f32_16x16x32_bf16 v[6:9], v[172:175], v[226:229], v[6:9]
	v_mfma_f32_16x16x32_bf16 v[2:5], v[180:183], v[226:229], v[2:5]
	s_setprio 0
	s_barrier
	s_add_u32 s30, s30, 0x100
	s_addc_u32 s31, s31, 0
	s_add_u32 s15, s15, 0x100
	s_addc_u32 s17, s17, 0
	s_cmp_ge_i32 s29, s68
	s_mov_b32 s19, s29
	s_cbranch_scc0 .LBB0_1315
	s_branch .Lpeeldone_7

.Lpeeldone_7:
	s_and_b64 vcc, exec, s[12:13]
	s_cbranch_vccnz .LBB0_1323
	s_cmp_gt_i32 s6, -1
	s_mov_b64 s[28:29], -1
	s_cbranch_scc1 .LBB0_1324

.Lpeel_6:
	ds_read_b128 v[144:147], v166
	ds_read_b128 v[148:151], v166 offset:1024
	ds_read_b128 v[152:155], v166 offset:2048
	ds_read_b128 v[156:159], v166 offset:3072
	ds_read_b128 v[160:163], v167
	ds_read_b128 v[170:173], v167 offset:1024
	ds_read_b128 v[174:177], v167 offset:2048
	ds_read_b128 v[178:181], v167 offset:3072
	s_add_i32 s30, s26, 2
	s_add_u32 s27, s24, 0xffea0080
	s_addc_u32 s28, s25, -1
	s_cmp_eq_u32 s22, s26
	s_cselect_b32 s26, s20, s17
	s_cselect_b32 s29, s19, s28
	s_cselect_b32 s28, s18, s27
	s_cselect_b32 s27, s21, s23
	v_lshl_add_u64 v[202:203], s[24:25], 0, v[140:141]
	s_add_i32 m0, s34, 0xc000
	ds_read_b128 v[182:185], v168
	ds_read_b128 v[186:189], v168 offset:1024
	ds_read_b128 v[190:193], v168 offset:2048
	ds_read_b128 v[198:201], v168 offset:3072
	ds_read_b128 v[210:213], v168 offset:4096
	ds_read_b128 v[214:217], v168 offset:5120
	ds_read_b128 v[218:221], v168 offset:6144
	ds_read_b128 v[222:225], v168 offset:7168
	global_load_lds_dwordx4 v[202:203], off
	v_lshl_add_u64 v[202:203], s[24:25], 0, v[142:143]
	s_add_i32 m0, s34, 0xe000
	s_nop 0
	global_load_lds_dwordx4 v[202:203], off
	s_waitcnt vmcnt(8)
	s_waitcnt lgkmcnt(0)
	s_barrier
	s_setprio 1
	s_waitcnt lgkmcnt(0)
	v_mfma_f32_16x16x32_bf16 v[126:129], v[144:147], v[182:185], 0
	v_mfma_f32_16x16x32_bf16 v[122:125], v[152:155], v[182:185], 0
	v_mfma_f32_16x16x32_bf16 v[114:117], v[144:147], v[190:193], 0
	v_mfma_f32_16x16x32_bf16 v[106:109], v[152:155], v[190:193], 0
	v_mfma_f32_16x16x32_bf16 v[94:97], v[144:147], v[210:213], 0
	v_mfma_f32_16x16x32_bf16 v[90:93], v[152:155], v[210:213], 0
	v_mfma_f32_16x16x32_bf16 v[78:81], v[144:147], v[218:221], 0
	v_mfma_f32_16x16x32_bf16 v[74:77], v[152:155], v[218:221], 0
	v_mfma_f32_16x16x32_bf16 v[126:129], v[148:151], v[186:189], v[126:129]
	v_mfma_f32_16x16x32_bf16 v[122:125], v[156:159], v[186:189], v[122:125]
	v_mfma_f32_16x16x32_bf16 v[114:117], v[148:151], v[198:201], v[114:117]
	v_mfma_f32_16x16x32_bf16 v[106:109], v[156:159], v[198:201], v[106:109]
	v_mfma_f32_16x16x32_bf16 v[94:97], v[148:151], v[214:217], v[94:97]
	v_mfma_f32_16x16x32_bf16 v[90:93], v[156:159], v[214:217], v[90:93]
	v_mfma_f32_16x16x32_bf16 v[78:81], v[148:151], v[222:225], v[78:81]
	v_mfma_f32_16x16x32_bf16 v[74:77], v[156:159], v[222:225], v[74:77]
	s_setprio 0
	s_setprio 1
	v_mfma_f32_16x16x32_bf16 v[118:121], v[160:163], v[182:185], 0
	v_mfma_f32_16x16x32_bf16 v[110:113], v[174:177], v[182:185], 0
	v_mfma_f32_16x16x32_bf16 v[102:105], v[160:163], v[190:193], 0
	v_mfma_f32_16x16x32_bf16 v[98:101], v[174:177], v[190:193], 0
	v_mfma_f32_16x16x32_bf16 v[86:89], v[160:163], v[210:213], 0
	v_mfma_f32_16x16x32_bf16 v[82:85], v[174:177], v[210:213], 0
	v_mfma_f32_16x16x32_bf16 v[70:73], v[160:163], v[218:221], 0
	v_mfma_f32_16x16x32_bf16 v[66:69], v[174:177], v[218:221], 0
	v_mfma_f32_16x16x32_bf16 v[118:121], v[170:173], v[186:189], v[118:121]
	v_mfma_f32_16x16x32_bf16 v[110:113], v[178:181], v[186:189], v[110:113]
	v_mfma_f32_16x16x32_bf16 v[102:105], v[170:173], v[198:201], v[102:105]
	v_mfma_f32_16x16x32_bf16 v[98:101], v[178:181], v[198:201], v[98:101]
	v_mfma_f32_16x16x32_bf16 v[86:89], v[170:173], v[214:217], v[86:89]
	v_mfma_f32_16x16x32_bf16 v[82:85], v[178:181], v[214:217], v[82:85]
	v_mfma_f32_16x16x32_bf16 v[70:73], v[170:173], v[222:225], v[70:73]
	v_mfma_f32_16x16x32_bf16 v[66:69], v[178:181], v[222:225], v[66:69]
	s_setprio 0
	s_barrier
	s_add_i32 s31, s57, s33
	v_lshl_add_u64 v[202:203], s[26:27], 0, v[132:133]
	s_mov_b32 m0, s31
	ds_read_b128 v[182:185], v168 offset:16384
	ds_read_b128 v[186:189], v168 offset:17408
	ds_read_b128 v[190:193], v168 offset:18432
	ds_read_b128 v[198:201], v168 offset:19456
	ds_read_b128 v[210:213], v168 offset:20480
	ds_read_b128 v[214:217], v168 offset:21504
	ds_read_b128 v[218:221], v168 offset:22528
	ds_read_b128 v[222:225], v168 offset:23552
	global_load_lds_dwordx4 v[202:203], off
	s_add_i32 m0, s31, 0x2000
	s_add_u32 s68, s26, 0x160000
	v_lshl_add_u64 v[206:207], s[26:27], 0, v[136:137]
	s_addc_u32 s69, s27, 0
	s_add_i32 s31, s58, s33
	global_load_lds_dwordx4 v[206:207], off
	v_lshl_add_u64 v[226:227], s[68:69], 0, v[132:133]
	s_mov_b32 m0, s31
	v_lshl_add_u64 v[228:229], s[28:29], 0, v[134:135]
	global_load_lds_dwordx4 v[226:227], off
	v_lshl_add_u64 v[226:227], s[68:69], 0, v[136:137]
	s_add_i32 m0, s31, 0x2000
	s_nop 0
	global_load_lds_dwordx4 v[226:227], off
	v_lshl_add_u64 v[226:227], s[28:29], 0, v[130:131]
	s_mov_b32 m0, s34
	s_nop 0
	global_load_lds_dwordx4 v[226:227], off
	s_mov_b32 m0, s35
	s_nop 0
	global_load_lds_dwordx4 v[228:229], off
	s_waitcnt vmcnt(8)
	s_waitcnt lgkmcnt(0)
	s_barrier
	s_setprio 1
	s_waitcnt lgkmcnt(0)
	v_mfma_f32_16x16x32_bf16 v[62:65], v[144:147], v[182:185], 0
	v_mfma_f32_16x16x32_bf16 v[58:61], v[152:155], v[182:185], 0
	v_mfma_f32_16x16x32_bf16 v[46:49], v[144:147], v[190:193], 0
	v_mfma_f32_16x16x32_bf16 v[42:45], v[152:155], v[190:193], 0
	v_mfma_f32_16x16x32_bf16 v[30:33], v[144:147], v[210:213], 0
	v_mfma_f32_16x16x32_bf16 v[26:29], v[152:155], v[210:213], 0
	v_mfma_f32_16x16x32_bf16 v[14:17], v[144:147], v[218:221], 0
	v_mfma_f32_16x16x32_bf16 v[10:13], v[152:155], v[218:221], 0
	v_mfma_f32_16x16x32_bf16 v[62:65], v[148:151], v[186:189], v[62:65]
	v_mfma_f32_16x16x32_bf16 v[58:61], v[156:159], v[186:189], v[58:61]
	v_mfma_f32_16x16x32_bf16 v[46:49], v[148:151], v[198:201], v[46:49]
	v_mfma_f32_16x16x32_bf16 v[42:45], v[156:159], v[198:201], v[42:45]
	v_mfma_f32_16x16x32_bf16 v[30:33], v[148:151], v[214:217], v[30:33]
	v_mfma_f32_16x16x32_bf16 v[26:29], v[156:159], v[214:217], v[26:29]
	v_mfma_f32_16x16x32_bf16 v[14:17], v[148:151], v[222:225], v[14:17]
	v_mfma_f32_16x16x32_bf16 v[10:13], v[156:159], v[222:225], v[10:13]
	s_setprio 0
	s_setprio 1
	v_mfma_f32_16x16x32_bf16 v[54:57], v[160:163], v[182:185], 0
	v_mfma_f32_16x16x32_bf16 v[50:53], v[174:177], v[182:185], 0
	v_mfma_f32_16x16x32_bf16 v[38:41], v[160:163], v[190:193], 0
	v_mfma_f32_16x16x32_bf16 v[34:37], v[174:177], v[190:193], 0
	v_mfma_f32_16x16x32_bf16 v[22:25], v[160:163], v[210:213], 0
	v_mfma_f32_16x16x32_bf16 v[18:21], v[174:177], v[210:213], 0
	v_mfma_f32_16x16x32_bf16 v[6:9], v[160:163], v[218:221], 0
	v_mfma_f32_16x16x32_bf16 v[2:5], v[174:177], v[218:221], 0
	v_mfma_f32_16x16x32_bf16 v[54:57], v[170:173], v[186:189], v[54:57]
	v_mfma_f32_16x16x32_bf16 v[50:53], v[178:181], v[186:189], v[50:53]
	v_mfma_f32_16x16x32_bf16 v[38:41], v[170:173], v[198:201], v[38:41]
	v_mfma_f32_16x16x32_bf16 v[34:37], v[178:181], v[198:201], v[34:37]
	v_mfma_f32_16x16x32_bf16 v[22:25], v[170:173], v[214:217], v[22:25]
	v_mfma_f32_16x16x32_bf16 v[18:21], v[178:181], v[214:217], v[18:21]
	v_mfma_f32_16x16x32_bf16 v[6:9], v[170:173], v[222:225], v[6:9]
	v_mfma_f32_16x16x32_bf16 v[2:5], v[178:181], v[222:225], v[2:5]
	s_setprio 0
	s_barrier
	s_add_i32 s31, 0, 0x18000
	s_add_i32 s68, 0, 0x1c000
	v_add_u32_e32 v156, s31, v164
	v_add_u32_e32 v169, s68, v164
	ds_read_b128 v[144:147], v156
	ds_read_b128 v[148:151], v156 offset:1024
	ds_read_b128 v[152:155], v156 offset:2048
	ds_read_b128 v[156:159], v156 offset:3072
	ds_read_b128 v[160:163], v169
	ds_read_b128 v[170:173], v169 offset:1024
	ds_read_b128 v[174:177], v169 offset:2048
	ds_read_b128 v[178:181], v169 offset:3072
	s_add_u32 s28, s28, 0x160000
	s_addc_u32 s29, s29, 0
	s_mov_b32 m0, s36
	v_lshl_add_u64 v[230:231], s[28:29], 0, v[130:131]
	ds_read_b128 v[182:185], v168 offset:32768
	ds_read_b128 v[186:189], v168 offset:33792
	ds_read_b128 v[190:193], v168 offset:34816
	ds_read_b128 v[198:201], v168 offset:35840
	ds_read_b128 v[210:213], v168 offset:36864
	ds_read_b128 v[214:217], v168 offset:37888
	ds_read_b128 v[218:221], v168 offset:38912
	ds_read_b128 v[222:225], v168 offset:39936
	global_load_lds_dwordx4 v[230:231], off
	v_lshl_add_u64 v[230:231], s[28:29], 0, v[134:135]
	s_mov_b32 m0, s37
	s_nop 0
	global_load_lds_dwordx4 v[230:231], off
	s_waitcnt vmcnt(8)
	s_waitcnt lgkmcnt(0)
	s_barrier
	s_setprio 1
	s_waitcnt lgkmcnt(0)
	v_mfma_f32_16x16x32_bf16 v[126:129], v[144:147], v[182:185], v[126:129]
	v_mfma_f32_16x16x32_bf16 v[122:125], v[152:155], v[182:185], v[122:125]
	v_mfma_f32_16x16x32_bf16 v[114:117], v[144:147], v[190:193], v[114:117]
	v_mfma_f32_16x16x32_bf16 v[106:109], v[152:155], v[190:193], v[106:109]
	v_mfma_f32_16x16x32_bf16 v[94:97], v[144:147], v[210:213], v[94:97]
	v_mfma_f32_16x16x32_bf16 v[90:93], v[152:155], v[210:213], v[90:93]
	v_mfma_f32_16x16x32_bf16 v[78:81], v[144:147], v[218:221], v[78:81]
	v_mfma_f32_16x16x32_bf16 v[74:77], v[152:155], v[218:221], v[74:77]
	v_mfma_f32_16x16x32_bf16 v[126:129], v[148:151], v[186:189], v[126:129]
	v_mfma_f32_16x16x32_bf16 v[122:125], v[156:159], v[186:189], v[122:125]
	v_mfma_f32_16x16x32_bf16 v[114:117], v[148:151], v[198:201], v[114:117]
	v_mfma_f32_16x16x32_bf16 v[106:109], v[156:159], v[198:201], v[106:109]
	v_mfma_f32_16x16x32_bf16 v[94:97], v[148:151], v[214:217], v[94:97]
	v_mfma_f32_16x16x32_bf16 v[90:93], v[156:159], v[214:217], v[90:93]
	v_mfma_f32_16x16x32_bf16 v[78:81], v[148:151], v[222:225], v[78:81]
	v_mfma_f32_16x16x32_bf16 v[74:77], v[156:159], v[222:225], v[74:77]
	s_setprio 0
	s_setprio 1
	v_mfma_f32_16x16x32_bf16 v[118:121], v[160:163], v[182:185], v[118:121]
	v_mfma_f32_16x16x32_bf16 v[110:113], v[174:177], v[182:185], v[110:113]
	v_mfma_f32_16x16x32_bf16 v[102:105], v[160:163], v[190:193], v[102:105]
	v_mfma_f32_16x16x32_bf16 v[98:101], v[174:177], v[190:193], v[98:101]
	v_mfma_f32_16x16x32_bf16 v[86:89], v[160:163], v[210:213], v[86:89]
	v_mfma_f32_16x16x32_bf16 v[82:85], v[174:177], v[210:213], v[82:85]
	v_mfma_f32_16x16x32_bf16 v[70:73], v[160:163], v[218:221], v[70:73]
	v_mfma_f32_16x16x32_bf16 v[66:69], v[174:177], v[218:221], v[66:69]
	v_mfma_f32_16x16x32_bf16 v[118:121], v[170:173], v[186:189], v[118:121]
	v_mfma_f32_16x16x32_bf16 v[110:113], v[178:181], v[186:189], v[110:113]
	v_mfma_f32_16x16x32_bf16 v[102:105], v[170:173], v[198:201], v[102:105]
	v_mfma_f32_16x16x32_bf16 v[98:101], v[178:181], v[198:201], v[98:101]
	v_mfma_f32_16x16x32_bf16 v[86:89], v[170:173], v[214:217], v[86:89]
	v_mfma_f32_16x16x32_bf16 v[82:85], v[178:181], v[214:217], v[82:85]
	v_mfma_f32_16x16x32_bf16 v[70:73], v[170:173], v[222:225], v[70:73]
	v_mfma_f32_16x16x32_bf16 v[66:69], v[178:181], v[222:225], v[66:69]
	s_setprio 0
	s_barrier
	s_add_i32 s28, s31, s33
	v_lshl_add_u64 v[202:203], v[202:203], 0, s[12:13]
	s_mov_b32 m0, s28
	ds_read_b128 v[182:185], v168 offset:49152
	ds_read_b128 v[186:189], v168 offset:50176
	ds_read_b128 v[190:193], v168 offset:51200
	ds_read_b128 v[198:201], v168 offset:52224
	ds_read_b128 v[210:213], v168 offset:53248
	ds_read_b128 v[214:217], v168 offset:54272
	ds_read_b128 v[218:221], v168 offset:55296
	ds_read_b128 v[222:225], v168 offset:56320
	global_load_lds_dwordx4 v[202:203], off
	s_add_i32 m0, s28, 0x2000
	s_add_u32 s26, s26, 0x160080
	v_lshl_add_u64 v[202:203], v[206:207], 0, s[12:13]
	s_addc_u32 s27, s27, 0
	s_add_i32 s28, s68, s33
	global_load_lds_dwordx4 v[202:203], off
	v_lshl_add_u64 v[202:203], s[26:27], 0, v[132:133]
	s_mov_b32 m0, s28
	s_nop 0
	global_load_lds_dwordx4 v[202:203], off
	v_lshl_add_u64 v[202:203], s[26:27], 0, v[136:137]
	s_add_i32 m0, s28, 0x2000
	s_nop 0
	global_load_lds_dwordx4 v[202:203], off
	v_lshl_add_u64 v[202:203], v[226:227], 0, s[12:13]
	s_mov_b32 m0, s47
	s_nop 0
	global_load_lds_dwordx4 v[202:203], off
	v_lshl_add_u64 v[202:203], v[228:229], 0, s[12:13]
	s_mov_b32 m0, s48
	s_nop 0
	global_load_lds_dwordx4 v[202:203], off
	s_waitcnt vmcnt(8)
	s_waitcnt lgkmcnt(0)
	s_barrier
	s_setprio 1
	s_waitcnt lgkmcnt(0)
	v_mfma_f32_16x16x32_bf16 v[62:65], v[144:147], v[182:185], v[62:65]
	v_mfma_f32_16x16x32_bf16 v[58:61], v[152:155], v[182:185], v[58:61]
	v_mfma_f32_16x16x32_bf16 v[46:49], v[144:147], v[190:193], v[46:49]
	v_mfma_f32_16x16x32_bf16 v[42:45], v[152:155], v[190:193], v[42:45]
	v_mfma_f32_16x16x32_bf16 v[30:33], v[144:147], v[210:213], v[30:33]
	v_mfma_f32_16x16x32_bf16 v[26:29], v[152:155], v[210:213], v[26:29]
	v_mfma_f32_16x16x32_bf16 v[14:17], v[144:147], v[218:221], v[14:17]
	v_mfma_f32_16x16x32_bf16 v[10:13], v[152:155], v[218:221], v[10:13]
	v_mfma_f32_16x16x32_bf16 v[62:65], v[148:151], v[186:189], v[62:65]
	v_mfma_f32_16x16x32_bf16 v[58:61], v[156:159], v[186:189], v[58:61]
	v_mfma_f32_16x16x32_bf16 v[46:49], v[148:151], v[198:201], v[46:49]
	v_mfma_f32_16x16x32_bf16 v[42:45], v[156:159], v[198:201], v[42:45]
	v_mfma_f32_16x16x32_bf16 v[30:33], v[148:151], v[214:217], v[30:33]
	v_mfma_f32_16x16x32_bf16 v[26:29], v[156:159], v[214:217], v[26:29]
	v_mfma_f32_16x16x32_bf16 v[14:17], v[148:151], v[222:225], v[14:17]
	v_mfma_f32_16x16x32_bf16 v[10:13], v[156:159], v[222:225], v[10:13]
	s_setprio 0
	s_setprio 1
	v_mfma_f32_16x16x32_bf16 v[54:57], v[160:163], v[182:185], v[54:57]
	v_mfma_f32_16x16x32_bf16 v[50:53], v[174:177], v[182:185], v[50:53]
	v_mfma_f32_16x16x32_bf16 v[38:41], v[160:163], v[190:193], v[38:41]
	v_mfma_f32_16x16x32_bf16 v[34:37], v[174:177], v[190:193], v[34:37]
	v_mfma_f32_16x16x32_bf16 v[22:25], v[160:163], v[210:213], v[22:25]
	v_mfma_f32_16x16x32_bf16 v[18:21], v[174:177], v[210:213], v[18:21]
	v_mfma_f32_16x16x32_bf16 v[6:9], v[160:163], v[218:221], v[6:9]
	v_mfma_f32_16x16x32_bf16 v[2:5], v[174:177], v[218:221], v[2:5]
	v_mfma_f32_16x16x32_bf16 v[54:57], v[170:173], v[186:189], v[54:57]
	v_mfma_f32_16x16x32_bf16 v[50:53], v[178:181], v[186:189], v[50:53]
	v_mfma_f32_16x16x32_bf16 v[38:41], v[170:173], v[198:201], v[38:41]
	v_mfma_f32_16x16x32_bf16 v[34:37], v[178:181], v[198:201], v[34:37]
	v_mfma_f32_16x16x32_bf16 v[22:25], v[170:173], v[214:217], v[22:25]
	v_mfma_f32_16x16x32_bf16 v[18:21], v[178:181], v[214:217], v[18:21]
	v_mfma_f32_16x16x32_bf16 v[6:9], v[170:173], v[222:225], v[6:9]
	v_mfma_f32_16x16x32_bf16 v[2:5], v[178:181], v[222:225], v[2:5]
	s_setprio 0
	s_barrier
	s_add_u32 s24, s24, 0x100
	s_addc_u32 s25, s25, 0
	s_add_u32 s17, s17, 0x100
	s_addc_u32 s23, s23, 0
	s_cmp_ge_i32 s30, s67
	s_mov_b32 s26, s30
	s_cbranch_scc0 .LBB0_1451
	s_branch .Lpeeldone_6

.Lpeeldone_6:
	s_and_b64 vcc, exec, s[14:15]
	s_cbranch_vccnz .LBB0_1459
	s_cmp_gt_i32 s6, -1
	s_mov_b64 s[22:23], -1
	s_cbranch_scc1 .LBB0_1460

.Lpeel_3:
	ds_read_b128 v[150:153], v146
	ds_read_b128 v[154:157], v146 offset:1024
	ds_read_b128 v[158:161], v146 offset:2048
	ds_read_b128 v[162:165], v146 offset:3072
	ds_read_b128 v[166:169], v147
	ds_read_b128 v[170:173], v147 offset:1024
	ds_read_b128 v[174:177], v147 offset:2048
	ds_read_b128 v[178:181], v147 offset:3072
	s_add_i32 s29, s23, 2
	s_add_u32 s34, s30, 0xfff80080
	s_addc_u32 s35, s31, -1
	s_cmp_eq_u32 s28, s23
	s_cselect_b32 s37, s25, s35
	s_cselect_b32 s36, s24, s34
	s_cselect_b32 s35, s27, s21
	s_cselect_b32 s34, s26, s19
	v_lshl_add_u64 v[202:203], s[30:31], 0, v[140:141]
	s_add_i32 m0, s15, 0xc000
	ds_read_b128 v[182:185], v148
	ds_read_b128 v[186:189], v148 offset:1024
	ds_read_b128 v[190:193], v148 offset:2048
	ds_read_b128 v[198:201], v148 offset:3072
	ds_read_b128 v[210:213], v148 offset:4096
	ds_read_b128 v[214:217], v148 offset:5120
	ds_read_b128 v[218:221], v148 offset:6144
	ds_read_b128 v[222:225], v148 offset:7168
	global_load_lds_dwordx4 v[202:203], off
	v_lshl_add_u64 v[202:203], s[30:31], 0, v[142:143]
	s_add_i32 m0, s15, 0xe000
	s_nop 0
	global_load_lds_dwordx4 v[202:203], off
	s_waitcnt vmcnt(8)
	s_waitcnt lgkmcnt(0)
	s_barrier
	s_setprio 1
	s_waitcnt lgkmcnt(0)
	v_mfma_f32_16x16x32_bf16 v[126:129], v[150:153], v[182:185], 0
	v_mfma_f32_16x16x32_bf16 v[122:125], v[158:161], v[182:185], 0
	v_mfma_f32_16x16x32_bf16 v[118:121], v[150:153], v[190:193], 0
	v_mfma_f32_16x16x32_bf16 v[114:117], v[158:161], v[190:193], 0
	v_mfma_f32_16x16x32_bf16 v[110:113], v[150:153], v[210:213], 0
	v_mfma_f32_16x16x32_bf16 v[106:109], v[158:161], v[210:213], 0
	v_mfma_f32_16x16x32_bf16 v[102:105], v[150:153], v[218:221], 0
	v_mfma_f32_16x16x32_bf16 v[98:101], v[158:161], v[218:221], 0
	v_mfma_f32_16x16x32_bf16 v[126:129], v[154:157], v[186:189], v[126:129]
	v_mfma_f32_16x16x32_bf16 v[122:125], v[162:165], v[186:189], v[122:125]
	v_mfma_f32_16x16x32_bf16 v[118:121], v[154:157], v[198:201], v[118:121]
	v_mfma_f32_16x16x32_bf16 v[114:117], v[162:165], v[198:201], v[114:117]
	v_mfma_f32_16x16x32_bf16 v[110:113], v[154:157], v[214:217], v[110:113]
	v_mfma_f32_16x16x32_bf16 v[106:109], v[162:165], v[214:217], v[106:109]
	v_mfma_f32_16x16x32_bf16 v[102:105], v[154:157], v[222:225], v[102:105]
	v_mfma_f32_16x16x32_bf16 v[98:101], v[162:165], v[222:225], v[98:101]
	s_setprio 0
	s_setprio 1
	v_mfma_f32_16x16x32_bf16 v[94:97], v[166:169], v[182:185], 0
	v_mfma_f32_16x16x32_bf16 v[90:93], v[174:177], v[182:185], 0
	v_mfma_f32_16x16x32_bf16 v[86:89], v[166:169], v[190:193], 0
	v_mfma_f32_16x16x32_bf16 v[82:85], v[174:177], v[190:193], 0
	v_mfma_f32_16x16x32_bf16 v[78:81], v[166:169], v[210:213], 0
	v_mfma_f32_16x16x32_bf16 v[74:77], v[174:177], v[210:213], 0
	v_mfma_f32_16x16x32_bf16 v[70:73], v[166:169], v[218:221], 0
	v_mfma_f32_16x16x32_bf16 v[66:69], v[174:177], v[218:221], 0
	v_mfma_f32_16x16x32_bf16 v[94:97], v[170:173], v[186:189], v[94:97]
	v_mfma_f32_16x16x32_bf16 v[90:93], v[178:181], v[186:189], v[90:93]
	v_mfma_f32_16x16x32_bf16 v[86:89], v[170:173], v[198:201], v[86:89]
	v_mfma_f32_16x16x32_bf16 v[82:85], v[178:181], v[198:201], v[82:85]
	v_mfma_f32_16x16x32_bf16 v[78:81], v[170:173], v[214:217], v[78:81]
	v_mfma_f32_16x16x32_bf16 v[74:77], v[178:181], v[214:217], v[74:77]
	v_mfma_f32_16x16x32_bf16 v[70:73], v[170:173], v[222:225], v[70:73]
	v_mfma_f32_16x16x32_bf16 v[66:69], v[178:181], v[222:225], v[66:69]
	s_setprio 0
	s_barrier
	s_add_i32 s23, s60, s33
	v_lshl_add_u64 v[202:203], s[34:35], 0, v[132:133]
	s_mov_b32 m0, s23
	ds_read_b128 v[182:185], v148 offset:16384
	ds_read_b128 v[186:189], v148 offset:17408
	ds_read_b128 v[190:193], v148 offset:18432
	ds_read_b128 v[198:201], v148 offset:19456
	ds_read_b128 v[210:213], v148 offset:20480
	ds_read_b128 v[214:217], v148 offset:21504
	ds_read_b128 v[218:221], v148 offset:22528
	ds_read_b128 v[222:225], v148 offset:23552
	global_load_lds_dwordx4 v[202:203], off
	s_add_i32 m0, s23, 0x2000
	s_add_u32 s38, s34, 0x80000
	v_lshl_add_u64 v[206:207], s[34:35], 0, v[136:137]
	s_addc_u32 s39, s35, 0
	s_add_i32 s23, s61, s33
	global_load_lds_dwordx4 v[206:207], off
	v_lshl_add_u64 v[226:227], s[38:39], 0, v[132:133]
	s_mov_b32 m0, s23
	v_lshl_add_u64 v[228:229], s[36:37], 0, v[134:135]
	global_load_lds_dwordx4 v[226:227], off
	v_lshl_add_u64 v[226:227], s[38:39], 0, v[136:137]
	s_add_i32 m0, s23, 0x2000
	s_nop 0
	global_load_lds_dwordx4 v[226:227], off
	v_lshl_add_u64 v[226:227], s[36:37], 0, v[130:131]
	s_mov_b32 m0, s15
	s_nop 0
	global_load_lds_dwordx4 v[226:227], off
	s_mov_b32 m0, s41
	s_nop 0
	global_load_lds_dwordx4 v[228:229], off
	s_waitcnt vmcnt(8)
	s_waitcnt lgkmcnt(0)
	s_barrier
	s_setprio 1
	s_waitcnt lgkmcnt(0)
	v_mfma_f32_16x16x32_bf16 v[62:65], v[150:153], v[182:185], 0
	v_mfma_f32_16x16x32_bf16 v[58:61], v[158:161], v[182:185], 0
	v_mfma_f32_16x16x32_bf16 v[54:57], v[150:153], v[190:193], 0
	v_mfma_f32_16x16x32_bf16 v[50:53], v[158:161], v[190:193], 0
	v_mfma_f32_16x16x32_bf16 v[46:49], v[150:153], v[210:213], 0
	v_mfma_f32_16x16x32_bf16 v[42:45], v[158:161], v[210:213], 0
	v_mfma_f32_16x16x32_bf16 v[38:41], v[150:153], v[218:221], 0
	v_mfma_f32_16x16x32_bf16 v[34:37], v[158:161], v[218:221], 0
	v_mfma_f32_16x16x32_bf16 v[62:65], v[154:157], v[186:189], v[62:65]
	v_mfma_f32_16x16x32_bf16 v[58:61], v[162:165], v[186:189], v[58:61]
	v_mfma_f32_16x16x32_bf16 v[54:57], v[154:157], v[198:201], v[54:57]
	v_mfma_f32_16x16x32_bf16 v[50:53], v[162:165], v[198:201], v[50:53]
	v_mfma_f32_16x16x32_bf16 v[46:49], v[154:157], v[214:217], v[46:49]
	v_mfma_f32_16x16x32_bf16 v[42:45], v[162:165], v[214:217], v[42:45]
	v_mfma_f32_16x16x32_bf16 v[38:41], v[154:157], v[222:225], v[38:41]
	v_mfma_f32_16x16x32_bf16 v[34:37], v[162:165], v[222:225], v[34:37]
	s_setprio 0
	s_setprio 1
	v_mfma_f32_16x16x32_bf16 v[30:33], v[166:169], v[182:185], 0
	v_mfma_f32_16x16x32_bf16 v[26:29], v[174:177], v[182:185], 0
	v_mfma_f32_16x16x32_bf16 v[22:25], v[166:169], v[190:193], 0
	v_mfma_f32_16x16x32_bf16 v[18:21], v[174:177], v[190:193], 0
	v_mfma_f32_16x16x32_bf16 v[14:17], v[166:169], v[210:213], 0
	v_mfma_f32_16x16x32_bf16 v[10:13], v[174:177], v[210:213], 0
	v_mfma_f32_16x16x32_bf16 v[6:9], v[166:169], v[218:221], 0
	v_mfma_f32_16x16x32_bf16 v[2:5], v[174:177], v[218:221], 0
	v_mfma_f32_16x16x32_bf16 v[30:33], v[170:173], v[186:189], v[30:33]
	v_mfma_f32_16x16x32_bf16 v[26:29], v[178:181], v[186:189], v[26:29]
	v_mfma_f32_16x16x32_bf16 v[22:25], v[170:173], v[198:201], v[22:25]
	v_mfma_f32_16x16x32_bf16 v[18:21], v[178:181], v[198:201], v[18:21]
	v_mfma_f32_16x16x32_bf16 v[14:17], v[170:173], v[214:217], v[14:17]
	v_mfma_f32_16x16x32_bf16 v[10:13], v[178:181], v[214:217], v[10:13]
	v_mfma_f32_16x16x32_bf16 v[6:9], v[170:173], v[222:225], v[6:9]
	v_mfma_f32_16x16x32_bf16 v[2:5], v[178:181], v[222:225], v[2:5]
	s_setprio 0
	s_barrier
	s_add_i32 s23, 0, 0x18000
	v_add_u32_e32 v149, s23, v144
	s_add_i32 s38, 0, 0x1c000
	ds_read_b128 v[150:153], v149
	ds_read_b128 v[154:157], v149 offset:1024
	ds_read_b128 v[158:161], v149 offset:2048
	ds_read_b128 v[162:165], v149 offset:3072
	v_add_u32_e32 v149, s38, v144
	ds_read_b128 v[166:169], v149
	ds_read_b128 v[170:173], v149 offset:1024
	ds_read_b128 v[174:177], v149 offset:2048
	ds_read_b128 v[178:181], v149 offset:3072
	s_add_u32 s36, s36, 0x80000
	s_addc_u32 s37, s37, 0
	s_mov_b32 m0, s42
	v_lshl_add_u64 v[230:231], s[36:37], 0, v[130:131]
	ds_read_b128 v[182:185], v148 offset:32768
	ds_read_b128 v[186:189], v148 offset:33792
	ds_read_b128 v[190:193], v148 offset:34816
	ds_read_b128 v[198:201], v148 offset:35840
	ds_read_b128 v[210:213], v148 offset:36864
	ds_read_b128 v[214:217], v148 offset:37888
	ds_read_b128 v[218:221], v148 offset:38912
	ds_read_b128 v[222:225], v148 offset:39936
	global_load_lds_dwordx4 v[230:231], off
	v_lshl_add_u64 v[230:231], s[36:37], 0, v[134:135]
	s_mov_b32 m0, s43
	s_nop 0
	global_load_lds_dwordx4 v[230:231], off
	s_waitcnt vmcnt(8)
	s_waitcnt lgkmcnt(0)
	s_barrier
	s_setprio 1
	s_waitcnt lgkmcnt(0)
	v_mfma_f32_16x16x32_bf16 v[126:129], v[150:153], v[182:185], v[126:129]
	v_mfma_f32_16x16x32_bf16 v[122:125], v[158:161], v[182:185], v[122:125]
	v_mfma_f32_16x16x32_bf16 v[118:121], v[150:153], v[190:193], v[118:121]
	v_mfma_f32_16x16x32_bf16 v[114:117], v[158:161], v[190:193], v[114:117]
	v_mfma_f32_16x16x32_bf16 v[110:113], v[150:153], v[210:213], v[110:113]
	v_mfma_f32_16x16x32_bf16 v[106:109], v[158:161], v[210:213], v[106:109]
	v_mfma_f32_16x16x32_bf16 v[102:105], v[150:153], v[218:221], v[102:105]
	v_mfma_f32_16x16x32_bf16 v[98:101], v[158:161], v[218:221], v[98:101]
	v_mfma_f32_16x16x32_bf16 v[126:129], v[154:157], v[186:189], v[126:129]
	v_mfma_f32_16x16x32_bf16 v[122:125], v[162:165], v[186:189], v[122:125]
	v_mfma_f32_16x16x32_bf16 v[118:121], v[154:157], v[198:201], v[118:121]
	v_mfma_f32_16x16x32_bf16 v[114:117], v[162:165], v[198:201], v[114:117]
	v_mfma_f32_16x16x32_bf16 v[110:113], v[154:157], v[214:217], v[110:113]
	v_mfma_f32_16x16x32_bf16 v[106:109], v[162:165], v[214:217], v[106:109]
	v_mfma_f32_16x16x32_bf16 v[102:105], v[154:157], v[222:225], v[102:105]
	v_mfma_f32_16x16x32_bf16 v[98:101], v[162:165], v[222:225], v[98:101]
	s_setprio 0
	s_setprio 1
	v_mfma_f32_16x16x32_bf16 v[94:97], v[166:169], v[182:185], v[94:97]
	v_mfma_f32_16x16x32_bf16 v[90:93], v[174:177], v[182:185], v[90:93]
	v_mfma_f32_16x16x32_bf16 v[86:89], v[166:169], v[190:193], v[86:89]
	v_mfma_f32_16x16x32_bf16 v[82:85], v[174:177], v[190:193], v[82:85]
	v_mfma_f32_16x16x32_bf16 v[78:81], v[166:169], v[210:213], v[78:81]
	v_mfma_f32_16x16x32_bf16 v[74:77], v[174:177], v[210:213], v[74:77]
	v_mfma_f32_16x16x32_bf16 v[70:73], v[166:169], v[218:221], v[70:73]
	v_mfma_f32_16x16x32_bf16 v[66:69], v[174:177], v[218:221], v[66:69]
	v_mfma_f32_16x16x32_bf16 v[94:97], v[170:173], v[186:189], v[94:97]
	v_mfma_f32_16x16x32_bf16 v[90:93], v[178:181], v[186:189], v[90:93]
	v_mfma_f32_16x16x32_bf16 v[86:89], v[170:173], v[198:201], v[86:89]
	v_mfma_f32_16x16x32_bf16 v[82:85], v[178:181], v[198:201], v[82:85]
	v_mfma_f32_16x16x32_bf16 v[78:81], v[170:173], v[214:217], v[78:81]
	v_mfma_f32_16x16x32_bf16 v[74:77], v[178:181], v[214:217], v[74:77]
	v_mfma_f32_16x16x32_bf16 v[70:73], v[170:173], v[222:225], v[70:73]
	v_mfma_f32_16x16x32_bf16 v[66:69], v[178:181], v[222:225], v[66:69]
	s_setprio 0
	s_barrier
	s_add_i32 s23, s23, s33
	v_lshl_add_u64 v[202:203], v[202:203], 0, s[10:11]
	s_mov_b32 m0, s23
	ds_read_b128 v[182:185], v148 offset:49152
	ds_read_b128 v[186:189], v148 offset:50176
	ds_read_b128 v[190:193], v148 offset:51200
	ds_read_b128 v[198:201], v148 offset:52224
	ds_read_b128 v[210:213], v148 offset:53248
	ds_read_b128 v[214:217], v148 offset:54272
	ds_read_b128 v[218:221], v148 offset:55296
	ds_read_b128 v[222:225], v148 offset:56320
	global_load_lds_dwordx4 v[202:203], off
	s_add_i32 m0, s23, 0x2000
	s_add_u32 s34, s34, 0x80080
	v_lshl_add_u64 v[202:203], v[206:207], 0, s[10:11]
	s_addc_u32 s35, s35, 0
	s_add_i32 s23, s38, s33
	global_load_lds_dwordx4 v[202:203], off
	v_lshl_add_u64 v[202:203], s[34:35], 0, v[132:133]
	s_mov_b32 m0, s23
	s_nop 0
	global_load_lds_dwordx4 v[202:203], off
	v_lshl_add_u64 v[202:203], s[34:35], 0, v[136:137]
	s_add_i32 m0, s23, 0x2000
	s_nop 0
	global_load_lds_dwordx4 v[202:203], off
	v_lshl_add_u64 v[202:203], v[226:227], 0, s[10:11]
	s_mov_b32 m0, s51
	s_nop 0
	global_load_lds_dwordx4 v[202:203], off
	v_lshl_add_u64 v[202:203], v[228:229], 0, s[10:11]
	s_mov_b32 m0, s52
	s_nop 0
	global_load_lds_dwordx4 v[202:203], off
	s_waitcnt vmcnt(8)
	s_waitcnt lgkmcnt(0)
	s_barrier
	s_setprio 1
	s_waitcnt lgkmcnt(0)
	v_mfma_f32_16x16x32_bf16 v[62:65], v[150:153], v[182:185], v[62:65]
	v_mfma_f32_16x16x32_bf16 v[58:61], v[158:161], v[182:185], v[58:61]
	v_mfma_f32_16x16x32_bf16 v[54:57], v[150:153], v[190:193], v[54:57]
	v_mfma_f32_16x16x32_bf16 v[50:53], v[158:161], v[190:193], v[50:53]
	v_mfma_f32_16x16x32_bf16 v[46:49], v[150:153], v[210:213], v[46:49]
	v_mfma_f32_16x16x32_bf16 v[42:45], v[158:161], v[210:213], v[42:45]
	v_mfma_f32_16x16x32_bf16 v[38:41], v[150:153], v[218:221], v[38:41]
	v_mfma_f32_16x16x32_bf16 v[34:37], v[158:161], v[218:221], v[34:37]
	v_mfma_f32_16x16x32_bf16 v[62:65], v[154:157], v[186:189], v[62:65]
	v_mfma_f32_16x16x32_bf16 v[58:61], v[162:165], v[186:189], v[58:61]
	v_mfma_f32_16x16x32_bf16 v[54:57], v[154:157], v[198:201], v[54:57]
	v_mfma_f32_16x16x32_bf16 v[50:53], v[162:165], v[198:201], v[50:53]
	v_mfma_f32_16x16x32_bf16 v[46:49], v[154:157], v[214:217], v[46:49]
	v_mfma_f32_16x16x32_bf16 v[42:45], v[162:165], v[214:217], v[42:45]
	v_mfma_f32_16x16x32_bf16 v[38:41], v[154:157], v[222:225], v[38:41]
	v_mfma_f32_16x16x32_bf16 v[34:37], v[162:165], v[222:225], v[34:37]
	s_setprio 0
	s_setprio 1
	v_mfma_f32_16x16x32_bf16 v[30:33], v[166:169], v[182:185], v[30:33]
	v_mfma_f32_16x16x32_bf16 v[26:29], v[174:177], v[182:185], v[26:29]
	v_mfma_f32_16x16x32_bf16 v[22:25], v[166:169], v[190:193], v[22:25]
	v_mfma_f32_16x16x32_bf16 v[18:21], v[174:177], v[190:193], v[18:21]
	v_mfma_f32_16x16x32_bf16 v[14:17], v[166:169], v[210:213], v[14:17]
	v_mfma_f32_16x16x32_bf16 v[10:13], v[174:177], v[210:213], v[10:13]
	v_mfma_f32_16x16x32_bf16 v[6:9], v[166:169], v[218:221], v[6:9]
	v_mfma_f32_16x16x32_bf16 v[2:5], v[174:177], v[218:221], v[2:5]
	v_mfma_f32_16x16x32_bf16 v[30:33], v[170:173], v[186:189], v[30:33]
	v_mfma_f32_16x16x32_bf16 v[26:29], v[178:181], v[186:189], v[26:29]
	v_mfma_f32_16x16x32_bf16 v[22:25], v[170:173], v[198:201], v[22:25]
	v_mfma_f32_16x16x32_bf16 v[18:21], v[178:181], v[198:201], v[18:21]
	v_mfma_f32_16x16x32_bf16 v[14:17], v[170:173], v[214:217], v[14:17]
	v_mfma_f32_16x16x32_bf16 v[10:13], v[178:181], v[214:217], v[10:13]
	v_mfma_f32_16x16x32_bf16 v[6:9], v[170:173], v[222:225], v[6:9]
	v_mfma_f32_16x16x32_bf16 v[2:5], v[178:181], v[222:225], v[2:5]
	s_setprio 0
	s_barrier
	s_add_u32 s30, s30, 0x100
	s_addc_u32 s31, s31, 0
	s_add_u32 s19, s19, 0x100
	s_addc_u32 s21, s21, 0
	s_cmp_ge_i32 s29, s68
	s_mov_b32 s23, s29
	s_cbranch_scc0 .LBB0_1973
	s_branch .Lpeeldone_3

.Lpeeldone_3:
	s_and_b64 vcc, exec, s[16:17]
	s_cbranch_vccz .LBB0_1976
	s_barrier

.Lpeel_1:
	ds_read_b128 v[152:155], v148
	ds_read_b128 v[156:159], v148 offset:1024
	ds_read_b128 v[160:163], v148 offset:2048
	ds_read_b128 v[164:167], v148 offset:3072
	ds_read_b128 v[168:171], v149
	ds_read_b128 v[172:175], v149 offset:1024
	ds_read_b128 v[176:179], v149 offset:2048
	ds_read_b128 v[180:183], v149 offset:3072
	s_add_i32 s29, s19, 2
	s_add_u32 s34, s30, 0xfff80080
	s_addc_u32 s35, s31, -1
	s_cmp_eq_u32 s28, s19
	s_cselect_b32 s37, s21, s35
	s_cselect_b32 s36, s20, s34
	s_cselect_b32 s35, s23, s17
	s_cselect_b32 s34, s22, s15
	v_lshl_add_u64 v[144:145], s[30:31], 0, v[140:141]
	s_add_i32 m0, s27, 0xc000
	ds_read_b128 v[184:187], v150
	ds_read_b128 v[188:191], v150 offset:1024
	ds_read_b128 v[192:195], v150 offset:2048
	ds_read_b128 v[198:201], v150 offset:3072
	ds_read_b128 v[210:213], v150 offset:4096
	ds_read_b128 v[214:217], v150 offset:5120
	ds_read_b128 v[218:221], v150 offset:6144
	ds_read_b128 v[222:225], v150 offset:7168
	global_load_lds_dwordx4 v[144:145], off
	v_lshl_add_u64 v[144:145], s[30:31], 0, v[142:143]
	s_add_i32 m0, s27, 0xe000
	s_nop 0
	global_load_lds_dwordx4 v[144:145], off
	s_waitcnt vmcnt(8)
	s_waitcnt lgkmcnt(0)
	s_barrier
	s_setprio 1
	s_waitcnt lgkmcnt(0)
	v_mfma_f32_16x16x32_bf16 v[126:129], v[152:155], v[184:187], 0
	v_mfma_f32_16x16x32_bf16 v[122:125], v[160:163], v[184:187], 0
	v_mfma_f32_16x16x32_bf16 v[110:113], v[152:155], v[192:195], 0
	v_mfma_f32_16x16x32_bf16 v[106:109], v[160:163], v[192:195], 0
	v_mfma_f32_16x16x32_bf16 v[94:97], v[152:155], v[210:213], 0
	v_mfma_f32_16x16x32_bf16 v[90:93], v[160:163], v[210:213], 0
	v_mfma_f32_16x16x32_bf16 v[78:81], v[152:155], v[218:221], 0
	v_mfma_f32_16x16x32_bf16 v[74:77], v[160:163], v[218:221], 0
	v_mfma_f32_16x16x32_bf16 v[126:129], v[156:159], v[188:191], v[126:129]
	v_mfma_f32_16x16x32_bf16 v[122:125], v[164:167], v[188:191], v[122:125]
	v_mfma_f32_16x16x32_bf16 v[110:113], v[156:159], v[198:201], v[110:113]
	v_mfma_f32_16x16x32_bf16 v[106:109], v[164:167], v[198:201], v[106:109]
	v_mfma_f32_16x16x32_bf16 v[94:97], v[156:159], v[214:217], v[94:97]
	v_mfma_f32_16x16x32_bf16 v[90:93], v[164:167], v[214:217], v[90:93]
	v_mfma_f32_16x16x32_bf16 v[78:81], v[156:159], v[222:225], v[78:81]
	v_mfma_f32_16x16x32_bf16 v[74:77], v[164:167], v[222:225], v[74:77]
	s_setprio 0
	s_setprio 1
	v_mfma_f32_16x16x32_bf16 v[118:121], v[168:171], v[184:187], 0
	v_mfma_f32_16x16x32_bf16 v[114:117], v[176:179], v[184:187], 0
	v_mfma_f32_16x16x32_bf16 v[102:105], v[168:171], v[192:195], 0
	v_mfma_f32_16x16x32_bf16 v[98:101], v[176:179], v[192:195], 0
	v_mfma_f32_16x16x32_bf16 v[86:89], v[168:171], v[210:213], 0
	v_mfma_f32_16x16x32_bf16 v[82:85], v[176:179], v[210:213], 0
	v_mfma_f32_16x16x32_bf16 v[70:73], v[168:171], v[218:221], 0
	v_mfma_f32_16x16x32_bf16 v[66:69], v[176:179], v[218:221], 0
	v_mfma_f32_16x16x32_bf16 v[118:121], v[172:175], v[188:191], v[118:121]
	v_mfma_f32_16x16x32_bf16 v[114:117], v[180:183], v[188:191], v[114:117]
	v_mfma_f32_16x16x32_bf16 v[102:105], v[172:175], v[198:201], v[102:105]
	v_mfma_f32_16x16x32_bf16 v[98:101], v[180:183], v[198:201], v[98:101]
	v_mfma_f32_16x16x32_bf16 v[86:89], v[172:175], v[214:217], v[86:89]
	v_mfma_f32_16x16x32_bf16 v[82:85], v[180:183], v[214:217], v[82:85]
	v_mfma_f32_16x16x32_bf16 v[70:73], v[172:175], v[222:225], v[70:73]
	v_mfma_f32_16x16x32_bf16 v[66:69], v[180:183], v[222:225], v[66:69]
	s_setprio 0
	s_barrier
	s_add_i32 s19, s60, s33
	v_lshl_add_u64 v[144:145], s[34:35], 0, v[132:133]
	s_mov_b32 m0, s19
	ds_read_b128 v[184:187], v150 offset:16384
	ds_read_b128 v[188:191], v150 offset:17408
	ds_read_b128 v[192:195], v150 offset:18432
	ds_read_b128 v[198:201], v150 offset:19456
	ds_read_b128 v[210:213], v150 offset:20480
	ds_read_b128 v[214:217], v150 offset:21504
	ds_read_b128 v[218:221], v150 offset:22528
	ds_read_b128 v[222:225], v150 offset:23552
	global_load_lds_dwordx4 v[144:145], off
	s_add_i32 m0, s19, 0x2000
	s_add_u32 s38, s34, 0x80000
	v_lshl_add_u64 v[202:203], s[34:35], 0, v[136:137]
	s_addc_u32 s39, s35, 0
	s_add_i32 s19, s61, s33
	global_load_lds_dwordx4 v[202:203], off
	v_lshl_add_u64 v[206:207], s[38:39], 0, v[132:133]
	s_mov_b32 m0, s19
	v_lshl_add_u64 v[226:227], s[36:37], 0, v[134:135]
	global_load_lds_dwordx4 v[206:207], off
	v_lshl_add_u64 v[206:207], s[38:39], 0, v[136:137]
	s_add_i32 m0, s19, 0x2000
	s_nop 0
	global_load_lds_dwordx4 v[206:207], off
	v_lshl_add_u64 v[206:207], s[36:37], 0, v[130:131]
	s_mov_b32 m0, s27
	s_nop 0
	global_load_lds_dwordx4 v[206:207], off
	s_mov_b32 m0, s41
	s_nop 0
	global_load_lds_dwordx4 v[226:227], off
	s_waitcnt vmcnt(8)
	s_waitcnt lgkmcnt(0)
	s_barrier
	s_setprio 1
	s_waitcnt lgkmcnt(0)
	v_mfma_f32_16x16x32_bf16 v[62:65], v[152:155], v[184:187], 0
	v_mfma_f32_16x16x32_bf16 v[58:61], v[160:163], v[184:187], 0
	v_mfma_f32_16x16x32_bf16 v[46:49], v[152:155], v[192:195], 0
	v_mfma_f32_16x16x32_bf16 v[42:45], v[160:163], v[192:195], 0
	v_mfma_f32_16x16x32_bf16 v[30:33], v[152:155], v[210:213], 0
	v_mfma_f32_16x16x32_bf16 v[26:29], v[160:163], v[210:213], 0
	v_mfma_f32_16x16x32_bf16 v[14:17], v[152:155], v[218:221], 0
	v_mfma_f32_16x16x32_bf16 v[10:13], v[160:163], v[218:221], 0
	v_mfma_f32_16x16x32_bf16 v[62:65], v[156:159], v[188:191], v[62:65]
	v_mfma_f32_16x16x32_bf16 v[58:61], v[164:167], v[188:191], v[58:61]
	v_mfma_f32_16x16x32_bf16 v[46:49], v[156:159], v[198:201], v[46:49]
	v_mfma_f32_16x16x32_bf16 v[42:45], v[164:167], v[198:201], v[42:45]
	v_mfma_f32_16x16x32_bf16 v[30:33], v[156:159], v[214:217], v[30:33]
	v_mfma_f32_16x16x32_bf16 v[26:29], v[164:167], v[214:217], v[26:29]
	v_mfma_f32_16x16x32_bf16 v[14:17], v[156:159], v[222:225], v[14:17]
	v_mfma_f32_16x16x32_bf16 v[10:13], v[164:167], v[222:225], v[10:13]
	s_setprio 0
	s_setprio 1
	v_mfma_f32_16x16x32_bf16 v[54:57], v[168:171], v[184:187], 0
	v_mfma_f32_16x16x32_bf16 v[50:53], v[176:179], v[184:187], 0
	v_mfma_f32_16x16x32_bf16 v[38:41], v[168:171], v[192:195], 0
	v_mfma_f32_16x16x32_bf16 v[34:37], v[176:179], v[192:195], 0
	v_mfma_f32_16x16x32_bf16 v[22:25], v[168:171], v[210:213], 0
	v_mfma_f32_16x16x32_bf16 v[18:21], v[176:179], v[210:213], 0
	v_mfma_f32_16x16x32_bf16 v[6:9], v[168:171], v[218:221], 0
	v_mfma_f32_16x16x32_bf16 v[2:5], v[176:179], v[218:221], 0
	v_mfma_f32_16x16x32_bf16 v[54:57], v[172:175], v[188:191], v[54:57]
	v_mfma_f32_16x16x32_bf16 v[50:53], v[180:183], v[188:191], v[50:53]
	v_mfma_f32_16x16x32_bf16 v[38:41], v[172:175], v[198:201], v[38:41]
	v_mfma_f32_16x16x32_bf16 v[34:37], v[180:183], v[198:201], v[34:37]
	v_mfma_f32_16x16x32_bf16 v[22:25], v[172:175], v[214:217], v[22:25]
	v_mfma_f32_16x16x32_bf16 v[18:21], v[180:183], v[214:217], v[18:21]
	v_mfma_f32_16x16x32_bf16 v[6:9], v[172:175], v[222:225], v[6:9]
	v_mfma_f32_16x16x32_bf16 v[2:5], v[180:183], v[222:225], v[2:5]
	s_setprio 0
	s_barrier
	s_add_i32 s19, 0, 0x18000
	v_add_u32_e32 v151, s19, v146
	s_add_i32 s38, 0, 0x1c000
	ds_read_b128 v[152:155], v151
	ds_read_b128 v[156:159], v151 offset:1024
	ds_read_b128 v[160:163], v151 offset:2048
	ds_read_b128 v[164:167], v151 offset:3072
	v_add_u32_e32 v151, s38, v146
	ds_read_b128 v[168:171], v151
	ds_read_b128 v[172:175], v151 offset:1024
	ds_read_b128 v[176:179], v151 offset:2048
	ds_read_b128 v[180:183], v151 offset:3072
	s_add_u32 s36, s36, 0x80000
	s_addc_u32 s37, s37, 0
	s_mov_b32 m0, s42
	v_lshl_add_u64 v[228:229], s[36:37], 0, v[130:131]
	ds_read_b128 v[184:187], v150 offset:32768
	ds_read_b128 v[188:191], v150 offset:33792
	ds_read_b128 v[192:195], v150 offset:34816
	ds_read_b128 v[198:201], v150 offset:35840
	ds_read_b128 v[210:213], v150 offset:36864
	ds_read_b128 v[214:217], v150 offset:37888
	ds_read_b128 v[218:221], v150 offset:38912
	ds_read_b128 v[222:225], v150 offset:39936
	global_load_lds_dwordx4 v[228:229], off
	v_lshl_add_u64 v[228:229], s[36:37], 0, v[134:135]
	s_mov_b32 m0, s43
	s_nop 0
	global_load_lds_dwordx4 v[228:229], off
	s_waitcnt vmcnt(8)
	s_waitcnt lgkmcnt(0)
	s_barrier
	s_setprio 1
	s_waitcnt lgkmcnt(0)
	v_mfma_f32_16x16x32_bf16 v[126:129], v[152:155], v[184:187], v[126:129]
	v_mfma_f32_16x16x32_bf16 v[122:125], v[160:163], v[184:187], v[122:125]
	v_mfma_f32_16x16x32_bf16 v[110:113], v[152:155], v[192:195], v[110:113]
	v_mfma_f32_16x16x32_bf16 v[106:109], v[160:163], v[192:195], v[106:109]
	v_mfma_f32_16x16x32_bf16 v[94:97], v[152:155], v[210:213], v[94:97]
	v_mfma_f32_16x16x32_bf16 v[90:93], v[160:163], v[210:213], v[90:93]
	v_mfma_f32_16x16x32_bf16 v[78:81], v[152:155], v[218:221], v[78:81]
	v_mfma_f32_16x16x32_bf16 v[74:77], v[160:163], v[218:221], v[74:77]
	v_mfma_f32_16x16x32_bf16 v[126:129], v[156:159], v[188:191], v[126:129]
	v_mfma_f32_16x16x32_bf16 v[122:125], v[164:167], v[188:191], v[122:125]
	v_mfma_f32_16x16x32_bf16 v[110:113], v[156:159], v[198:201], v[110:113]
	v_mfma_f32_16x16x32_bf16 v[106:109], v[164:167], v[198:201], v[106:109]
	v_mfma_f32_16x16x32_bf16 v[94:97], v[156:159], v[214:217], v[94:97]
	v_mfma_f32_16x16x32_bf16 v[90:93], v[164:167], v[214:217], v[90:93]
	v_mfma_f32_16x16x32_bf16 v[78:81], v[156:159], v[222:225], v[78:81]
	v_mfma_f32_16x16x32_bf16 v[74:77], v[164:167], v[222:225], v[74:77]
	s_setprio 0
	s_setprio 1
	v_mfma_f32_16x16x32_bf16 v[118:121], v[168:171], v[184:187], v[118:121]
	v_mfma_f32_16x16x32_bf16 v[114:117], v[176:179], v[184:187], v[114:117]
	v_mfma_f32_16x16x32_bf16 v[102:105], v[168:171], v[192:195], v[102:105]
	v_mfma_f32_16x16x32_bf16 v[98:101], v[176:179], v[192:195], v[98:101]
	v_mfma_f32_16x16x32_bf16 v[86:89], v[168:171], v[210:213], v[86:89]
	v_mfma_f32_16x16x32_bf16 v[82:85], v[176:179], v[210:213], v[82:85]
	v_mfma_f32_16x16x32_bf16 v[70:73], v[168:171], v[218:221], v[70:73]
	v_mfma_f32_16x16x32_bf16 v[66:69], v[176:179], v[218:221], v[66:69]
	v_mfma_f32_16x16x32_bf16 v[118:121], v[172:175], v[188:191], v[118:121]
	v_mfma_f32_16x16x32_bf16 v[114:117], v[180:183], v[188:191], v[114:117]
	v_mfma_f32_16x16x32_bf16 v[102:105], v[172:175], v[198:201], v[102:105]
	v_mfma_f32_16x16x32_bf16 v[98:101], v[180:183], v[198:201], v[98:101]
	v_mfma_f32_16x16x32_bf16 v[86:89], v[172:175], v[214:217], v[86:89]
	v_mfma_f32_16x16x32_bf16 v[82:85], v[180:183], v[214:217], v[82:85]
	v_mfma_f32_16x16x32_bf16 v[70:73], v[172:175], v[222:225], v[70:73]
	v_mfma_f32_16x16x32_bf16 v[66:69], v[180:183], v[222:225], v[66:69]
	s_setprio 0
	s_barrier
	s_add_i32 s19, s19, s33
	v_lshl_add_u64 v[144:145], v[144:145], 0, s[10:11]
	s_mov_b32 m0, s19
	ds_read_b128 v[184:187], v150 offset:49152
	ds_read_b128 v[188:191], v150 offset:50176
	ds_read_b128 v[192:195], v150 offset:51200
	ds_read_b128 v[198:201], v150 offset:52224
	ds_read_b128 v[210:213], v150 offset:53248
	ds_read_b128 v[214:217], v150 offset:54272
	ds_read_b128 v[218:221], v150 offset:55296
	ds_read_b128 v[222:225], v150 offset:56320
	global_load_lds_dwordx4 v[144:145], off
	s_add_i32 m0, s19, 0x2000
	s_add_u32 s34, s34, 0x80080
	v_lshl_add_u64 v[144:145], v[202:203], 0, s[10:11]
	s_addc_u32 s35, s35, 0
	s_add_i32 s19, s38, s33
	global_load_lds_dwordx4 v[144:145], off
	v_lshl_add_u64 v[144:145], s[34:35], 0, v[132:133]
	s_mov_b32 m0, s19
	s_nop 0
	global_load_lds_dwordx4 v[144:145], off
	v_lshl_add_u64 v[144:145], s[34:35], 0, v[136:137]
	s_add_i32 m0, s19, 0x2000
	s_nop 0
	global_load_lds_dwordx4 v[144:145], off
	v_lshl_add_u64 v[144:145], v[206:207], 0, s[10:11]
	s_mov_b32 m0, s51
	s_nop 0
	global_load_lds_dwordx4 v[144:145], off
	v_lshl_add_u64 v[144:145], v[226:227], 0, s[10:11]
	s_mov_b32 m0, s52
	s_nop 0
	global_load_lds_dwordx4 v[144:145], off
	s_waitcnt vmcnt(8)
	s_waitcnt lgkmcnt(0)
	s_barrier
	s_setprio 1
	s_waitcnt lgkmcnt(0)
	v_mfma_f32_16x16x32_bf16 v[62:65], v[152:155], v[184:187], v[62:65]
	v_mfma_f32_16x16x32_bf16 v[58:61], v[160:163], v[184:187], v[58:61]
	v_mfma_f32_16x16x32_bf16 v[46:49], v[152:155], v[192:195], v[46:49]
	v_mfma_f32_16x16x32_bf16 v[42:45], v[160:163], v[192:195], v[42:45]
	v_mfma_f32_16x16x32_bf16 v[30:33], v[152:155], v[210:213], v[30:33]
	v_mfma_f32_16x16x32_bf16 v[26:29], v[160:163], v[210:213], v[26:29]
	v_mfma_f32_16x16x32_bf16 v[14:17], v[152:155], v[218:221], v[14:17]
	v_mfma_f32_16x16x32_bf16 v[10:13], v[160:163], v[218:221], v[10:13]
	v_mfma_f32_16x16x32_bf16 v[62:65], v[156:159], v[188:191], v[62:65]
	v_mfma_f32_16x16x32_bf16 v[58:61], v[164:167], v[188:191], v[58:61]
	v_mfma_f32_16x16x32_bf16 v[46:49], v[156:159], v[198:201], v[46:49]
	v_mfma_f32_16x16x32_bf16 v[42:45], v[164:167], v[198:201], v[42:45]
	v_mfma_f32_16x16x32_bf16 v[30:33], v[156:159], v[214:217], v[30:33]
	v_mfma_f32_16x16x32_bf16 v[26:29], v[164:167], v[214:217], v[26:29]
	v_mfma_f32_16x16x32_bf16 v[14:17], v[156:159], v[222:225], v[14:17]
	v_mfma_f32_16x16x32_bf16 v[10:13], v[164:167], v[222:225], v[10:13]
	s_setprio 0
	s_setprio 1
	v_mfma_f32_16x16x32_bf16 v[54:57], v[168:171], v[184:187], v[54:57]
	v_mfma_f32_16x16x32_bf16 v[50:53], v[176:179], v[184:187], v[50:53]
	v_mfma_f32_16x16x32_bf16 v[38:41], v[168:171], v[192:195], v[38:41]
	v_mfma_f32_16x16x32_bf16 v[34:37], v[176:179], v[192:195], v[34:37]
	v_mfma_f32_16x16x32_bf16 v[22:25], v[168:171], v[210:213], v[22:25]
	v_mfma_f32_16x16x32_bf16 v[18:21], v[176:179], v[210:213], v[18:21]
	v_mfma_f32_16x16x32_bf16 v[6:9], v[168:171], v[218:221], v[6:9]
	v_mfma_f32_16x16x32_bf16 v[2:5], v[176:179], v[218:221], v[2:5]
	v_mfma_f32_16x16x32_bf16 v[54:57], v[172:175], v[188:191], v[54:57]
	v_mfma_f32_16x16x32_bf16 v[50:53], v[180:183], v[188:191], v[50:53]
	v_mfma_f32_16x16x32_bf16 v[38:41], v[172:175], v[198:201], v[38:41]
	v_mfma_f32_16x16x32_bf16 v[34:37], v[180:183], v[198:201], v[34:37]
	v_mfma_f32_16x16x32_bf16 v[22:25], v[172:175], v[214:217], v[22:25]
	v_mfma_f32_16x16x32_bf16 v[18:21], v[180:183], v[214:217], v[18:21]
	v_mfma_f32_16x16x32_bf16 v[6:9], v[172:175], v[222:225], v[6:9]
	v_mfma_f32_16x16x32_bf16 v[2:5], v[180:183], v[222:225], v[2:5]
	s_setprio 0
	s_barrier
	s_add_u32 s30, s30, 0x100
	s_addc_u32 s31, s31, 0
	s_add_u32 s15, s15, 0x100
	s_addc_u32 s17, s17, 0
	s_cmp_ge_i32 s29, s68
	s_mov_b32 s19, s29
	s_cbranch_scc0 .LBB0_2547
	s_branch .Lpeeldone_1

.Lpeel_0:
	ds_read_b128 v[144:147], v170
	ds_read_b128 v[148:151], v170 offset:1024
	ds_read_b128 v[152:155], v170 offset:2048
	ds_read_b128 v[156:159], v170 offset:3072
	ds_read_b128 v[160:163], v171
	ds_read_b128 v[164:167], v171 offset:1024
	ds_read_b128 v[174:177], v171 offset:2048
	ds_read_b128 v[178:181], v171 offset:3072
	s_add_i32 s30, s26, 2
	s_add_u32 s27, s24, 0xffea0080
	s_addc_u32 s28, s25, -1
	s_cmp_eq_u32 s22, s26
	s_cselect_b32 s26, s20, s17
	s_cselect_b32 s29, s19, s28
	s_cselect_b32 s28, s18, s27
	s_cselect_b32 s27, s21, s23
	v_lshl_add_u64 v[214:215], s[24:25], 0, v[140:141]
	s_add_i32 m0, s34, 0xc000
	ds_read_b128 v[182:185], v172
	ds_read_b128 v[186:189], v172 offset:1024
	ds_read_b128 v[190:193], v172 offset:2048
	ds_read_b128 v[194:197], v172 offset:3072
	ds_read_b128 v[198:201], v172 offset:4096
	ds_read_b128 v[202:205], v172 offset:5120
	ds_read_b128 v[206:209], v172 offset:6144
	ds_read_b128 v[210:213], v172 offset:7168
	global_load_lds_dwordx4 v[214:215], off
	v_lshl_add_u64 v[214:215], s[24:25], 0, v[142:143]
	s_add_i32 m0, s34, 0xe000
	s_nop 0
	global_load_lds_dwordx4 v[214:215], off
	s_waitcnt vmcnt(8)
	s_waitcnt lgkmcnt(0)
	s_barrier
	s_setprio 1
	s_waitcnt lgkmcnt(0)
	v_mfma_f32_16x16x32_bf16 v[126:129], v[144:147], v[182:185], 0
	v_mfma_f32_16x16x32_bf16 v[122:125], v[152:155], v[182:185], 0
	v_mfma_f32_16x16x32_bf16 v[118:121], v[144:147], v[190:193], 0
	v_mfma_f32_16x16x32_bf16 v[110:113], v[152:155], v[190:193], 0
	v_mfma_f32_16x16x32_bf16 v[94:97], v[144:147], v[198:201], 0
	v_mfma_f32_16x16x32_bf16 v[90:93], v[152:155], v[198:201], 0
	v_mfma_f32_16x16x32_bf16 v[82:85], v[144:147], v[206:209], 0
	v_mfma_f32_16x16x32_bf16 v[74:77], v[152:155], v[206:209], 0
	v_mfma_f32_16x16x32_bf16 v[126:129], v[148:151], v[186:189], v[126:129]
	v_mfma_f32_16x16x32_bf16 v[122:125], v[156:159], v[186:189], v[122:125]
	v_mfma_f32_16x16x32_bf16 v[118:121], v[148:151], v[194:197], v[118:121]
	v_mfma_f32_16x16x32_bf16 v[110:113], v[156:159], v[194:197], v[110:113]
	v_mfma_f32_16x16x32_bf16 v[94:97], v[148:151], v[202:205], v[94:97]
	v_mfma_f32_16x16x32_bf16 v[90:93], v[156:159], v[202:205], v[90:93]
	v_mfma_f32_16x16x32_bf16 v[82:85], v[148:151], v[210:213], v[82:85]
	v_mfma_f32_16x16x32_bf16 v[74:77], v[156:159], v[210:213], v[74:77]
	s_setprio 0
	s_setprio 1
	v_mfma_f32_16x16x32_bf16 v[114:117], v[160:163], v[182:185], 0
	v_mfma_f32_16x16x32_bf16 v[106:109], v[174:177], v[182:185], 0
	v_mfma_f32_16x16x32_bf16 v[102:105], v[160:163], v[190:193], 0
	v_mfma_f32_16x16x32_bf16 v[98:101], v[174:177], v[190:193], 0
	v_mfma_f32_16x16x32_bf16 v[86:89], v[160:163], v[198:201], 0
	v_mfma_f32_16x16x32_bf16 v[78:81], v[174:177], v[198:201], 0
	v_mfma_f32_16x16x32_bf16 v[70:73], v[160:163], v[206:209], 0
	v_mfma_f32_16x16x32_bf16 v[66:69], v[174:177], v[206:209], 0
	v_mfma_f32_16x16x32_bf16 v[114:117], v[164:167], v[186:189], v[114:117]
	v_mfma_f32_16x16x32_bf16 v[106:109], v[178:181], v[186:189], v[106:109]
	v_mfma_f32_16x16x32_bf16 v[102:105], v[164:167], v[194:197], v[102:105]
	v_mfma_f32_16x16x32_bf16 v[98:101], v[178:181], v[194:197], v[98:101]
	v_mfma_f32_16x16x32_bf16 v[86:89], v[164:167], v[202:205], v[86:89]
	v_mfma_f32_16x16x32_bf16 v[78:81], v[178:181], v[202:205], v[78:81]
	v_mfma_f32_16x16x32_bf16 v[70:73], v[164:167], v[210:213], v[70:73]
	v_mfma_f32_16x16x32_bf16 v[66:69], v[178:181], v[210:213], v[66:69]
	s_setprio 0
	s_barrier
	s_add_i32 s31, s57, s33
	v_lshl_add_u64 v[214:215], s[26:27], 0, v[132:133]
	s_mov_b32 m0, s31
	ds_read_b128 v[182:185], v172 offset:16384
	ds_read_b128 v[186:189], v172 offset:17408
	ds_read_b128 v[190:193], v172 offset:18432
	ds_read_b128 v[194:197], v172 offset:19456
	ds_read_b128 v[198:201], v172 offset:20480
	ds_read_b128 v[202:205], v172 offset:21504
	ds_read_b128 v[206:209], v172 offset:22528
	ds_read_b128 v[210:213], v172 offset:23552
	global_load_lds_dwordx4 v[214:215], off
	s_add_i32 m0, s31, 0x2000
	s_add_u32 s68, s26, 0x160000
	v_lshl_add_u64 v[216:217], s[26:27], 0, v[136:137]
	s_addc_u32 s69, s27, 0
	s_add_i32 s31, s58, s33
	global_load_lds_dwordx4 v[216:217], off
	v_lshl_add_u64 v[218:219], s[68:69], 0, v[132:133]
	s_mov_b32 m0, s31
	v_lshl_add_u64 v[220:221], s[28:29], 0, v[134:135]
	global_load_lds_dwordx4 v[218:219], off
	v_lshl_add_u64 v[218:219], s[68:69], 0, v[136:137]
	s_add_i32 m0, s31, 0x2000
	s_nop 0
	global_load_lds_dwordx4 v[218:219], off
	v_lshl_add_u64 v[218:219], s[28:29], 0, v[130:131]
	s_mov_b32 m0, s34
	s_nop 0
	global_load_lds_dwordx4 v[218:219], off
	s_mov_b32 m0, s35
	s_nop 0
	global_load_lds_dwordx4 v[220:221], off
	s_waitcnt vmcnt(8)
	s_waitcnt lgkmcnt(0)
	s_barrier
	s_setprio 1
	s_waitcnt lgkmcnt(0)
	v_mfma_f32_16x16x32_bf16 v[62:65], v[144:147], v[182:185], 0
	v_mfma_f32_16x16x32_bf16 v[58:61], v[152:155], v[182:185], 0
	v_mfma_f32_16x16x32_bf16 v[50:53], v[144:147], v[190:193], 0
	v_mfma_f32_16x16x32_bf16 v[42:45], v[152:155], v[190:193], 0
	v_mfma_f32_16x16x32_bf16 v[30:33], v[144:147], v[198:201], 0
	v_mfma_f32_16x16x32_bf16 v[26:29], v[152:155], v[198:201], 0
	v_mfma_f32_16x16x32_bf16 v[18:21], v[144:147], v[206:209], 0
	v_mfma_f32_16x16x32_bf16 v[10:13], v[152:155], v[206:209], 0
	v_mfma_f32_16x16x32_bf16 v[62:65], v[148:151], v[186:189], v[62:65]
	v_mfma_f32_16x16x32_bf16 v[58:61], v[156:159], v[186:189], v[58:61]
	v_mfma_f32_16x16x32_bf16 v[50:53], v[148:151], v[194:197], v[50:53]
	v_mfma_f32_16x16x32_bf16 v[42:45], v[156:159], v[194:197], v[42:45]
	v_mfma_f32_16x16x32_bf16 v[30:33], v[148:151], v[202:205], v[30:33]
	v_mfma_f32_16x16x32_bf16 v[26:29], v[156:159], v[202:205], v[26:29]
	v_mfma_f32_16x16x32_bf16 v[18:21], v[148:151], v[210:213], v[18:21]
	v_mfma_f32_16x16x32_bf16 v[10:13], v[156:159], v[210:213], v[10:13]
	s_setprio 0
	s_setprio 1
	v_mfma_f32_16x16x32_bf16 v[54:57], v[160:163], v[182:185], 0
	v_mfma_f32_16x16x32_bf16 v[46:49], v[174:177], v[182:185], 0
	v_mfma_f32_16x16x32_bf16 v[38:41], v[160:163], v[190:193], 0
	v_mfma_f32_16x16x32_bf16 v[34:37], v[174:177], v[190:193], 0
	v_mfma_f32_16x16x32_bf16 v[22:25], v[160:163], v[198:201], 0
	v_mfma_f32_16x16x32_bf16 v[14:17], v[174:177], v[198:201], 0
	v_mfma_f32_16x16x32_bf16 v[6:9], v[160:163], v[206:209], 0
	v_mfma_f32_16x16x32_bf16 v[2:5], v[174:177], v[206:209], 0
	v_mfma_f32_16x16x32_bf16 v[54:57], v[164:167], v[186:189], v[54:57]
	v_mfma_f32_16x16x32_bf16 v[46:49], v[178:181], v[186:189], v[46:49]
	v_mfma_f32_16x16x32_bf16 v[38:41], v[164:167], v[194:197], v[38:41]
	v_mfma_f32_16x16x32_bf16 v[34:37], v[178:181], v[194:197], v[34:37]
	v_mfma_f32_16x16x32_bf16 v[22:25], v[164:167], v[202:205], v[22:25]
	v_mfma_f32_16x16x32_bf16 v[14:17], v[178:181], v[202:205], v[14:17]
	v_mfma_f32_16x16x32_bf16 v[6:9], v[164:167], v[210:213], v[6:9]
	v_mfma_f32_16x16x32_bf16 v[2:5], v[178:181], v[210:213], v[2:5]
	s_setprio 0
	s_barrier
	s_add_i32 s31, 0, 0x18000
	s_add_i32 s68, 0, 0x1c000
	v_add_u32_e32 v156, s31, v168
	v_add_u32_e32 v173, s68, v168
	ds_read_b128 v[144:147], v156
	ds_read_b128 v[148:151], v156 offset:1024
	ds_read_b128 v[152:155], v156 offset:2048
	ds_read_b128 v[156:159], v156 offset:3072
	ds_read_b128 v[160:163], v173
	ds_read_b128 v[164:167], v173 offset:1024
	ds_read_b128 v[174:177], v173 offset:2048
	ds_read_b128 v[178:181], v173 offset:3072
	s_add_u32 s28, s28, 0x160000
	s_addc_u32 s29, s29, 0
	s_mov_b32 m0, s36
	v_lshl_add_u64 v[222:223], s[28:29], 0, v[130:131]
	ds_read_b128 v[182:185], v172 offset:32768
	ds_read_b128 v[186:189], v172 offset:33792
	ds_read_b128 v[190:193], v172 offset:34816
	ds_read_b128 v[194:197], v172 offset:35840
	ds_read_b128 v[198:201], v172 offset:36864
	ds_read_b128 v[202:205], v172 offset:37888
	ds_read_b128 v[206:209], v172 offset:38912
	ds_read_b128 v[210:213], v172 offset:39936
	global_load_lds_dwordx4 v[222:223], off
	v_lshl_add_u64 v[222:223], s[28:29], 0, v[134:135]
	s_mov_b32 m0, s37
	s_nop 0
	global_load_lds_dwordx4 v[222:223], off
	s_waitcnt vmcnt(8)
	s_waitcnt lgkmcnt(0)
	s_barrier
	s_setprio 1
	s_waitcnt lgkmcnt(0)
	v_mfma_f32_16x16x32_bf16 v[126:129], v[144:147], v[182:185], v[126:129]
	v_mfma_f32_16x16x32_bf16 v[122:125], v[152:155], v[182:185], v[122:125]
	v_mfma_f32_16x16x32_bf16 v[118:121], v[144:147], v[190:193], v[118:121]
	v_mfma_f32_16x16x32_bf16 v[110:113], v[152:155], v[190:193], v[110:113]
	v_mfma_f32_16x16x32_bf16 v[94:97], v[144:147], v[198:201], v[94:97]
	v_mfma_f32_16x16x32_bf16 v[90:93], v[152:155], v[198:201], v[90:93]
	v_mfma_f32_16x16x32_bf16 v[82:85], v[144:147], v[206:209], v[82:85]
	v_mfma_f32_16x16x32_bf16 v[74:77], v[152:155], v[206:209], v[74:77]
	v_mfma_f32_16x16x32_bf16 v[126:129], v[148:151], v[186:189], v[126:129]
	v_mfma_f32_16x16x32_bf16 v[122:125], v[156:159], v[186:189], v[122:125]
	v_mfma_f32_16x16x32_bf16 v[118:121], v[148:151], v[194:197], v[118:121]
	v_mfma_f32_16x16x32_bf16 v[110:113], v[156:159], v[194:197], v[110:113]
	v_mfma_f32_16x16x32_bf16 v[94:97], v[148:151], v[202:205], v[94:97]
	v_mfma_f32_16x16x32_bf16 v[90:93], v[156:159], v[202:205], v[90:93]
	v_mfma_f32_16x16x32_bf16 v[82:85], v[148:151], v[210:213], v[82:85]
	v_mfma_f32_16x16x32_bf16 v[74:77], v[156:159], v[210:213], v[74:77]
	s_setprio 0
	s_setprio 1
	v_mfma_f32_16x16x32_bf16 v[114:117], v[160:163], v[182:185], v[114:117]
	v_mfma_f32_16x16x32_bf16 v[106:109], v[174:177], v[182:185], v[106:109]
	v_mfma_f32_16x16x32_bf16 v[102:105], v[160:163], v[190:193], v[102:105]
	v_mfma_f32_16x16x32_bf16 v[98:101], v[174:177], v[190:193], v[98:101]
	v_mfma_f32_16x16x32_bf16 v[86:89], v[160:163], v[198:201], v[86:89]
	v_mfma_f32_16x16x32_bf16 v[78:81], v[174:177], v[198:201], v[78:81]
	v_mfma_f32_16x16x32_bf16 v[70:73], v[160:163], v[206:209], v[70:73]
	v_mfma_f32_16x16x32_bf16 v[66:69], v[174:177], v[206:209], v[66:69]
	v_mfma_f32_16x16x32_bf16 v[114:117], v[164:167], v[186:189], v[114:117]
	v_mfma_f32_16x16x32_bf16 v[106:109], v[178:181], v[186:189], v[106:109]
	v_mfma_f32_16x16x32_bf16 v[102:105], v[164:167], v[194:197], v[102:105]
	v_mfma_f32_16x16x32_bf16 v[98:101], v[178:181], v[194:197], v[98:101]
	v_mfma_f32_16x16x32_bf16 v[86:89], v[164:167], v[202:205], v[86:89]
	v_mfma_f32_16x16x32_bf16 v[78:81], v[178:181], v[202:205], v[78:81]
	v_mfma_f32_16x16x32_bf16 v[70:73], v[164:167], v[210:213], v[70:73]
	v_mfma_f32_16x16x32_bf16 v[66:69], v[178:181], v[210:213], v[66:69]
	s_setprio 0
	s_barrier
	s_add_i32 s28, s31, s33
	v_lshl_add_u64 v[214:215], v[214:215], 0, s[12:13]
	s_mov_b32 m0, s28
	ds_read_b128 v[182:185], v172 offset:49152
	ds_read_b128 v[186:189], v172 offset:50176
	ds_read_b128 v[190:193], v172 offset:51200
	ds_read_b128 v[194:197], v172 offset:52224
	ds_read_b128 v[198:201], v172 offset:53248
	ds_read_b128 v[202:205], v172 offset:54272
	ds_read_b128 v[206:209], v172 offset:55296
	ds_read_b128 v[210:213], v172 offset:56320
	global_load_lds_dwordx4 v[214:215], off
	s_add_i32 m0, s28, 0x2000
	s_add_u32 s26, s26, 0x160080
	v_lshl_add_u64 v[214:215], v[216:217], 0, s[12:13]
	s_addc_u32 s27, s27, 0
	s_add_i32 s28, s68, s33
	global_load_lds_dwordx4 v[214:215], off
	v_lshl_add_u64 v[214:215], s[26:27], 0, v[132:133]
	s_mov_b32 m0, s28
	s_nop 0
	global_load_lds_dwordx4 v[214:215], off
	v_lshl_add_u64 v[214:215], s[26:27], 0, v[136:137]
	s_add_i32 m0, s28, 0x2000
	s_nop 0
	global_load_lds_dwordx4 v[214:215], off
	v_lshl_add_u64 v[214:215], v[218:219], 0, s[12:13]
	s_mov_b32 m0, s47
	s_nop 0
	global_load_lds_dwordx4 v[214:215], off
	v_lshl_add_u64 v[214:215], v[220:221], 0, s[12:13]
	s_mov_b32 m0, s48
	s_nop 0
	global_load_lds_dwordx4 v[214:215], off
	s_waitcnt vmcnt(8)
	s_waitcnt lgkmcnt(0)
	s_barrier
	s_setprio 1
	s_waitcnt lgkmcnt(0)
	v_mfma_f32_16x16x32_bf16 v[62:65], v[144:147], v[182:185], v[62:65]
	v_mfma_f32_16x16x32_bf16 v[58:61], v[152:155], v[182:185], v[58:61]
	v_mfma_f32_16x16x32_bf16 v[50:53], v[144:147], v[190:193], v[50:53]
	v_mfma_f32_16x16x32_bf16 v[42:45], v[152:155], v[190:193], v[42:45]
	v_mfma_f32_16x16x32_bf16 v[30:33], v[144:147], v[198:201], v[30:33]
	v_mfma_f32_16x16x32_bf16 v[26:29], v[152:155], v[198:201], v[26:29]
	v_mfma_f32_16x16x32_bf16 v[18:21], v[144:147], v[206:209], v[18:21]
	v_mfma_f32_16x16x32_bf16 v[10:13], v[152:155], v[206:209], v[10:13]
	v_mfma_f32_16x16x32_bf16 v[62:65], v[148:151], v[186:189], v[62:65]
	v_mfma_f32_16x16x32_bf16 v[58:61], v[156:159], v[186:189], v[58:61]
	v_mfma_f32_16x16x32_bf16 v[50:53], v[148:151], v[194:197], v[50:53]
	v_mfma_f32_16x16x32_bf16 v[42:45], v[156:159], v[194:197], v[42:45]
	v_mfma_f32_16x16x32_bf16 v[30:33], v[148:151], v[202:205], v[30:33]
	v_mfma_f32_16x16x32_bf16 v[26:29], v[156:159], v[202:205], v[26:29]
	v_mfma_f32_16x16x32_bf16 v[18:21], v[148:151], v[210:213], v[18:21]
	v_mfma_f32_16x16x32_bf16 v[10:13], v[156:159], v[210:213], v[10:13]
	s_setprio 0
	s_setprio 1
	v_mfma_f32_16x16x32_bf16 v[54:57], v[160:163], v[182:185], v[54:57]
	v_mfma_f32_16x16x32_bf16 v[46:49], v[174:177], v[182:185], v[46:49]
	v_mfma_f32_16x16x32_bf16 v[38:41], v[160:163], v[190:193], v[38:41]
	v_mfma_f32_16x16x32_bf16 v[34:37], v[174:177], v[190:193], v[34:37]
	v_mfma_f32_16x16x32_bf16 v[22:25], v[160:163], v[198:201], v[22:25]
	v_mfma_f32_16x16x32_bf16 v[14:17], v[174:177], v[198:201], v[14:17]
	v_mfma_f32_16x16x32_bf16 v[6:9], v[160:163], v[206:209], v[6:9]
	v_mfma_f32_16x16x32_bf16 v[2:5], v[174:177], v[206:209], v[2:5]
	v_mfma_f32_16x16x32_bf16 v[54:57], v[164:167], v[186:189], v[54:57]
	v_mfma_f32_16x16x32_bf16 v[46:49], v[178:181], v[186:189], v[46:49]
	v_mfma_f32_16x16x32_bf16 v[38:41], v[164:167], v[194:197], v[38:41]
	v_mfma_f32_16x16x32_bf16 v[34:37], v[178:181], v[194:197], v[34:37]
	v_mfma_f32_16x16x32_bf16 v[22:25], v[164:167], v[202:205], v[22:25]
	v_mfma_f32_16x16x32_bf16 v[14:17], v[178:181], v[202:205], v[14:17]
	v_mfma_f32_16x16x32_bf16 v[6:9], v[164:167], v[210:213], v[6:9]
	v_mfma_f32_16x16x32_bf16 v[2:5], v[178:181], v[210:213], v[2:5]
	s_setprio 0
	s_barrier
	s_add_u32 s24, s24, 0x100
	s_addc_u32 s25, s25, 0
	s_add_u32 s17, s17, 0x100
	s_addc_u32 s23, s23, 0
	s_cmp_ge_i32 s30, s67
	s_mov_b32 s26, s30
	s_cbranch_scc0 .LBB0_2683
	s_branch .Lpeeldone_0
